# v52 + cross-lane sum reductions via DPP / v_permlane16,32_swap instead of ds_bpermute (dense epilogue, out-proj/down rowss tails, RoPE)
# speedup vs baseline: 1.0105x; 1.0105x over previous
;     __device__ __forceinline__ void operator()(const f32x4 (&acc)[2][2][4][2], const Unit& u, int wr, int wc, int fr, int fq) const {
;     ...
;             const bool isq = (pn == 6) || (wc < 2);
;             const int hcol = (pn == 6) ? 64 * wc : (wc < 2 ? 64 * (4 + wc) : 64 * (wc - 2));
;             bf16_t* base = qkv + (isq ? OFF_QC : OFF_KC) + hcol + 8 * fqo;
;             const int pitch = isq ? 384 : 128;
;             const float* gw = (isq ? gq : gk) + 4 * fqo;
;             const float osc = isq ? 0.125f * 1.4426950408889634f : 1.0f;
; #pragma unroll
;             for (int ai = 0; ai < 2; ++ai)
; #pragma unroll
;                 for (int m = 0; m < 4; ++m) {
;                     const int row = row0 + ai * HALF + m * 16; const int t = row & 16383;
;                     const float rv = rsqrtf(rowss[row] * (1.0f / 1024.0f) + 1e-6f);
;                     float ss = 0.f; f32x4 hv[2][2];
; #pragma unroll
;                     for (int bj = 0; bj < 2; ++bj)
; #pragma unroll
;                         for (int n = 0; n < 2; ++n) { const f32x4 v = acc[ai][bj][m][n] * rv + *(const f32x4*)(bp + bj * HALF + 4 * n); hv[bj][n] = v; ss += (v[0] * v[0] + v[1] * v[1]) + (v[2] * v[2] + v[3] * v[3]); }
;                     ss += __shfl_xor(ss, 16); ss += __shfl_xor(ss, 32);
;                     const float rinv = rsqrtf(ss * (1.0f / 64.0f) + 1e-6f) * osc;
.LBB0_259:
	s_ashr_i32 s0, s6, 6
	s_lshl_b32 s4, s6, 8
	s_ashr_i32 s1, s0, 31
	s_add_i32 s4, s4, s11
	s_lshl_b64 s[0:1], s[0:1], 13
	s_add_u32 s5, s79, s0
	s_addc_u32 s6, s10, s1
	s_lshl_b32 s0, s66, 8
	s_ashr_i32 s1, s0, 31
	s_lshl_b64 s[0:1], s[0:1], 2
	s_add_u32 s0, s5, s0
	v_mov_b32_e32 v244, v238
	s_addc_u32 s1, s6, s1
	s_add_u32 s0, s0, s80
	v_lshlrev_b32_e32 v164, 3, v244
	v_or_b32_e32 v162, s4, v237
	s_addc_u32 s1, s1, 0
	v_ashrrev_i32_e32 v165, 31, v164
	v_lshl_add_u64 v[166:167], v[164:165], 2, s[0:1]
	s_mov_b64 s[0:1], -1
	s_cmp_gt_i32 s66, 5
	v_ashrrev_i32_e32 v163, 31, v162
	v_or_b32_e32 v243, 16, v162
	v_or_b32_e32 v242, 32, v162
	v_or_b32_e32 v241, 48, v162
	s_cbranch_scc0 .LBB0_261
	s_cmp_eq_u32 s66, 6
	s_cselect_b64 s[0:1], -1, 0
	s_and_b64 s[6:7], s[0:1], exec
	v_readlane_b32 s5, v255, 23
	s_cselect_b32 s34, s81, s5
	s_or_b64 vcc, s[0:1], s[38:39]
	s_and_b64 s[0:1], vcc, exec
	s_mov_b32 s0, 0x5800000
	s_cselect_b32 s0, s0, 0x7000000
	s_add_u32 s5, s2, s0
	s_addc_u32 s6, s3, 0
	s_lshl_b64 s[0:1], s[34:35], 1
	s_add_u32 s0, s5, s0
	s_addc_u32 s1, s6, s1
	v_readlane_b32 s48, v252, 2
	v_lshl_add_u64 v[170:171], v[164:165], 1, s[0:1]
	s_and_b64 s[0:1], vcc, exec
	v_readlane_b32 s50, v252, 4
	v_readlane_b32 s52, v252, 6
	v_lshlrev_b32_e32 v130, 2, v244
	v_readlane_b32 s51, v252, 5
	v_readlane_b32 s53, v252, 7
	s_cselect_b32 s0, s50, s52
	v_ashrrev_i32_e32 v131, 31, v130
	s_cselect_b32 s1, s51, s53
	s_add_u32 s0, s0, s76
	v_lshlrev_b64 v[186:187], 2, v[130:131]
	v_and_b32_e32 v131, 64, v230
	s_addc_u32 s1, s1, s77
	v_xor_b32_e32 v130, 16, v230
	v_add_u32_e32 v131, 64, v131
	v_lshl_add_u64 v[168:169], s[0:1], 0, v[186:187]
	v_cmp_lt_i32_e64 s[0:1], v130, v131
	v_lshl_add_u64 v[172:173], v[162:163], 2, s[12:13]
	v_cndmask_b32_e32 v245, 1.0, v231, vcc
	v_cndmask_b32_e64 v130, v230, v130, s[0:1]
	v_lshlrev_b32_e32 v246, 2, v130
	v_xor_b32_e32 v130, 32, v230
	v_cmp_lt_i32_e64 s[0:1], v130, v131
	v_mov_b32_e32 v159, v129
	v_mov_b32_e32 v161, v129
	v_cndmask_b32_e64 v130, v230, v130, s[0:1]
	v_lshlrev_b32_e32 v247, 2, v130
	global_load_dword v130, v[172:173], off
	global_load_dword v248, v[172:173], off offset:64
	global_load_dword v249, v[172:173], off offset:128
	global_load_dword v250, v[172:173], off offset:192
	global_load_dword v251, v[172:173], off offset:512
	global_load_dword v143, v[172:173], off offset:576
	global_load_dword v145, v[172:173], off offset:640
	global_load_dword v147, v[172:173], off offset:704
	s_and_b64 s[0:1], vcc, exec
	s_movk_i32 s0, 0x180
	s_cselect_b32 s0, s0, 0x80
	s_and_b32 s1, s4, 0x3fc0
	s_add_u32 s4, s82, s1
	s_addc_u32 s5, s83, 0
	v_readlane_b32 s49, v252, 3
	v_readlane_b32 s54, v252, 8
	v_readlane_b32 s55, v252, 9
	v_readlane_b32 s56, v252, 10
	v_readlane_b32 s57, v252, 11
	v_readlane_b32 s58, v252, 12
	v_readlane_b32 s59, v252, 13
	v_readlane_b32 s60, v252, 14
	v_readlane_b32 s61, v252, 15
	v_readlane_b32 s62, v252, 16
	v_readlane_b32 s63, v252, 17
	s_waitcnt vmcnt(7)
	v_fmamk_f32 v130, v130, 0x3a800000, v227
	s_nop 0
	v_rsq_f32_e32 v130, v130
	s_nop 0
	v_mov_b32_e32 v188, v130
	global_load_dwordx4 v[130:133], v[166:167], off offset:16
	global_load_dwordx4 v[134:137], v[166:167], off
	s_waitcnt vmcnt(1)
	v_pk_fma_f32 v[140:141], v[122:123], v[188:189], v[132:133] op_sel_hi:[1,0,1]
	s_waitcnt vmcnt(0)
	v_pk_fma_f32 v[192:193], v[124:125], v[188:189], v[134:135] op_sel_hi:[1,0,1]
	v_pk_fma_f32 v[194:195], v[126:127], v[188:189], v[136:137] op_sel_hi:[1,0,1]
	v_pk_mul_f32 v[136:137], v[192:193], v[192:193]
	v_pk_mul_f32 v[134:135], v[194:195], v[194:195]
	s_nop 0
	v_pk_mov_b32 v[138:139], v[136:137], v[134:135] op_sel:[1,0]
	v_mov_b32_e32 v137, v135
	v_pk_add_f32 v[134:135], v[138:139], v[136:137]
	v_pk_fma_f32 v[138:139], v[120:121], v[188:189], v[130:131] op_sel_hi:[1,0,1]
	v_pk_mul_f32 v[130:131], v[140:141], v[140:141]
	v_pk_mul_f32 v[132:133], v[138:139], v[138:139]
	v_pk_add_f32 v[198:199], v[134:135], v[134:135] op_sel_hi:[0,1]
	v_pk_mov_b32 v[134:135], v[132:133], v[130:131] op_sel:[1,0]
	v_mov_b32_e32 v133, v131
	v_pk_add_f32 v[130:131], v[134:135], v[132:133]
	s_nop 0
	v_pk_add_f32 v[200:201], v[130:131], v[130:131] op_sel_hi:[0,1]
	global_load_dwordx4 v[130:133], v[166:167], off offset:528
	global_load_dwordx4 v[134:137], v[166:167], off offset:512
	s_waitcnt vmcnt(1)
	v_pk_fma_f32 v[190:191], v[58:59], v[188:189], v[132:133] op_sel_hi:[1,0,1]
	s_waitcnt vmcnt(0)
	v_pk_fma_f32 v[206:207], v[60:61], v[188:189], v[134:135] op_sel_hi:[1,0,1]
	v_pk_fma_f32 v[204:205], v[62:63], v[188:189], v[136:137] op_sel_hi:[1,0,1]
	v_mul_f32_e32 v134, v206, v206
	v_pk_fma_f32 v[134:135], v[206:207], v[206:207], v[134:135] op_sel_hi:[1,1,0]
	v_pk_fma_f32 v[196:197], v[56:57], v[188:189], v[130:131] op_sel_hi:[1,0,1]
	global_load_dwordx4 v[120:123], v[166:167], off offset:16
	global_load_dwordx4 v[124:127], v[166:167], off
	global_load_dwordx4 v[56:59], v[166:167], off offset:528
	global_load_dwordx4 v[60:63], v[166:167], off offset:512
	v_mul_f32_e32 v134, v204, v204
	v_pk_fma_f32 v[136:137], v[204:205], v[204:205], v[134:135] op_sel_hi:[1,1,0]
	v_mul_f32_e32 v134, v196, v196
	v_mul_f32_e32 v136, v197, v197
	v_mul_f32_e32 v198, v190, v190
	v_mul_f32_e32 v200, v191, v191
	v_pk_add_f32 v[130:131], v[134:135], v[136:137]
	v_pk_add_f32 v[132:133], v[198:199], v[200:201]
	v_lshl_add_u64 v[200:201], s[4:5], 0, v[186:187]
	v_pk_add_f32 v[130:131], v[130:131], v[132:133]
	s_add_u32 s4, s84, s1
	v_add_f32_e32 v130, v130, v131
	v_mov_b32_e32 v131, v130
	s_nop 1
	v_permlane16_swap_b32_e32 v131, v130
	s_addc_u32 s5, s85, 0
	v_lshl_add_u64 v[202:203], s[4:5], 0, v[186:187]
	global_load_dwordx4 v[134:137], v[200:201], off
	s_waitcnt lgkmcnt(0)
; __device__ __forceinline__ unsigned pk_bf16(float lo, float hi) { f32x2 v = {lo, hi}; bf16x2_t b = __builtin_convertvector(v, bf16x2_t); return __builtin_bit_cast(unsigned, b); }
;     __device__ __forceinline__ void operator()(const f32x4 (&acc)[2][2][4][2], const Unit& u, int wr, int wc, int fr, int fq) const {
;     ...
;                         for (int n = 0; n < 2; ++n) { const f32x4 v = acc[ai][bj][m][n] * rv + *(const f32x4*)(bp + bj * HALF + 4 * n); hv[bj][n] = v; ss += (v[0] * v[0] + v[1] * v[1]) + (v[2] * v[2] + v[3] * v[3]); }
;                     ss += __shfl_xor(ss, 16); ss += __shfl_xor(ss, 32);
;                     const float rinv = rsqrtf(ss * (1.0f / 64.0f) + 1e-6f) * osc;
; #pragma unroll
;                     for (int bj = 0; bj < 2; ++bj) {
;                         const int pos = bj == 0 ? (t >> 6) : (t & 63);
;                         const f32x4 c = *(const f32x4*)(ropec + pos * 16 + 4 * fqo), s = *(const f32x4*)(ropes + pos * 16 + 4 * fqo);
;                         const f32x4 x1 = hv[bj][0] * rinv * *(const f32x4*)(gw + 32 * bj), x2 = hv[bj][1] * rinv * *(const f32x4*)(gw + 32 * bj + 16);
;                         const f32x4 o1 = x1 * c - x2 * s, o2 = x2 * c + x1 * s;
;                         u32x4 w; w.x = pk_bf16(o1[0], o1[1]); w.y = pk_bf16(o1[2], o1[3]); w.z = pk_bf16(o2[0], o2[1]); w.w = pk_bf16(o2[2], o2[3]);
;                         *(u32x4*)(base + (size_t)row * pitch + 32 * bj) = w;
;                     }
	v_add_f32_e32 v130, v130, v131
	v_mov_b32_e32 v131, v130
	s_nop 1
	v_permlane32_swap_b32_e32 v131, v130
	s_waitcnt lgkmcnt(0)
	v_add_f32_e32 v130, v130, v131
	v_fmamk_f32 v130, v130, 0x3c800000, v227
	s_nop 0
	v_rsq_f32_e32 v130, v130
	s_nop 0
	v_mul_f32_e32 v198, v245, v130
	v_pk_mul_f32 v[208:209], v[194:195], v[198:199] op_sel_hi:[1,0]
	v_pk_mul_f32 v[210:211], v[192:193], v[198:199] op_sel_hi:[1,0]
	global_load_dwordx4 v[192:195], v[168:169], off
	v_mad_i64_i32 v[130:131], s[6:7], s0, v162, 0
	v_lshl_add_u64 v[188:189], v[130:131], 1, v[170:171]
	global_load_dwordx4 v[130:133], v[202:203], off
	v_pk_mul_f32 v[204:205], v[204:205], v[198:199] op_sel_hi:[1,0]
	v_pk_mul_f32 v[206:207], v[206:207], v[198:199] op_sel_hi:[1,0]
	v_pk_mul_f32 v[196:197], v[196:197], v[198:199] op_sel_hi:[1,0]
	v_pk_mul_f32 v[190:191], v[190:191], v[198:199] op_sel_hi:[1,0]
	s_waitcnt vmcnt(1)
	v_pk_mul_f32 v[192:193], v[192:193], v[210:211]
	v_pk_mul_f32 v[194:195], v[194:195], v[208:209]
	v_pk_mul_f32 v[208:209], v[138:139], v[198:199] op_sel_hi:[1,0]
	v_pk_mul_f32 v[210:211], v[140:141], v[198:199] op_sel_hi:[1,0]
	global_load_dwordx4 v[138:141], v[168:169], off offset:64
	s_waitcnt vmcnt(0)
	v_pk_mul_f32 v[140:141], v[140:141], v[210:211]
	v_pk_mul_f32 v[138:139], v[138:139], v[208:209]
	v_pk_mul_f32 v[210:211], v[132:133], v[140:141]
	v_pk_mul_f32 v[208:209], v[130:131], v[138:139]
	v_pk_fma_f32 v[210:211], v[136:137], v[194:195], v[210:211] neg_lo:[0,0,1] neg_hi:[0,0,1]
	v_pk_fma_f32 v[208:209], v[134:135], v[192:193], v[208:209] neg_lo:[0,0,1] neg_hi:[0,0,1]
	v_pk_mul_f32 v[134:135], v[134:135], v[138:139]
	v_pk_mul_f32 v[136:137], v[136:137], v[140:141]
	s_nop 0
	v_pk_fma_f32 v[136:137], v[132:133], v[194:195], v[136:137]
	v_pk_fma_f32 v[132:133], v[130:131], v[192:193], v[134:135]
	v_cvt_pk_bf16_f32 v130, v208, v209
	v_cvt_pk_bf16_f32 v131, v210, v211
	v_cvt_pk_bf16_f32 v132, v132, v133
	v_cvt_pk_bf16_f32 v133, v136, v137
	global_store_dwordx4 v[188:189], v[130:133], off
	global_load_dwordx4 v[138:141], v[168:169], off offset:128
	v_lshl_add_u64 v[192:193], v[150:151], 0, v[186:187]
	v_lshl_add_u64 v[194:195], v[152:153], 0, v[186:187]
	global_load_dwordx4 v[130:133], v[192:193], off
	global_load_dwordx4 v[134:137], v[194:195], off
	s_waitcnt vmcnt(2)
	v_pk_mul_f32 v[206:207], v[138:139], v[206:207]
	v_pk_mul_f32 v[204:205], v[140:141], v[204:205]
	global_load_dwordx4 v[138:141], v[168:169], off offset:192
	s_waitcnt vmcnt(0)
	v_pk_mul_f32 v[140:141], v[140:141], v[190:191]
	v_pk_mul_f32 v[138:139], v[138:139], v[196:197]
	v_pk_mul_f32 v[196:197], v[136:137], v[140:141]
	v_pk_mul_f32 v[190:191], v[134:135], v[138:139]
	v_pk_fma_f32 v[196:197], v[132:133], v[204:205], v[196:197] neg_lo:[0,0,1] neg_hi:[0,0,1]
	v_pk_fma_f32 v[190:191], v[130:131], v[206:207], v[190:191] neg_lo:[0,0,1] neg_hi:[0,0,1]
	v_pk_mul_f32 v[130:131], v[130:131], v[138:139]
	v_pk_mul_f32 v[132:133], v[132:133], v[140:141]
	s_nop 0
	v_pk_fma_f32 v[136:137], v[136:137], v[204:205], v[132:133]
	v_pk_fma_f32 v[132:133], v[134:135], v[206:207], v[130:131]
	v_cvt_pk_bf16_f32 v130, v190, v191
	v_cvt_pk_bf16_f32 v131, v196, v197
	v_cvt_pk_bf16_f32 v132, v132, v133
	v_cvt_pk_bf16_f32 v133, v136, v137
	global_store_dwordx4 v[188:189], v[130:133], off offset:64
	s_nop 1
	v_fmamk_f32 v130, v248, 0x3a800000, v227
	s_nop 0
	v_rsq_f32_e32 v130, v130
	s_nop 0
	v_mov_b32_e32 v188, v130
	v_pk_fma_f32 v[130:131], v[112:113], v[188:189], v[120:121] op_sel_hi:[1,0,1]
	v_pk_fma_f32 v[190:191], v[116:117], v[188:189], v[124:125] op_sel_hi:[1,0,1]
	v_pk_fma_f32 v[212:213], v[118:119], v[188:189], v[126:127] op_sel_hi:[1,0,1]
	v_pk_mul_f32 v[136:137], v[190:191], v[190:191]
	v_pk_mul_f32 v[134:135], v[212:213], v[212:213]
	v_pk_fma_f32 v[132:133], v[114:115], v[188:189], v[122:123] op_sel_hi:[1,0,1]
	v_pk_mov_b32 v[138:139], v[136:137], v[134:135] op_sel:[1,0]
	v_mov_b32_e32 v137, v135
	v_pk_add_f32 v[134:135], v[138:139], v[136:137]
	v_pk_mul_f32 v[136:137], v[130:131], v[130:131]
	v_pk_add_f32 v[196:197], v[134:135], v[134:135] op_sel_hi:[0,1]
	v_pk_mul_f32 v[134:135], v[132:133], v[132:133]
	s_nop 0
	v_pk_mov_b32 v[138:139], v[136:137], v[134:135] op_sel:[1,0]
	v_mov_b32_e32 v137, v135
	v_pk_add_f32 v[134:135], v[138:139], v[136:137]
	s_nop 0
	v_pk_add_f32 v[206:207], v[134:135], v[134:135] op_sel_hi:[0,1]
	v_pk_fma_f32 v[198:199], v[50:51], v[188:189], v[58:59] op_sel_hi:[1,0,1]
	v_pk_fma_f32 v[210:211], v[52:53], v[188:189], v[60:61] op_sel_hi:[1,0,1]
	v_pk_fma_f32 v[208:209], v[54:55], v[188:189], v[62:63] op_sel_hi:[1,0,1]
	v_mul_f32_e32 v138, v210, v210
	v_pk_fma_f32 v[138:139], v[210:211], v[210:211], v[138:139] op_sel_hi:[1,1,0]
	v_pk_fma_f32 v[204:205], v[48:49], v[188:189], v[56:57] op_sel_hi:[1,0,1]
	global_load_dwordx4 v[112:115], v[168:169], off
	global_load_dwordx4 v[116:119], v[168:169], off offset:64
	global_load_dwordx4 v[48:51], v[168:169], off offset:128
	global_load_dwordx4 v[52:55], v[168:169], off offset:192
	v_mul_f32_e32 v138, v208, v208
	v_pk_fma_f32 v[140:141], v[208:209], v[208:209], v[138:139] op_sel_hi:[1,1,0]
	v_mul_f32_e32 v138, v204, v204
	v_mul_f32_e32 v140, v205, v205
	v_mul_f32_e32 v196, v198, v198
	v_mul_f32_e32 v206, v199, v199
	v_pk_add_f32 v[134:135], v[138:139], v[140:141]
	v_pk_add_f32 v[136:137], v[196:197], v[206:207]
	s_nop 0
	v_pk_add_f32 v[134:135], v[134:135], v[136:137]
	s_nop 0
	v_add_f32_e32 v134, v134, v135
	v_mov_b32_e32 v135, v134
	s_nop 1
	v_permlane16_swap_b32_e32 v135, v134
	s_waitcnt lgkmcnt(0)
	v_add_f32_e32 v134, v134, v135
	v_mov_b32_e32 v135, v134
	s_nop 1
	v_permlane32_swap_b32_e32 v135, v134
	s_waitcnt lgkmcnt(0)
; __device__ __forceinline__ unsigned pk_bf16(float lo, float hi) { f32x2 v = {lo, hi}; bf16x2_t b = __builtin_convertvector(v, bf16x2_t); return __builtin_bit_cast(unsigned, b); }
;     __device__ __forceinline__ void operator()(const f32x4 (&acc)[2][2][4][2], const Unit& u, int wr, int wc, int fr, int fq) const {
;     ...
;                         for (int n = 0; n < 2; ++n) { const f32x4 v = acc[ai][bj][m][n] * rv + *(const f32x4*)(bp + bj * HALF + 4 * n); hv[bj][n] = v; ss += (v[0] * v[0] + v[1] * v[1]) + (v[2] * v[2] + v[3] * v[3]); }
;                     ss += __shfl_xor(ss, 16); ss += __shfl_xor(ss, 32);
;                     const float rinv = rsqrtf(ss * (1.0f / 64.0f) + 1e-6f) * osc;
; #pragma unroll
;                     for (int bj = 0; bj < 2; ++bj) {
;                         const int pos = bj == 0 ? (t >> 6) : (t & 63);
;                         const f32x4 c = *(const f32x4*)(ropec + pos * 16 + 4 * fqo), s = *(const f32x4*)(ropes + pos * 16 + 4 * fqo);
;                         const f32x4 x1 = hv[bj][0] * rinv * *(const f32x4*)(gw + 32 * bj), x2 = hv[bj][1] * rinv * *(const f32x4*)(gw + 32 * bj + 16);
;                         const f32x4 o1 = x1 * c - x2 * s, o2 = x2 * c + x1 * s;
;                         u32x4 w; w.x = pk_bf16(o1[0], o1[1]); w.y = pk_bf16(o1[2], o1[3]); w.z = pk_bf16(o2[0], o2[1]); w.w = pk_bf16(o2[2], o2[3]);
;                         *(u32x4*)(base + (size_t)row * pitch + 32 * bj) = w;
;                     }
	v_add_f32_e32 v134, v134, v135
	v_fmamk_f32 v134, v134, 0x3c800000, v227
	s_nop 0
	v_rsq_f32_e32 v134, v134
	s_nop 0
	v_mul_f32_e32 v206, v245, v134
	v_mad_i64_i32 v[134:135], s[4:5], s0, v243, 0
	v_lshl_add_u64 v[196:197], v[134:135], 1, v[170:171]
	global_load_dwordx4 v[134:137], v[200:201], off
	global_load_dwordx4 v[138:141], v[202:203], off
	v_pk_mul_f32 v[214:215], v[190:191], v[206:207] op_sel_hi:[1,0]
	global_load_dwordx4 v[188:191], v[168:169], off
	v_pk_mul_f32 v[212:213], v[212:213], v[206:207] op_sel_hi:[1,0]
	v_pk_mul_f32 v[198:199], v[198:199], v[206:207] op_sel_hi:[1,0]
	s_waitcnt vmcnt(0)
	v_pk_mul_f32 v[188:189], v[188:189], v[214:215]
	v_pk_mul_f32 v[190:191], v[190:191], v[212:213]
	v_pk_mul_f32 v[212:213], v[130:131], v[206:207] op_sel_hi:[1,0]
	v_pk_mul_f32 v[214:215], v[132:133], v[206:207] op_sel_hi:[1,0]
	global_load_dwordx4 v[130:133], v[168:169], off offset:64
	s_waitcnt vmcnt(0)
	v_pk_mul_f32 v[132:133], v[132:133], v[214:215]
	v_pk_mul_f32 v[130:131], v[130:131], v[212:213]
	v_pk_mul_f32 v[214:215], v[140:141], v[132:133]
	v_pk_mul_f32 v[212:213], v[138:139], v[130:131]
	v_pk_mul_f32 v[130:131], v[134:135], v[130:131]
	v_pk_mul_f32 v[132:133], v[136:137], v[132:133]
	v_pk_fma_f32 v[214:215], v[136:137], v[190:191], v[214:215] neg_lo:[0,0,1] neg_hi:[0,0,1]
	v_pk_fma_f32 v[212:213], v[134:135], v[188:189], v[212:213] neg_lo:[0,0,1] neg_hi:[0,0,1]
	v_pk_fma_f32 v[134:135], v[140:141], v[190:191], v[132:133]
	v_pk_fma_f32 v[132:133], v[138:139], v[188:189], v[130:131]
	v_cvt_pk_bf16_f32 v130, v212, v213
	v_cvt_pk_bf16_f32 v131, v214, v215
	v_cvt_pk_bf16_f32 v132, v132, v133
	v_cvt_pk_bf16_f32 v133, v134, v135
	global_store_dwordx4 v[196:197], v[130:133], off
	v_pk_mul_f32 v[212:213], v[208:209], v[206:207] op_sel_hi:[1,0]
	v_pk_mul_f32 v[214:215], v[210:211], v[206:207] op_sel_hi:[1,0]
	global_load_dwordx4 v[208:211], v[168:169], off offset:128
	v_lshl_add_u64 v[138:139], s[82:83], 0, v[186:187]
	v_lshl_add_u64 v[140:141], s[84:85], 0, v[186:187]
	v_lshl_add_u64 v[188:189], v[138:139], 0, v[128:129]
	v_lshl_add_u64 v[190:191], v[140:141], 0, v[128:129]
	global_load_dwordx4 v[134:137], v[188:189], off
	global_load_dwordx4 v[130:133], v[190:191], off
	s_waitcnt vmcnt(2)
	v_pk_mul_f32 v[210:211], v[210:211], v[212:213]
	v_pk_mul_f32 v[212:213], v[204:205], v[206:207] op_sel_hi:[1,0]
	global_load_dwordx4 v[204:207], v[168:169], off offset:192
	v_pk_mul_f32 v[208:209], v[208:209], v[214:215]
	s_waitcnt vmcnt(0)
	v_pk_mul_f32 v[198:199], v[206:207], v[198:199]
	v_pk_mul_f32 v[204:205], v[204:205], v[212:213]
	v_pk_mul_f32 v[212:213], v[132:133], v[198:199]
	v_pk_mul_f32 v[206:207], v[130:131], v[204:205]
	v_pk_fma_f32 v[212:213], v[136:137], v[210:211], v[212:213] neg_lo:[0,0,1] neg_hi:[0,0,1]
	v_pk_fma_f32 v[206:207], v[134:135], v[208:209], v[206:207] neg_lo:[0,0,1] neg_hi:[0,0,1]
	v_pk_mul_f32 v[134:135], v[134:135], v[204:205]
	v_pk_mul_f32 v[136:137], v[136:137], v[198:199]
	s_nop 0
	v_pk_fma_f32 v[136:137], v[132:133], v[210:211], v[136:137]
	v_pk_fma_f32 v[132:133], v[130:131], v[208:209], v[134:135]
	v_cvt_pk_bf16_f32 v130, v206, v207
	v_cvt_pk_bf16_f32 v131, v212, v213
	v_cvt_pk_bf16_f32 v132, v132, v133
	v_cvt_pk_bf16_f32 v133, v136, v137
	global_store_dwordx4 v[196:197], v[130:133], off offset:64
	s_nop 1
	v_fmamk_f32 v130, v249, 0x3a800000, v227
	s_nop 0
	v_rsq_f32_e32 v130, v130
	s_nop 0
	v_mov_b32_e32 v196, v130
	v_pk_fma_f32 v[216:217], v[104:105], v[196:197], v[120:121] op_sel_hi:[1,0,1]
	v_pk_fma_f32 v[198:199], v[108:109], v[196:197], v[124:125] op_sel_hi:[1,0,1]
	v_pk_fma_f32 v[220:221], v[110:111], v[196:197], v[126:127] op_sel_hi:[1,0,1]
	v_pk_mul_f32 v[136:137], v[198:199], v[198:199]
	v_pk_mul_f32 v[134:135], v[220:221], v[220:221]
	v_pk_fma_f32 v[218:219], v[106:107], v[196:197], v[122:123] op_sel_hi:[1,0,1]
	v_pk_mov_b32 v[204:205], v[136:137], v[134:135] op_sel:[1,0]
	v_mov_b32_e32 v137, v135
	v_pk_add_f32 v[134:135], v[204:205], v[136:137]
	v_pk_mul_f32 v[130:131], v[218:219], v[218:219]
	v_pk_mul_f32 v[132:133], v[216:217], v[216:217]
	v_pk_add_f32 v[204:205], v[134:135], v[134:135] op_sel_hi:[0,1]
	v_pk_mov_b32 v[134:135], v[132:133], v[130:131] op_sel:[1,0]
	v_mov_b32_e32 v133, v131
	v_pk_add_f32 v[130:131], v[134:135], v[132:133]
	s_nop 0
	v_pk_add_f32 v[210:211], v[130:131], v[130:131] op_sel_hi:[0,1]
	v_pk_fma_f32 v[206:207], v[42:43], v[196:197], v[58:59] op_sel_hi:[1,0,1]
	v_pk_fma_f32 v[214:215], v[44:45], v[196:197], v[60:61] op_sel_hi:[1,0,1]
	v_pk_fma_f32 v[212:213], v[46:47], v[196:197], v[62:63] op_sel_hi:[1,0,1]
	v_mul_f32_e32 v134, v214, v214
	v_pk_fma_f32 v[134:135], v[214:215], v[214:215], v[134:135] op_sel_hi:[1,1,0]
	v_pk_fma_f32 v[208:209], v[40:41], v[196:197], v[56:57] op_sel_hi:[1,0,1]
	v_mul_f32_e32 v134, v212, v212
	v_pk_fma_f32 v[136:137], v[212:213], v[212:213], v[134:135] op_sel_hi:[1,1,0]
	v_mul_f32_e32 v134, v208, v208
	v_mul_f32_e32 v136, v209, v209
	v_mul_f32_e32 v204, v206, v206
	v_mul_f32_e32 v210, v207, v207
	v_pk_add_f32 v[130:131], v[134:135], v[136:137]
	v_pk_add_f32 v[132:133], v[204:205], v[210:211]
	s_nop 0
	v_pk_add_f32 v[130:131], v[130:131], v[132:133]
	s_nop 0
	v_add_f32_e32 v130, v130, v131
	v_mov_b32_e32 v131, v130
	s_nop 1
	v_permlane16_swap_b32_e32 v131, v130
	s_waitcnt lgkmcnt(0)
	v_add_f32_e32 v130, v130, v131
	v_mov_b32_e32 v131, v130
	s_nop 1
	v_permlane32_swap_b32_e32 v131, v130
	s_waitcnt lgkmcnt(0)
; __device__ __forceinline__ unsigned pk_bf16(float lo, float hi) { f32x2 v = {lo, hi}; bf16x2_t b = __builtin_convertvector(v, bf16x2_t); return __builtin_bit_cast(unsigned, b); }
;     __device__ __forceinline__ void operator()(const f32x4 (&acc)[2][2][4][2], const Unit& u, int wr, int wc, int fr, int fq) const {
;     ...
;                         for (int n = 0; n < 2; ++n) { const f32x4 v = acc[ai][bj][m][n] * rv + *(const f32x4*)(bp + bj * HALF + 4 * n); hv[bj][n] = v; ss += (v[0] * v[0] + v[1] * v[1]) + (v[2] * v[2] + v[3] * v[3]); }
;                     ss += __shfl_xor(ss, 16); ss += __shfl_xor(ss, 32);
;                     const float rinv = rsqrtf(ss * (1.0f / 64.0f) + 1e-6f) * osc;
; #pragma unroll
;                     for (int bj = 0; bj < 2; ++bj) {
;                         const int pos = bj == 0 ? (t >> 6) : (t & 63);
;                         const f32x4 c = *(const f32x4*)(ropec + pos * 16 + 4 * fqo), s = *(const f32x4*)(ropes + pos * 16 + 4 * fqo);
;                         const f32x4 x1 = hv[bj][0] * rinv * *(const f32x4*)(gw + 32 * bj), x2 = hv[bj][1] * rinv * *(const f32x4*)(gw + 32 * bj + 16);
;                         const f32x4 o1 = x1 * c - x2 * s, o2 = x2 * c + x1 * s;
;                         u32x4 w; w.x = pk_bf16(o1[0], o1[1]); w.y = pk_bf16(o1[2], o1[3]); w.z = pk_bf16(o2[0], o2[1]); w.w = pk_bf16(o2[2], o2[3]);
;                         *(u32x4*)(base + (size_t)row * pitch + 32 * bj) = w;
;                     }
	v_add_f32_e32 v130, v130, v131
	v_fmamk_f32 v130, v130, 0x3c800000, v227
	s_nop 0
	v_rsq_f32_e32 v130, v130
	s_nop 0
	v_mul_f32_e32 v210, v245, v130
	v_mad_i64_i32 v[130:131], s[4:5], s0, v242, 0
	v_lshl_add_u64 v[204:205], v[130:131], 1, v[170:171]
	global_load_dwordx4 v[134:137], v[200:201], off
	global_load_dwordx4 v[130:133], v[202:203], off
	v_pk_mul_f32 v[222:223], v[198:199], v[210:211] op_sel_hi:[1,0]
	v_pk_mul_f32 v[220:221], v[220:221], v[210:211] op_sel_hi:[1,0]
	v_pk_mul_f32 v[216:217], v[216:217], v[210:211] op_sel_hi:[1,0]
	v_pk_mul_f32 v[218:219], v[218:219], v[210:211] op_sel_hi:[1,0]
	v_pk_mul_f32 v[196:197], v[112:113], v[222:223]
	v_pk_mul_f32 v[198:199], v[114:115], v[220:221]
	v_pk_mul_f32 v[218:219], v[118:119], v[218:219]
	v_pk_mul_f32 v[216:217], v[116:117], v[216:217]
	s_waitcnt vmcnt(0)
	v_pk_mul_f32 v[222:223], v[132:133], v[218:219]
	v_pk_mul_f32 v[220:221], v[130:131], v[216:217]
	v_pk_fma_f32 v[222:223], v[136:137], v[198:199], v[222:223] neg_lo:[0,0,1] neg_hi:[0,0,1]
	v_pk_fma_f32 v[220:221], v[134:135], v[196:197], v[220:221] neg_lo:[0,0,1] neg_hi:[0,0,1]
	v_pk_mul_f32 v[134:135], v[134:135], v[216:217]
	v_pk_mul_f32 v[136:137], v[136:137], v[218:219]
	v_pk_mul_f32 v[216:217], v[212:213], v[210:211] op_sel_hi:[1,0]
	v_pk_fma_f32 v[136:137], v[132:133], v[198:199], v[136:137]
	v_pk_fma_f32 v[132:133], v[130:131], v[196:197], v[134:135]
	v_cvt_pk_bf16_f32 v130, v220, v221
	v_cvt_pk_bf16_f32 v131, v222, v223
	v_cvt_pk_bf16_f32 v132, v132, v133
	v_cvt_pk_bf16_f32 v133, v136, v137
	global_store_dwordx4 v[204:205], v[130:133], off
	v_pk_mul_f32 v[218:219], v[214:215], v[210:211] op_sel_hi:[1,0]
	v_lshl_add_u64 v[196:197], v[138:139], 0, v[158:159]
	v_lshl_add_u64 v[198:199], v[140:141], 0, v[158:159]
	global_load_dwordx4 v[130:133], v[196:197], off
	global_load_dwordx4 v[134:137], v[198:199], off
	v_add_u32_e32 v159, 0x80, v162
	v_pk_mul_f32 v[214:215], v[50:51], v[216:217]
	v_pk_mul_f32 v[216:217], v[208:209], v[210:211] op_sel_hi:[1,0]
	v_pk_mul_f32 v[210:211], v[206:207], v[210:211] op_sel_hi:[1,0]
	v_pk_mul_f32 v[212:213], v[48:49], v[218:219]
	v_pk_mul_f32 v[208:209], v[54:55], v[210:211]
	v_pk_mul_f32 v[206:207], v[52:53], v[216:217]
	s_waitcnt vmcnt(0)
	v_pk_mul_f32 v[216:217], v[136:137], v[208:209]
	v_pk_mul_f32 v[210:211], v[134:135], v[206:207]
	v_pk_fma_f32 v[216:217], v[132:133], v[214:215], v[216:217] neg_lo:[0,0,1] neg_hi:[0,0,1]
	v_pk_fma_f32 v[210:211], v[130:131], v[212:213], v[210:211] neg_lo:[0,0,1] neg_hi:[0,0,1]
	v_pk_mul_f32 v[130:131], v[130:131], v[206:207]
	v_pk_mul_f32 v[132:133], v[132:133], v[208:209]
	s_nop 0
	v_pk_fma_f32 v[136:137], v[136:137], v[214:215], v[132:133]
	v_pk_fma_f32 v[132:133], v[134:135], v[212:213], v[130:131]
	v_cvt_pk_bf16_f32 v130, v210, v211
	v_cvt_pk_bf16_f32 v131, v216, v217
	v_cvt_pk_bf16_f32 v132, v132, v133
	v_cvt_pk_bf16_f32 v133, v136, v137
	global_store_dwordx4 v[204:205], v[130:133], off offset:64
	s_nop 1
	v_fmamk_f32 v130, v250, 0x3a800000, v227
	s_nop 0
	v_rsq_f32_e32 v130, v130
	s_nop 0
	v_mov_b32_e32 v204, v130
	v_pk_fma_f32 v[216:217], v[96:97], v[204:205], v[120:121] op_sel_hi:[1,0,1]
	v_pk_fma_f32 v[220:221], v[100:101], v[204:205], v[124:125] op_sel_hi:[1,0,1]
	v_pk_fma_f32 v[222:223], v[102:103], v[204:205], v[126:127] op_sel_hi:[1,0,1]
	v_pk_mul_f32 v[136:137], v[220:221], v[220:221]
	v_pk_mul_f32 v[134:135], v[222:223], v[222:223]
	v_pk_fma_f32 v[218:219], v[98:99], v[204:205], v[122:123] op_sel_hi:[1,0,1]
	v_pk_mov_b32 v[206:207], v[136:137], v[134:135] op_sel:[1,0]
	v_mov_b32_e32 v137, v135
	v_pk_add_f32 v[134:135], v[206:207], v[136:137]
	v_pk_mul_f32 v[130:131], v[218:219], v[218:219]
	v_pk_mul_f32 v[132:133], v[216:217], v[216:217]
	v_pk_add_f32 v[210:211], v[134:135], v[134:135] op_sel_hi:[0,1]
	v_pk_mov_b32 v[134:135], v[132:133], v[130:131] op_sel:[1,0]
	v_mov_b32_e32 v133, v131
	v_pk_add_f32 v[130:131], v[134:135], v[132:133]
	s_nop 0
	v_pk_add_f32 v[224:225], v[130:131], v[130:131] op_sel_hi:[0,1]
	v_pk_fma_f32 v[206:207], v[34:35], v[204:205], v[58:59] op_sel_hi:[1,0,1]
	v_pk_fma_f32 v[214:215], v[36:37], v[204:205], v[60:61] op_sel_hi:[1,0,1]
	v_pk_fma_f32 v[212:213], v[38:39], v[204:205], v[62:63] op_sel_hi:[1,0,1]
	v_mul_f32_e32 v134, v214, v214
	v_pk_fma_f32 v[134:135], v[214:215], v[214:215], v[134:135] op_sel_hi:[1,1,0]
	v_pk_fma_f32 v[208:209], v[32:33], v[204:205], v[56:57] op_sel_hi:[1,0,1]
	v_mul_f32_e32 v134, v212, v212
	v_pk_fma_f32 v[136:137], v[212:213], v[212:213], v[134:135] op_sel_hi:[1,1,0]
	v_mul_f32_e32 v134, v208, v208
	v_mul_f32_e32 v136, v209, v209
	v_mul_f32_e32 v210, v206, v206
	v_mul_f32_e32 v224, v207, v207
	v_pk_add_f32 v[130:131], v[134:135], v[136:137]
	v_pk_add_f32 v[132:133], v[210:211], v[224:225]
	s_nop 0
	v_pk_add_f32 v[130:131], v[130:131], v[132:133]
	s_nop 0
	v_add_f32_e32 v130, v130, v131
	v_mov_b32_e32 v131, v130
	s_nop 1
	v_permlane16_swap_b32_e32 v131, v130
	s_waitcnt lgkmcnt(0)
	v_add_f32_e32 v130, v130, v131
	v_mov_b32_e32 v131, v130
	s_nop 1
	v_permlane32_swap_b32_e32 v131, v130
	s_waitcnt lgkmcnt(0)
	v_add_f32_e32 v130, v130, v131
	v_fmamk_f32 v130, v130, 0x3c800000, v227
	s_nop 0
	v_rsq_f32_e32 v130, v130
	s_nop 0
	v_mul_f32_e32 v210, v245, v130
	v_mad_i64_i32 v[130:131], s[4:5], s0, v241, 0
	v_lshl_add_u64 v[204:205], v[130:131], 1, v[170:171]
	global_load_dwordx4 v[134:137], v[200:201], off
	global_load_dwordx4 v[130:133], v[202:203], off
	v_pk_mul_f32 v[222:223], v[222:223], v[210:211] op_sel_hi:[1,0]
	v_pk_mul_f32 v[220:221], v[220:221], v[210:211] op_sel_hi:[1,0]
	v_pk_mul_f32 v[216:217], v[216:217], v[210:211] op_sel_hi:[1,0]
	v_pk_mul_f32 v[218:219], v[218:219], v[210:211] op_sel_hi:[1,0]
	v_pk_mul_f32 v[212:213], v[212:213], v[210:211] op_sel_hi:[1,0]
	v_pk_mul_f32 v[214:215], v[214:215], v[210:211] op_sel_hi:[1,0]
	v_pk_mul_f32 v[208:209], v[208:209], v[210:211] op_sel_hi:[1,0]
	v_pk_mul_f32 v[206:207], v[206:207], v[210:211] op_sel_hi:[1,0]
	v_pk_mul_f32 v[200:201], v[112:113], v[220:221]
	v_pk_mul_f32 v[202:203], v[114:115], v[222:223]
	v_pk_mul_f32 v[218:219], v[118:119], v[218:219]
	v_pk_mul_f32 v[216:217], v[116:117], v[216:217]
	s_waitcnt vmcnt(0)
; __device__ __forceinline__ unsigned pk_bf16(float lo, float hi) { f32x2 v = {lo, hi}; bf16x2_t b = __builtin_convertvector(v, bf16x2_t); return __builtin_bit_cast(unsigned, b); }
;     __device__ __forceinline__ void operator()(const f32x4 (&acc)[2][2][4][2], const Unit& u, int wr, int wc, int fr, int fq) const {
;     ...
;                         for (int n = 0; n < 2; ++n) { const f32x4 v = acc[ai][bj][m][n] * rv + *(const f32x4*)(bp + bj * HALF + 4 * n); hv[bj][n] = v; ss += (v[0] * v[0] + v[1] * v[1]) + (v[2] * v[2] + v[3] * v[3]); }
;                     ss += __shfl_xor(ss, 16); ss += __shfl_xor(ss, 32);
;                     const float rinv = rsqrtf(ss * (1.0f / 64.0f) + 1e-6f) * osc;
; #pragma unroll
;                     for (int bj = 0; bj < 2; ++bj) {
;                         const int pos = bj == 0 ? (t >> 6) : (t & 63);
;                         const f32x4 c = *(const f32x4*)(ropec + pos * 16 + 4 * fqo), s = *(const f32x4*)(ropes + pos * 16 + 4 * fqo);
;                         const f32x4 x1 = hv[bj][0] * rinv * *(const f32x4*)(gw + 32 * bj), x2 = hv[bj][1] * rinv * *(const f32x4*)(gw + 32 * bj + 16);
;                         const f32x4 o1 = x1 * c - x2 * s, o2 = x2 * c + x1 * s;
;                         u32x4 w; w.x = pk_bf16(o1[0], o1[1]); w.y = pk_bf16(o1[2], o1[3]); w.z = pk_bf16(o2[0], o2[1]); w.w = pk_bf16(o2[2], o2[3]);
;                         *(u32x4*)(base + (size_t)row * pitch + 32 * bj) = w;
;                     }
	v_pk_mul_f32 v[222:223], v[132:133], v[218:219]
	v_pk_mul_f32 v[220:221], v[130:131], v[216:217]
	v_pk_fma_f32 v[222:223], v[136:137], v[202:203], v[222:223] neg_lo:[0,0,1] neg_hi:[0,0,1]
	v_pk_fma_f32 v[220:221], v[134:135], v[200:201], v[220:221] neg_lo:[0,0,1] neg_hi:[0,0,1]
	v_pk_mul_f32 v[134:135], v[134:135], v[216:217]
	v_pk_mul_f32 v[136:137], v[136:137], v[218:219]
	s_nop 0
	v_pk_fma_f32 v[136:137], v[132:133], v[202:203], v[136:137]
	v_pk_fma_f32 v[132:133], v[130:131], v[200:201], v[134:135]
	v_cvt_pk_bf16_f32 v130, v220, v221
	v_cvt_pk_bf16_f32 v131, v222, v223
	v_cvt_pk_bf16_f32 v132, v132, v133
	v_cvt_pk_bf16_f32 v133, v136, v137
	global_store_dwordx4 v[204:205], v[130:133], off
	v_lshl_add_u64 v[200:201], v[138:139], 0, v[160:161]
	v_lshl_add_u64 v[202:203], v[140:141], 0, v[160:161]
	global_load_dwordx4 v[130:133], v[200:201], off
	global_load_dwordx4 v[134:137], v[202:203], off
	v_pk_mul_f32 v[214:215], v[48:49], v[214:215]
	v_pk_mul_f32 v[212:213], v[50:51], v[212:213]
	v_pk_mul_f32 v[140:141], v[54:55], v[206:207]
	v_pk_mul_f32 v[138:139], v[52:53], v[208:209]
	s_waitcnt vmcnt(0)
	v_pk_mul_f32 v[208:209], v[136:137], v[140:141]
	v_pk_mul_f32 v[206:207], v[134:135], v[138:139]
	v_pk_fma_f32 v[208:209], v[132:133], v[212:213], v[208:209] neg_lo:[0,0,1] neg_hi:[0,0,1]
	v_pk_fma_f32 v[206:207], v[130:131], v[214:215], v[206:207] neg_lo:[0,0,1] neg_hi:[0,0,1]
	v_pk_mul_f32 v[130:131], v[130:131], v[138:139]
	v_pk_mul_f32 v[132:133], v[132:133], v[140:141]
	s_nop 0
	v_pk_fma_f32 v[136:137], v[136:137], v[212:213], v[132:133]
	v_pk_fma_f32 v[132:133], v[134:135], v[214:215], v[130:131]
	v_cvt_pk_bf16_f32 v130, v206, v207
	v_cvt_pk_bf16_f32 v131, v208, v209
	v_cvt_pk_bf16_f32 v132, v132, v133
	v_cvt_pk_bf16_f32 v133, v136, v137
	global_store_dwordx4 v[204:205], v[130:133], off offset:64
	s_nop 1
	v_fmamk_f32 v130, v251, 0x3a800000, v227
	s_nop 0
	v_rsq_f32_e32 v130, v130
	s_nop 0
	v_mov_b32_e32 v204, v130
	v_pk_fma_f32 v[140:141], v[90:91], v[204:205], v[122:123] op_sel_hi:[1,0,1]
	v_pk_fma_f32 v[218:219], v[92:93], v[204:205], v[124:125] op_sel_hi:[1,0,1]
	v_pk_fma_f32 v[220:221], v[94:95], v[204:205], v[126:127] op_sel_hi:[1,0,1]
	v_pk_mul_f32 v[136:137], v[218:219], v[218:219]
	v_pk_mul_f32 v[134:135], v[220:221], v[220:221]
	s_nop 0
	v_pk_mov_b32 v[138:139], v[136:137], v[134:135] op_sel:[1,0]
	v_mov_b32_e32 v137, v135
	v_pk_add_f32 v[134:135], v[138:139], v[136:137]
	v_pk_fma_f32 v[138:139], v[88:89], v[204:205], v[120:121] op_sel_hi:[1,0,1]
	v_pk_mul_f32 v[130:131], v[140:141], v[140:141]
	v_pk_mul_f32 v[132:133], v[138:139], v[138:139]
	v_pk_add_f32 v[206:207], v[134:135], v[134:135] op_sel_hi:[0,1]
	v_pk_mov_b32 v[134:135], v[132:133], v[130:131] op_sel:[1,0]
	v_mov_b32_e32 v133, v131
	v_pk_add_f32 v[130:131], v[134:135], v[132:133]
	s_nop 0
	v_pk_add_f32 v[216:217], v[130:131], v[130:131] op_sel_hi:[0,1]
	v_pk_fma_f32 v[208:209], v[26:27], v[204:205], v[58:59] op_sel_hi:[1,0,1]
	v_pk_fma_f32 v[214:215], v[28:29], v[204:205], v[60:61] op_sel_hi:[1,0,1]
	v_pk_fma_f32 v[212:213], v[30:31], v[204:205], v[62:63] op_sel_hi:[1,0,1]
	v_mul_f32_e32 v134, v214, v214
	v_pk_fma_f32 v[134:135], v[214:215], v[214:215], v[134:135] op_sel_hi:[1,1,0]
	v_pk_fma_f32 v[210:211], v[24:25], v[204:205], v[56:57] op_sel_hi:[1,0,1]
	v_mul_f32_e32 v134, v212, v212
	v_pk_fma_f32 v[136:137], v[212:213], v[212:213], v[134:135] op_sel_hi:[1,1,0]
	v_mul_f32_e32 v134, v210, v210
	v_mul_f32_e32 v136, v211, v211
	v_mul_f32_e32 v206, v208, v208
	v_mul_f32_e32 v216, v209, v209
	v_pk_add_f32 v[130:131], v[134:135], v[136:137]
	v_pk_add_f32 v[132:133], v[206:207], v[216:217]
	s_nop 0
	v_pk_add_f32 v[130:131], v[130:131], v[132:133]
	s_nop 0
	v_add_f32_e32 v130, v130, v131
	v_mov_b32_e32 v131, v130
	s_nop 1
	v_permlane16_swap_b32_e32 v131, v130
	s_waitcnt lgkmcnt(0)
	v_add_f32_e32 v130, v130, v131
	v_mov_b32_e32 v131, v130
	s_nop 1
	v_permlane32_swap_b32_e32 v131, v130
	s_waitcnt lgkmcnt(0)
	v_add_f32_e32 v130, v130, v131
	v_fmamk_f32 v130, v130, 0x3c800000, v227
	s_nop 0
	v_rsq_f32_e32 v130, v130
	s_nop 0
	v_mul_f32_e32 v216, v245, v130
	v_pk_mul_f32 v[222:223], v[220:221], v[216:217] op_sel_hi:[1,0]
	v_pk_mul_f32 v[224:225], v[218:219], v[216:217] op_sel_hi:[1,0]
	v_mad_i64_i32 v[130:131], s[4:5], s0, v159, 0
	v_lshl_add_u64 v[206:207], v[130:131], 1, v[170:171]
	v_and_b32_e32 v130, 0x3fc0, v159
	v_mov_b32_e32 v131, v129
	v_lshl_add_u64 v[132:133], s[82:83], 0, v[130:131]
	v_lshl_add_u64 v[130:131], s[84:85], 0, v[130:131]
	v_lshl_add_u64 v[204:205], v[132:133], 0, v[186:187]
	v_lshl_add_u64 v[186:187], v[130:131], 0, v[186:187]
	global_load_dwordx4 v[134:137], v[204:205], off
	global_load_dwordx4 v[130:133], v[186:187], off
	v_pk_mul_f32 v[210:211], v[210:211], v[216:217] op_sel_hi:[1,0]
	v_pk_mul_f32 v[208:209], v[208:209], v[216:217] op_sel_hi:[1,0]
	v_add_u32_e32 v159, 0x90, v162
	v_pk_mul_f32 v[218:219], v[112:113], v[224:225]
	v_pk_mul_f32 v[220:221], v[114:115], v[222:223]
	v_pk_mul_f32 v[222:223], v[138:139], v[216:217] op_sel_hi:[1,0]
	v_pk_mul_f32 v[224:225], v[140:141], v[216:217] op_sel_hi:[1,0]
	v_pk_mul_f32 v[140:141], v[118:119], v[224:225]
	v_pk_mul_f32 v[138:139], v[116:117], v[222:223]
	s_waitcnt vmcnt(0)
; __device__ __forceinline__ unsigned pk_bf16(float lo, float hi) { f32x2 v = {lo, hi}; bf16x2_t b = __builtin_convertvector(v, bf16x2_t); return __builtin_bit_cast(unsigned, b); }
;     __device__ __forceinline__ void operator()(const f32x4 (&acc)[2][2][4][2], const Unit& u, int wr, int wc, int fr, int fq) const {
;     ...
;                         for (int n = 0; n < 2; ++n) { const f32x4 v = acc[ai][bj][m][n] * rv + *(const f32x4*)(bp + bj * HALF + 4 * n); hv[bj][n] = v; ss += (v[0] * v[0] + v[1] * v[1]) + (v[2] * v[2] + v[3] * v[3]); }
;                     ss += __shfl_xor(ss, 16); ss += __shfl_xor(ss, 32);
;                     const float rinv = rsqrtf(ss * (1.0f / 64.0f) + 1e-6f) * osc;
; #pragma unroll
;                     for (int bj = 0; bj < 2; ++bj) {
;                         const int pos = bj == 0 ? (t >> 6) : (t & 63);
;                         const f32x4 c = *(const f32x4*)(ropec + pos * 16 + 4 * fqo), s = *(const f32x4*)(ropes + pos * 16 + 4 * fqo);
;                         const f32x4 x1 = hv[bj][0] * rinv * *(const f32x4*)(gw + 32 * bj), x2 = hv[bj][1] * rinv * *(const f32x4*)(gw + 32 * bj + 16);
;                         const f32x4 o1 = x1 * c - x2 * s, o2 = x2 * c + x1 * s;
;                         u32x4 w; w.x = pk_bf16(o1[0], o1[1]); w.y = pk_bf16(o1[2], o1[3]); w.z = pk_bf16(o2[0], o2[1]); w.w = pk_bf16(o2[2], o2[3]);
;                         *(u32x4*)(base + (size_t)row * pitch + 32 * bj) = w;
;                     }
	v_pk_mul_f32 v[224:225], v[132:133], v[140:141]
	v_pk_mul_f32 v[222:223], v[130:131], v[138:139]
	v_pk_fma_f32 v[224:225], v[136:137], v[220:221], v[224:225] neg_lo:[0,0,1] neg_hi:[0,0,1]
	v_pk_fma_f32 v[222:223], v[134:135], v[218:219], v[222:223] neg_lo:[0,0,1] neg_hi:[0,0,1]
	v_pk_mul_f32 v[134:135], v[134:135], v[138:139]
	v_pk_mul_f32 v[136:137], v[136:137], v[140:141]
	s_nop 0
	v_pk_fma_f32 v[136:137], v[132:133], v[220:221], v[136:137]
	v_pk_fma_f32 v[132:133], v[130:131], v[218:219], v[134:135]
	v_cvt_pk_bf16_f32 v130, v222, v223
	v_cvt_pk_bf16_f32 v131, v224, v225
	v_cvt_pk_bf16_f32 v132, v132, v133
	v_cvt_pk_bf16_f32 v133, v136, v137
	global_store_dwordx4 v[206:207], v[130:133], off
	global_load_dwordx4 v[130:133], v[192:193], off
	s_nop 0
	global_load_dwordx4 v[134:137], v[194:195], off
	v_pk_mul_f32 v[192:193], v[212:213], v[216:217] op_sel_hi:[1,0]
	v_pk_mul_f32 v[194:195], v[214:215], v[216:217] op_sel_hi:[1,0]
	v_pk_mul_f32 v[192:193], v[50:51], v[192:193]
	v_pk_mul_f32 v[194:195], v[48:49], v[194:195]
	v_pk_mul_f32 v[140:141], v[54:55], v[208:209]
	v_pk_mul_f32 v[138:139], v[52:53], v[210:211]
	s_waitcnt vmcnt(0)
	v_pk_mul_f32 v[210:211], v[136:137], v[140:141]
	v_pk_mul_f32 v[208:209], v[134:135], v[138:139]
	v_pk_fma_f32 v[210:211], v[132:133], v[192:193], v[210:211] neg_lo:[0,0,1] neg_hi:[0,0,1]
	v_pk_fma_f32 v[208:209], v[130:131], v[194:195], v[208:209] neg_lo:[0,0,1] neg_hi:[0,0,1]
	v_pk_mul_f32 v[130:131], v[130:131], v[138:139]
	v_pk_mul_f32 v[132:133], v[132:133], v[140:141]
	s_nop 0
	v_pk_fma_f32 v[136:137], v[136:137], v[192:193], v[132:133]
	v_pk_fma_f32 v[132:133], v[134:135], v[194:195], v[130:131]
	v_cvt_pk_bf16_f32 v130, v208, v209
	v_cvt_pk_bf16_f32 v131, v210, v211
	v_cvt_pk_bf16_f32 v132, v132, v133
	v_cvt_pk_bf16_f32 v133, v136, v137
	global_store_dwordx4 v[206:207], v[130:133], off offset:64
	s_nop 1
	v_fmamk_f32 v130, v143, 0x3a800000, v227
	s_nop 0
	v_rsq_f32_e32 v130, v130
	s_nop 0
	v_mov_b32_e32 v192, v130
	v_pk_fma_f32 v[140:141], v[82:83], v[192:193], v[122:123] op_sel_hi:[1,0,1]
	v_pk_fma_f32 v[214:215], v[84:85], v[192:193], v[124:125] op_sel_hi:[1,0,1]
	v_pk_fma_f32 v[216:217], v[86:87], v[192:193], v[126:127] op_sel_hi:[1,0,1]
	v_pk_mul_f32 v[136:137], v[214:215], v[214:215]
	v_pk_mul_f32 v[134:135], v[216:217], v[216:217]
	s_nop 0
	v_pk_mov_b32 v[138:139], v[136:137], v[134:135] op_sel:[1,0]
	v_mov_b32_e32 v137, v135
	v_pk_add_f32 v[134:135], v[138:139], v[136:137]
	v_pk_fma_f32 v[138:139], v[80:81], v[192:193], v[120:121] op_sel_hi:[1,0,1]
	v_pk_mul_f32 v[130:131], v[140:141], v[140:141]
	v_pk_mul_f32 v[132:133], v[138:139], v[138:139]
	v_pk_add_f32 v[212:213], v[134:135], v[134:135] op_sel_hi:[0,1]
	v_pk_mov_b32 v[134:135], v[132:133], v[130:131] op_sel:[1,0]
	v_mov_b32_e32 v133, v131
	v_pk_add_f32 v[130:131], v[134:135], v[132:133]
	s_nop 0
	v_pk_add_f32 v[218:219], v[130:131], v[130:131] op_sel_hi:[0,1]
	v_pk_fma_f32 v[194:195], v[18:19], v[192:193], v[58:59] op_sel_hi:[1,0,1]
	v_pk_fma_f32 v[210:211], v[20:21], v[192:193], v[60:61] op_sel_hi:[1,0,1]
	v_pk_fma_f32 v[208:209], v[22:23], v[192:193], v[62:63] op_sel_hi:[1,0,1]
	v_mul_f32_e32 v134, v210, v210
	v_pk_fma_f32 v[134:135], v[210:211], v[210:211], v[134:135] op_sel_hi:[1,1,0]
	v_pk_fma_f32 v[206:207], v[16:17], v[192:193], v[56:57] op_sel_hi:[1,0,1]
	v_mul_f32_e32 v134, v208, v208
	v_pk_fma_f32 v[136:137], v[208:209], v[208:209], v[134:135] op_sel_hi:[1,1,0]
	v_mul_f32_e32 v134, v206, v206
	v_mul_f32_e32 v136, v207, v207
	v_mul_f32_e32 v212, v194, v194
	v_mul_f32_e32 v218, v195, v195
	v_pk_add_f32 v[130:131], v[134:135], v[136:137]
	v_pk_add_f32 v[132:133], v[212:213], v[218:219]
	s_nop 0
	v_pk_add_f32 v[130:131], v[130:131], v[132:133]
	s_nop 0
	v_add_f32_e32 v130, v130, v131
	v_mov_b32_e32 v131, v130
	s_nop 1
	v_permlane16_swap_b32_e32 v131, v130
	s_waitcnt lgkmcnt(0)
	v_add_f32_e32 v130, v130, v131
	v_mov_b32_e32 v131, v130
	s_nop 1
	v_permlane32_swap_b32_e32 v131, v130
	s_waitcnt lgkmcnt(0)
	v_add_f32_e32 v130, v130, v131
	v_fmamk_f32 v130, v130, 0x3c800000, v227
	s_nop 0
	v_rsq_f32_e32 v130, v130
	s_nop 0
	v_mul_f32_e32 v212, v245, v130
	v_mad_i64_i32 v[130:131], s[4:5], s0, v159, 0
	v_lshl_add_u64 v[192:193], v[130:131], 1, v[170:171]
	global_load_dwordx4 v[134:137], v[204:205], off
	global_load_dwordx4 v[130:133], v[186:187], off
	v_pk_mul_f32 v[218:219], v[216:217], v[212:213] op_sel_hi:[1,0]
	v_pk_mul_f32 v[220:221], v[214:215], v[212:213] op_sel_hi:[1,0]
	v_pk_mul_f32 v[206:207], v[206:207], v[212:213] op_sel_hi:[1,0]
	v_pk_mul_f32 v[194:195], v[194:195], v[212:213] op_sel_hi:[1,0]
	v_add_u32_e32 v159, 0xa0, v162
	v_pk_mul_f32 v[214:215], v[112:113], v[220:221]
	v_pk_mul_f32 v[216:217], v[114:115], v[218:219]
	v_pk_mul_f32 v[218:219], v[138:139], v[212:213] op_sel_hi:[1,0]
	v_pk_mul_f32 v[220:221], v[140:141], v[212:213] op_sel_hi:[1,0]
	v_pk_mul_f32 v[140:141], v[118:119], v[220:221]
	v_pk_mul_f32 v[138:139], v[116:117], v[218:219]
	s_waitcnt vmcnt(0)
	v_pk_mul_f32 v[220:221], v[132:133], v[140:141]
	v_pk_mul_f32 v[218:219], v[130:131], v[138:139]
	v_pk_fma_f32 v[220:221], v[136:137], v[216:217], v[220:221] neg_lo:[0,0,1] neg_hi:[0,0,1]
	v_pk_fma_f32 v[218:219], v[134:135], v[214:215], v[218:219] neg_lo:[0,0,1] neg_hi:[0,0,1]
	v_pk_mul_f32 v[134:135], v[134:135], v[138:139]
	v_pk_mul_f32 v[136:137], v[136:137], v[140:141]
	s_nop 0
	v_pk_fma_f32 v[136:137], v[132:133], v[216:217], v[136:137]
	v_pk_fma_f32 v[132:133], v[130:131], v[214:215], v[134:135]
	v_cvt_pk_bf16_f32 v130, v218, v219
	v_cvt_pk_bf16_f32 v131, v220, v221
	v_cvt_pk_bf16_f32 v132, v132, v133
	v_cvt_pk_bf16_f32 v133, v136, v137
	global_store_dwordx4 v[192:193], v[130:133], off
	global_load_dwordx4 v[130:133], v[188:189], off
	s_nop 0
	global_load_dwordx4 v[134:137], v[190:191], off
	v_pk_mul_f32 v[188:189], v[208:209], v[212:213] op_sel_hi:[1,0]
	v_pk_mul_f32 v[190:191], v[210:211], v[212:213] op_sel_hi:[1,0]
	v_pk_mul_f32 v[188:189], v[50:51], v[188:189]
	v_pk_mul_f32 v[190:191], v[48:49], v[190:191]
	v_pk_mul_f32 v[140:141], v[54:55], v[194:195]
	v_pk_mul_f32 v[138:139], v[52:53], v[206:207]
	s_waitcnt vmcnt(0)
; __device__ __forceinline__ unsigned pk_bf16(float lo, float hi) { f32x2 v = {lo, hi}; bf16x2_t b = __builtin_convertvector(v, bf16x2_t); return __builtin_bit_cast(unsigned, b); }
;     __device__ __forceinline__ void operator()(const f32x4 (&acc)[2][2][4][2], const Unit& u, int wr, int wc, int fr, int fq) const {
;     ...
;                         for (int n = 0; n < 2; ++n) { const f32x4 v = acc[ai][bj][m][n] * rv + *(const f32x4*)(bp + bj * HALF + 4 * n); hv[bj][n] = v; ss += (v[0] * v[0] + v[1] * v[1]) + (v[2] * v[2] + v[3] * v[3]); }
;                     ss += __shfl_xor(ss, 16); ss += __shfl_xor(ss, 32);
;                     const float rinv = rsqrtf(ss * (1.0f / 64.0f) + 1e-6f) * osc;
; #pragma unroll
;                     for (int bj = 0; bj < 2; ++bj) {
;                         const int pos = bj == 0 ? (t >> 6) : (t & 63);
;                         const f32x4 c = *(const f32x4*)(ropec + pos * 16 + 4 * fqo), s = *(const f32x4*)(ropes + pos * 16 + 4 * fqo);
;                         const f32x4 x1 = hv[bj][0] * rinv * *(const f32x4*)(gw + 32 * bj), x2 = hv[bj][1] * rinv * *(const f32x4*)(gw + 32 * bj + 16);
;                         const f32x4 o1 = x1 * c - x2 * s, o2 = x2 * c + x1 * s;
;                         u32x4 w; w.x = pk_bf16(o1[0], o1[1]); w.y = pk_bf16(o1[2], o1[3]); w.z = pk_bf16(o2[0], o2[1]); w.w = pk_bf16(o2[2], o2[3]);
;                         *(u32x4*)(base + (size_t)row * pitch + 32 * bj) = w;
;                     }
	v_pk_mul_f32 v[206:207], v[136:137], v[140:141]
	v_pk_mul_f32 v[194:195], v[134:135], v[138:139]
	v_pk_fma_f32 v[206:207], v[132:133], v[188:189], v[206:207] neg_lo:[0,0,1] neg_hi:[0,0,1]
	v_pk_fma_f32 v[194:195], v[130:131], v[190:191], v[194:195] neg_lo:[0,0,1] neg_hi:[0,0,1]
	v_pk_mul_f32 v[130:131], v[130:131], v[138:139]
	v_pk_mul_f32 v[132:133], v[132:133], v[140:141]
	s_nop 0
	v_pk_fma_f32 v[136:137], v[136:137], v[188:189], v[132:133]
	v_pk_fma_f32 v[132:133], v[134:135], v[190:191], v[130:131]
	v_cvt_pk_bf16_f32 v130, v194, v195
	v_cvt_pk_bf16_f32 v131, v206, v207
	v_cvt_pk_bf16_f32 v132, v132, v133
	v_cvt_pk_bf16_f32 v133, v136, v137
	global_store_dwordx4 v[192:193], v[130:133], off offset:64
	s_nop 1
	v_fmamk_f32 v130, v145, 0x3a800000, v227
	s_nop 0
	v_rsq_f32_e32 v130, v130
	s_nop 0
	v_mov_b32_e32 v188, v130
	v_pk_fma_f32 v[140:141], v[74:75], v[188:189], v[122:123] op_sel_hi:[1,0,1]
	v_pk_fma_f32 v[210:211], v[76:77], v[188:189], v[124:125] op_sel_hi:[1,0,1]
	v_pk_fma_f32 v[212:213], v[78:79], v[188:189], v[126:127] op_sel_hi:[1,0,1]
	v_pk_mul_f32 v[136:137], v[210:211], v[210:211]
	v_pk_mul_f32 v[134:135], v[212:213], v[212:213]
	s_nop 0
	v_pk_mov_b32 v[138:139], v[136:137], v[134:135] op_sel:[1,0]
	v_mov_b32_e32 v137, v135
	v_pk_add_f32 v[134:135], v[138:139], v[136:137]
	v_pk_fma_f32 v[138:139], v[72:73], v[188:189], v[120:121] op_sel_hi:[1,0,1]
	v_pk_mul_f32 v[130:131], v[140:141], v[140:141]
	v_pk_mul_f32 v[132:133], v[138:139], v[138:139]
	v_pk_add_f32 v[208:209], v[134:135], v[134:135] op_sel_hi:[0,1]
	v_pk_mov_b32 v[134:135], v[132:133], v[130:131] op_sel:[1,0]
	v_mov_b32_e32 v133, v131
	v_pk_add_f32 v[130:131], v[134:135], v[132:133]
	s_nop 0
	v_pk_add_f32 v[214:215], v[130:131], v[130:131] op_sel_hi:[0,1]
	v_pk_fma_f32 v[190:191], v[10:11], v[188:189], v[58:59] op_sel_hi:[1,0,1]
	v_pk_fma_f32 v[206:207], v[12:13], v[188:189], v[60:61] op_sel_hi:[1,0,1]
	v_pk_fma_f32 v[194:195], v[14:15], v[188:189], v[62:63] op_sel_hi:[1,0,1]
	v_mul_f32_e32 v134, v206, v206
	v_pk_fma_f32 v[134:135], v[206:207], v[206:207], v[134:135] op_sel_hi:[1,1,0]
	v_pk_fma_f32 v[192:193], v[8:9], v[188:189], v[56:57] op_sel_hi:[1,0,1]
	v_mul_f32_e32 v134, v194, v194
	v_pk_fma_f32 v[136:137], v[194:195], v[194:195], v[134:135] op_sel_hi:[1,1,0]
	v_mul_f32_e32 v134, v192, v192
	v_mul_f32_e32 v136, v193, v193
	v_mul_f32_e32 v208, v190, v190
	v_mul_f32_e32 v214, v191, v191
	v_pk_add_f32 v[130:131], v[134:135], v[136:137]
	v_pk_add_f32 v[132:133], v[208:209], v[214:215]
	s_nop 0
	v_pk_add_f32 v[130:131], v[130:131], v[132:133]
	s_nop 0
	v_add_f32_e32 v130, v130, v131
	v_mov_b32_e32 v131, v130
	s_nop 1
	v_permlane16_swap_b32_e32 v131, v130
	s_waitcnt lgkmcnt(0)
	v_add_f32_e32 v130, v130, v131
	v_mov_b32_e32 v131, v130
	s_nop 1
	v_permlane32_swap_b32_e32 v131, v130
	s_waitcnt lgkmcnt(0)
	v_add_f32_e32 v130, v130, v131
	v_fmamk_f32 v130, v130, 0x3c800000, v227
	s_nop 0
	v_rsq_f32_e32 v130, v130
	s_nop 0
	v_mul_f32_e32 v208, v245, v130
	v_mad_i64_i32 v[130:131], s[4:5], s0, v159, 0
	v_lshl_add_u64 v[188:189], v[130:131], 1, v[170:171]
	global_load_dwordx4 v[134:137], v[204:205], off
	global_load_dwordx4 v[130:133], v[186:187], off
	v_pk_mul_f32 v[214:215], v[212:213], v[208:209] op_sel_hi:[1,0]
	v_pk_mul_f32 v[216:217], v[210:211], v[208:209] op_sel_hi:[1,0]
	v_pk_mul_f32 v[194:195], v[194:195], v[208:209] op_sel_hi:[1,0]
	v_pk_mul_f32 v[192:193], v[192:193], v[208:209] op_sel_hi:[1,0]
	v_pk_mul_f32 v[190:191], v[190:191], v[208:209] op_sel_hi:[1,0]
	v_add_u32_e32 v159, 0xb0, v162
	v_pk_mul_f32 v[210:211], v[112:113], v[216:217]
	v_pk_mul_f32 v[212:213], v[114:115], v[214:215]
	v_pk_mul_f32 v[214:215], v[138:139], v[208:209] op_sel_hi:[1,0]
	v_pk_mul_f32 v[216:217], v[140:141], v[208:209] op_sel_hi:[1,0]
	v_pk_mul_f32 v[140:141], v[118:119], v[216:217]
	v_pk_mul_f32 v[138:139], v[116:117], v[214:215]
	s_waitcnt vmcnt(0)
	v_pk_mul_f32 v[216:217], v[132:133], v[140:141]
	v_pk_mul_f32 v[214:215], v[130:131], v[138:139]
	v_pk_fma_f32 v[216:217], v[136:137], v[212:213], v[216:217] neg_lo:[0,0,1] neg_hi:[0,0,1]
	v_pk_fma_f32 v[214:215], v[134:135], v[210:211], v[214:215] neg_lo:[0,0,1] neg_hi:[0,0,1]
	v_pk_mul_f32 v[134:135], v[134:135], v[138:139]
	v_pk_mul_f32 v[136:137], v[136:137], v[140:141]
	s_nop 0
	v_pk_fma_f32 v[136:137], v[132:133], v[212:213], v[136:137]
	v_pk_fma_f32 v[132:133], v[130:131], v[210:211], v[134:135]
	v_cvt_pk_bf16_f32 v130, v214, v215
	v_cvt_pk_bf16_f32 v131, v216, v217
	v_cvt_pk_bf16_f32 v132, v132, v133
	v_cvt_pk_bf16_f32 v133, v136, v137
	global_store_dwordx4 v[188:189], v[130:133], off
	global_load_dwordx4 v[130:133], v[196:197], off
	s_nop 0
	global_load_dwordx4 v[134:137], v[198:199], off
	v_pk_mul_f32 v[196:197], v[206:207], v[208:209] op_sel_hi:[1,0]
	v_pk_mul_f32 v[194:195], v[50:51], v[194:195]
	v_pk_mul_f32 v[196:197], v[48:49], v[196:197]
	v_pk_mul_f32 v[140:141], v[54:55], v[190:191]
	v_pk_mul_f32 v[138:139], v[52:53], v[192:193]
	s_waitcnt vmcnt(0)
; __device__ __forceinline__ unsigned pk_bf16(float lo, float hi) { f32x2 v = {lo, hi}; bf16x2_t b = __builtin_convertvector(v, bf16x2_t); return __builtin_bit_cast(unsigned, b); }
;     __device__ __forceinline__ void operator()(const f32x4 (&acc)[2][2][4][2], const Unit& u, int wr, int wc, int fr, int fq) const {
;     ...
;                         for (int n = 0; n < 2; ++n) { const f32x4 v = acc[ai][bj][m][n] * rv + *(const f32x4*)(bp + bj * HALF + 4 * n); hv[bj][n] = v; ss += (v[0] * v[0] + v[1] * v[1]) + (v[2] * v[2] + v[3] * v[3]); }
;                     ss += __shfl_xor(ss, 16); ss += __shfl_xor(ss, 32);
;                     const float rinv = rsqrtf(ss * (1.0f / 64.0f) + 1e-6f) * osc;
; #pragma unroll
;                     for (int bj = 0; bj < 2; ++bj) {
;                         const int pos = bj == 0 ? (t >> 6) : (t & 63);
;                         const f32x4 c = *(const f32x4*)(ropec + pos * 16 + 4 * fqo), s = *(const f32x4*)(ropes + pos * 16 + 4 * fqo);
;                         const f32x4 x1 = hv[bj][0] * rinv * *(const f32x4*)(gw + 32 * bj), x2 = hv[bj][1] * rinv * *(const f32x4*)(gw + 32 * bj + 16);
;                         const f32x4 o1 = x1 * c - x2 * s, o2 = x2 * c + x1 * s;
;                         u32x4 w; w.x = pk_bf16(o1[0], o1[1]); w.y = pk_bf16(o1[2], o1[3]); w.z = pk_bf16(o2[0], o2[1]); w.w = pk_bf16(o2[2], o2[3]);
;                         *(u32x4*)(base + (size_t)row * pitch + 32 * bj) = w;
;                     }
	v_pk_mul_f32 v[192:193], v[136:137], v[140:141]
	v_pk_mul_f32 v[190:191], v[134:135], v[138:139]
	v_pk_fma_f32 v[192:193], v[132:133], v[194:195], v[192:193] neg_lo:[0,0,1] neg_hi:[0,0,1]
	v_pk_fma_f32 v[190:191], v[130:131], v[196:197], v[190:191] neg_lo:[0,0,1] neg_hi:[0,0,1]
	v_pk_mul_f32 v[130:131], v[130:131], v[138:139]
	v_pk_mul_f32 v[132:133], v[132:133], v[140:141]
	s_nop 0
	v_pk_fma_f32 v[136:137], v[136:137], v[194:195], v[132:133]
	v_pk_fma_f32 v[132:133], v[134:135], v[196:197], v[130:131]
	v_cvt_pk_bf16_f32 v130, v190, v191
	v_cvt_pk_bf16_f32 v131, v192, v193
	v_cvt_pk_bf16_f32 v132, v132, v133
	v_cvt_pk_bf16_f32 v133, v136, v137
	global_store_dwordx4 v[188:189], v[130:133], off offset:64
	s_nop 1
	v_fmamk_f32 v130, v147, 0x3a800000, v227
	s_nop 0
	v_rsq_f32_e32 v130, v130
	s_nop 0
	v_mov_b32_e32 v188, v130
	v_pk_fma_f32 v[140:141], v[66:67], v[188:189], v[122:123] op_sel_hi:[1,0,1]
	v_pk_fma_f32 v[196:197], v[68:69], v[188:189], v[124:125] op_sel_hi:[1,0,1]
	v_pk_fma_f32 v[198:199], v[70:71], v[188:189], v[126:127] op_sel_hi:[1,0,1]
	v_pk_mul_f32 v[136:137], v[196:197], v[196:197]
	v_pk_mul_f32 v[134:135], v[198:199], v[198:199]
	s_nop 0
	v_pk_mov_b32 v[138:139], v[136:137], v[134:135] op_sel:[1,0]
	v_mov_b32_e32 v137, v135
	v_pk_add_f32 v[134:135], v[138:139], v[136:137]
	v_pk_fma_f32 v[138:139], v[64:65], v[188:189], v[120:121] op_sel_hi:[1,0,1]
	v_pk_mul_f32 v[130:131], v[140:141], v[140:141]
	v_pk_mul_f32 v[132:133], v[138:139], v[138:139]
	v_pk_add_f32 v[194:195], v[134:135], v[134:135] op_sel_hi:[0,1]
	v_pk_mov_b32 v[134:135], v[132:133], v[130:131] op_sel:[1,0]
	v_mov_b32_e32 v133, v131
	v_pk_add_f32 v[130:131], v[134:135], v[132:133]
	s_nop 0
	v_pk_add_f32 v[206:207], v[130:131], v[130:131] op_sel_hi:[0,1]
	v_pk_fma_f32 v[172:173], v[2:3], v[188:189], v[58:59] op_sel_hi:[1,0,1]
	v_pk_fma_f32 v[192:193], v[4:5], v[188:189], v[60:61] op_sel_hi:[1,0,1]
	v_pk_fma_f32 v[190:191], v[6:7], v[188:189], v[62:63] op_sel_hi:[1,0,1]
	v_mul_f32_e32 v134, v192, v192
	v_pk_fma_f32 v[134:135], v[192:193], v[192:193], v[134:135] op_sel_hi:[1,1,0]
	v_pk_fma_f32 v[188:189], v[0:1], v[188:189], v[56:57] op_sel_hi:[1,0,1]
	v_mul_f32_e32 v134, v190, v190
	v_pk_fma_f32 v[136:137], v[190:191], v[190:191], v[134:135] op_sel_hi:[1,1,0]
	v_mul_f32_e32 v134, v188, v188
	v_mul_f32_e32 v136, v189, v189
	v_mul_f32_e32 v194, v172, v172
	v_mul_f32_e32 v206, v173, v173
	v_pk_add_f32 v[130:131], v[134:135], v[136:137]
	v_pk_add_f32 v[132:133], v[194:195], v[206:207]
	s_nop 0
	v_pk_add_f32 v[130:131], v[130:131], v[132:133]
	s_nop 0
	v_add_f32_e32 v130, v130, v131
	v_mov_b32_e32 v131, v130
	s_nop 1
	v_permlane16_swap_b32_e32 v131, v130
	s_waitcnt lgkmcnt(0)
	v_add_f32_e32 v130, v130, v131
	v_mov_b32_e32 v131, v130
	s_nop 1
	v_permlane32_swap_b32_e32 v131, v130
	s_waitcnt lgkmcnt(0)
	v_add_f32_e32 v130, v130, v131
	v_fmamk_f32 v130, v130, 0x3c800000, v227
	s_nop 0
	v_rsq_f32_e32 v130, v130
	s_nop 0
	v_mul_f32_e32 v194, v245, v130
	v_mad_i64_i32 v[130:131], s[0:1], s0, v159, 0
	v_lshl_add_u64 v[170:171], v[130:131], 1, v[170:171]
	global_load_dwordx4 v[134:137], v[204:205], off
	global_load_dwordx4 v[130:133], v[186:187], off
	v_pk_mul_f32 v[204:205], v[198:199], v[194:195] op_sel_hi:[1,0]
	v_pk_mul_f32 v[186:187], v[196:197], v[194:195] op_sel_hi:[1,0]
	v_pk_mul_f32 v[188:189], v[188:189], v[194:195] op_sel_hi:[1,0]
	v_pk_mul_f32 v[172:173], v[172:173], v[194:195] op_sel_hi:[1,0]
	s_mov_b64 s[0:1], 0
	v_pk_mul_f32 v[186:187], v[112:113], v[186:187]
	v_pk_mul_f32 v[196:197], v[114:115], v[204:205]
	v_pk_mul_f32 v[198:199], v[138:139], v[194:195] op_sel_hi:[1,0]
	v_pk_mul_f32 v[204:205], v[140:141], v[194:195] op_sel_hi:[1,0]
	v_pk_mul_f32 v[140:141], v[118:119], v[204:205]
	v_pk_mul_f32 v[138:139], v[116:117], v[198:199]
	s_waitcnt vmcnt(0)
	v_pk_mul_f32 v[204:205], v[132:133], v[140:141]
	v_pk_mul_f32 v[198:199], v[130:131], v[138:139]
	v_pk_fma_f32 v[204:205], v[136:137], v[196:197], v[204:205] neg_lo:[0,0,1] neg_hi:[0,0,1]
	v_pk_fma_f32 v[198:199], v[134:135], v[186:187], v[198:199] neg_lo:[0,0,1] neg_hi:[0,0,1]
	v_pk_mul_f32 v[134:135], v[134:135], v[138:139]
	v_pk_mul_f32 v[136:137], v[136:137], v[140:141]
	s_nop 0
	v_pk_fma_f32 v[136:137], v[132:133], v[196:197], v[136:137]
	v_pk_fma_f32 v[132:133], v[130:131], v[186:187], v[134:135]
	v_cvt_pk_bf16_f32 v130, v198, v199
	v_cvt_pk_bf16_f32 v131, v204, v205
	v_cvt_pk_bf16_f32 v132, v132, v133
	v_cvt_pk_bf16_f32 v133, v136, v137
	global_store_dwordx4 v[170:171], v[130:133], off
	global_load_dwordx4 v[130:133], v[200:201], off
	s_nop 0
	global_load_dwordx4 v[134:137], v[202:203], off
	v_pk_mul_f32 v[186:187], v[190:191], v[194:195] op_sel_hi:[1,0]
	v_pk_mul_f32 v[190:191], v[192:193], v[194:195] op_sel_hi:[1,0]
	v_pk_mul_f32 v[186:187], v[50:51], v[186:187]
	v_pk_mul_f32 v[190:191], v[48:49], v[190:191]
	v_pk_mul_f32 v[140:141], v[54:55], v[172:173]
	v_pk_mul_f32 v[138:139], v[52:53], v[188:189]
	s_waitcnt vmcnt(0)
	v_pk_mul_f32 v[172:173], v[136:137], v[140:141]
	v_pk_mul_f32 v[168:169], v[134:135], v[138:139]
	v_pk_fma_f32 v[172:173], v[132:133], v[186:187], v[172:173] neg_lo:[0,0,1] neg_hi:[0,0,1]
	v_pk_fma_f32 v[168:169], v[130:131], v[190:191], v[168:169] neg_lo:[0,0,1] neg_hi:[0,0,1]
	v_pk_mul_f32 v[130:131], v[130:131], v[138:139]
	v_pk_mul_f32 v[132:133], v[132:133], v[140:141]
	s_nop 0
	v_pk_fma_f32 v[136:137], v[136:137], v[186:187], v[132:133]
	v_pk_fma_f32 v[132:133], v[134:135], v[190:191], v[130:131]
	v_cvt_pk_bf16_f32 v130, v168, v169
	v_cvt_pk_bf16_f32 v131, v172, v173
	v_cvt_pk_bf16_f32 v132, v132, v133
	v_cvt_pk_bf16_f32 v133, v136, v137
	global_store_dwordx4 v[170:171], v[130:133], off offset:64

; #define WAIT_BAR(N) asm volatile("s_waitcnt vmcnt(" #N ") lgkmcnt(0)\n\ts_barrier":::"memory")
;   #define RESC() do{}while(0)
;   #define ROT() do{sl_prev=sl_cur;sl_cur=sl_next;sl_next=(sl_next==(NSLOT-1)*SLOTB)?0:sl_next+SLOTB;}while(0)
; template<int THRL> __device__ __forceinline__ void attn_unit(int b,int h,int qb,const bf16*Q,const bf16*__restrict__ K,const bf16*__restrict__ V,bf16*O,float*gssrow,float mref,char*shm){
;     ...
;     STEP(pB0,pB1,pA0,pA1,t,true,true,true);     WAIT_BAR(2); RESC(); ROT();
.LBB0_450:
	s_mov_b32 s30, s29
	s_mov_b32 s29, s21
	v_add_u32_e32 v128, s31, v199
	ds_read_b64_tr_b16 v[204:205], v128 offset:24576
	ds_read_b64_tr_b16 v[206:207], v128 offset:25088
	v_add_f32_e32 v84, v64, v65
	v_add_f32_e32 v84, v66, v84
	v_add_f32_e32 v84, v67, v84
	v_add_f32_e32 v84, v68, v84
	v_add_f32_e32 v84, v69, v84
	v_cvt_pk_bf16_f32 v154, v64, v65
	v_cvt_pk_bf16_f32 v155, v66, v67
	v_mfma_f32_32x32x16_bf16 v[96:111], v[80:83], v[158:161], v[32:47]
	ds_read_b64_tr_b16 v[64:65], v128 offset:28672
	ds_read_b64_tr_b16 v[66:67], v128 offset:29184
	v_add_f32_e32 v80, v70, v84
	v_add_f32_e32 v80, v71, v80
	v_add_f32_e32 v80, v72, v80
	v_add_f32_e32 v130, v73, v80
	v_mfma_f32_32x32x16_bf16 v[80:95], v[166:169], v[158:161], v[32:47]
	v_cvt_pk_bf16_f32 v156, v68, v69
	v_cvt_pk_bf16_f32 v157, v70, v71
	ds_read_b64_tr_b16 v[68:69], v128 offset:25600
	ds_read_b64_tr_b16 v[70:71], v128 offset:26112
	v_add_f32_e32 v130, v74, v130
	v_add_f32_e32 v130, v75, v130
	v_add_f32_e32 v130, v76, v130
	v_add_f32_e32 v130, v77, v130
	v_cvt_pk_bf16_f32 v146, v72, v73
	v_cvt_pk_bf16_f32 v147, v74, v75
	v_mfma_f32_32x32x16_bf16 v[96:111], v[170:173], v[150:153], v[96:111]
	ds_read_b64_tr_b16 v[72:73], v128 offset:29696
	ds_read_b64_tr_b16 v[74:75], v128 offset:30208
	v_mfma_f32_32x32x16_bf16 v[80:95], v[162:165], v[150:153], v[80:95]
	v_add_f32_e32 v130, v78, v130
	v_add_f32_e32 v130, v79, v130
	v_add_f32_e32 v130, v48, v130
	v_add_f32_e32 v130, v49, v130
	v_cvt_pk_bf16_f32 v148, v76, v77
	v_cvt_pk_bf16_f32 v149, v78, v79
	ds_read_b64_tr_b16 v[76:77], v128 offset:26624
	ds_read_b64_tr_b16 v[78:79], v128 offset:27136
	v_mfma_f32_32x32x16_bf16 v[96:111], v[124:127], v[142:145], v[96:111]
	v_add_f32_e32 v124, v50, v130
	v_add_f32_e32 v124, v51, v124
	v_add_f32_e32 v124, v52, v124
	v_add_f32_e32 v124, v53, v124
	v_cvt_pk_bf16_f32 v138, v48, v49
	v_cvt_pk_bf16_f32 v139, v50, v51
	ds_read_b64_tr_b16 v[48:49], v128 offset:30720
	ds_read_b64_tr_b16 v[50:51], v128 offset:31232
	v_mfma_f32_32x32x16_bf16 v[80:95], v[120:123], v[142:145], v[80:95]
	v_add_f32_e32 v120, v54, v124
	v_add_f32_e32 v120, v55, v120
	v_add_f32_e32 v120, v56, v120
	v_add_f32_e32 v120, v57, v120
	v_cvt_pk_bf16_f32 v140, v52, v53
	v_cvt_pk_bf16_f32 v141, v54, v55
	ds_read_b64_tr_b16 v[52:53], v128 offset:27648
	ds_read_b64_tr_b16 v[54:55], v128 offset:28160
	v_mfma_f32_32x32x16_bf16 v[96:111], v[116:119], v[134:137], v[96:111]
	v_add_f32_e32 v116, v58, v120
	v_add_f32_e32 v116, v59, v116
	v_add_f32_e32 v116, v60, v116
	v_add_f32_e32 v116, v61, v116
	v_cvt_pk_bf16_f32 v130, v56, v57
	v_cvt_pk_bf16_f32 v131, v58, v59
	ds_read_b64_tr_b16 v[56:57], v128 offset:31744
	ds_read_b64_tr_b16 v[58:59], v128 offset:32256
	v_mfma_f32_32x32x16_bf16 v[80:95], v[112:115], v[134:137], v[80:95]
	v_add_f32_e32 v112, v62, v116
	v_add_f32_e32 v112, v63, v112
	v_cvt_pk_bf16_f32 v132, v60, v61
	v_cvt_pk_bf16_f32 v133, v62, v63
	s_add_i32 m0, s21, s5
	s_nop 0
	global_load_lds_dwordx4 v216, s[98:99]
	s_add_i32 m0, s30, s4
	s_nop 0
	global_load_lds_dwordx4 v217, s[100:101]
	v_add_f32_e32 v128, v203, v112
	s_waitcnt lgkmcnt(14)
	v_mfma_f32_32x32x16_bf16 v[0:15], v[154:157], v[204:207], v[0:15]
	v_exp_f32_e32 v96, v96
	v_exp_f32_e32 v97, v97
	v_exp_f32_e32 v98, v98
	v_exp_f32_e32 v99, v99
	s_waitcnt lgkmcnt(12)
	v_mfma_f32_32x32x16_bf16 v[16:31], v[154:157], v[64:67], v[16:31]
	v_exp_f32_e32 v100, v100
	v_exp_f32_e32 v101, v101
	v_exp_f32_e32 v102, v102
	v_exp_f32_e32 v103, v103
	v_add_u32_e32 v64, s30, v200
	ds_read_b128 v[60:63], v64
	ds_read_b128 v[116:119], v64 offset:512
	s_waitcnt lgkmcnt(12)
	v_mfma_f32_32x32x16_bf16 v[0:15], v[146:149], v[68:71], v[0:15]
	v_exp_f32_e32 v104, v104
	v_exp_f32_e32 v105, v105
	v_exp_f32_e32 v106, v106
	v_exp_f32_e32 v107, v107
	ds_read_b128 v[120:123], v64 offset:2048
	ds_read_b128 v[124:127], v64 offset:2560
	s_waitcnt lgkmcnt(12)
	v_mfma_f32_32x32x16_bf16 v[16:31], v[146:149], v[72:75], v[16:31]
	v_exp_f32_e32 v108, v108
	v_exp_f32_e32 v109, v109
	v_exp_f32_e32 v110, v110
	v_exp_f32_e32 v111, v111
	ds_read_b128 v[162:165], v64 offset:4096
	ds_read_b128 v[166:169], v64 offset:4608
	s_waitcnt lgkmcnt(12)
	v_mfma_f32_32x32x16_bf16 v[0:15], v[138:141], v[76:79], v[0:15]
	v_exp_f32_e32 v80, v80
	v_exp_f32_e32 v81, v81
	v_exp_f32_e32 v82, v82
	v_exp_f32_e32 v83, v83
	ds_read_b128 v[170:173], v64 offset:6144
	ds_read_b128 v[112:115], v64 offset:6656
	s_waitcnt lgkmcnt(12)
	v_mfma_f32_32x32x16_bf16 v[16:31], v[138:141], v[48:51], v[16:31]
	v_exp_f32_e32 v84, v84
	v_exp_f32_e32 v85, v85
	v_exp_f32_e32 v86, v86
	v_exp_f32_e32 v87, v87
	s_waitcnt lgkmcnt(10)
	v_mfma_f32_32x32x16_bf16 v[0:15], v[130:133], v[52:55], v[0:15]
	v_exp_f32_e32 v88, v88
	v_exp_f32_e32 v89, v89
	v_exp_f32_e32 v90, v90
	v_exp_f32_e32 v91, v91
	s_waitcnt lgkmcnt(8)
	v_mfma_f32_32x32x16_bf16 v[16:31], v[130:133], v[56:59], v[16:31]
	v_exp_f32_e32 v92, v92
	v_exp_f32_e32 v93, v93
	v_exp_f32_e32 v94, v94
	v_exp_f32_e32 v95, v95
	s_waitcnt vmcnt(2) lgkmcnt(0)
	s_barrier
; #define WAIT_BAR(N) asm volatile("s_waitcnt vmcnt(" #N ") lgkmcnt(0)\n\ts_barrier":::"memory")
;   #define RESC() do{}while(0)
;   #define ROT() do{sl_prev=sl_cur;sl_cur=sl_next;sl_next=(sl_next==(NSLOT-1)*SLOTB)?0:sl_next+SLOTB;}while(0)
; template<int THRL> __device__ __forceinline__ void attn_unit(int b,int h,int qb,const bf16*Q,const bf16*__restrict__ K,const bf16*__restrict__ V,bf16*O,float*gssrow,float mref,char*shm){
;     ...
;     STEP(pA0,pA1,pB0,pB1,t+1,true,true,true);   WAIT_BAR(2); RESC(); ROT();
	s_add_i32 s21, s30, 0x2000
	s_cmpk_lg_i32 s30, 0x4000
	s_cselect_b32 s21, s21, 0
	v_add_u32_e32 v174, s29, v199
	ds_read_b64_tr_b16 v[204:205], v174 offset:24576
	ds_read_b64_tr_b16 v[206:207], v174 offset:25088
	v_mfma_f32_32x32x16_bf16 v[64:79], v[60:63], v[158:161], v[32:47]
	v_add_f32_e32 v48, v96, v97
	v_add_f32_e32 v48, v98, v48
	v_add_f32_e32 v48, v99, v48
	v_add_f32_e32 v48, v100, v48
	v_add_f32_e32 v48, v101, v48
	v_cvt_pk_bf16_f32 v154, v96, v97
	v_cvt_pk_bf16_f32 v155, v98, v99
	ds_read_b64_tr_b16 v[96:97], v174 offset:28672
	ds_read_b64_tr_b16 v[98:99], v174 offset:29184
	v_add_f32_e32 v48, v102, v48
	v_add_f32_e32 v48, v103, v48
	v_add_f32_e32 v48, v104, v48
	v_add_f32_e32 v130, v105, v48
	v_mfma_f32_32x32x16_bf16 v[48:63], v[116:119], v[158:161], v[32:47]
	v_cvt_pk_bf16_f32 v156, v100, v101
	v_cvt_pk_bf16_f32 v157, v102, v103
	ds_read_b64_tr_b16 v[100:101], v174 offset:25600
	ds_read_b64_tr_b16 v[102:103], v174 offset:26112
	v_mfma_f32_32x32x16_bf16 v[64:79], v[120:123], v[150:153], v[64:79]
	v_add_f32_e32 v116, v106, v130
	v_add_f32_e32 v116, v107, v116
	v_add_f32_e32 v116, v108, v116
	v_add_f32_e32 v116, v109, v116
	v_cvt_pk_bf16_f32 v146, v104, v105
	v_cvt_pk_bf16_f32 v147, v106, v107
	ds_read_b64_tr_b16 v[104:105], v174 offset:29696
	ds_read_b64_tr_b16 v[106:107], v174 offset:30208
	v_mfma_f32_32x32x16_bf16 v[48:63], v[124:127], v[150:153], v[48:63]
	v_add_f32_e32 v116, v110, v116
	v_add_f32_e32 v116, v111, v116
	v_add_f32_e32 v116, v80, v116
	v_add_f32_e32 v116, v81, v116
	v_cvt_pk_bf16_f32 v148, v108, v109
	v_cvt_pk_bf16_f32 v149, v110, v111
	ds_read_b64_tr_b16 v[108:109], v174 offset:26624
	ds_read_b64_tr_b16 v[110:111], v174 offset:27136
	v_mfma_f32_32x32x16_bf16 v[64:79], v[162:165], v[142:145], v[64:79]
	v_add_f32_e32 v116, v82, v116
	v_add_f32_e32 v116, v83, v116
	v_add_f32_e32 v116, v84, v116
	v_add_f32_e32 v116, v85, v116
	v_cvt_pk_bf16_f32 v138, v80, v81
	v_cvt_pk_bf16_f32 v139, v82, v83
	ds_read_b64_tr_b16 v[208:209], v174 offset:30720
	ds_read_b64_tr_b16 v[210:211], v174 offset:31232
	v_mfma_f32_32x32x16_bf16 v[48:63], v[166:169], v[142:145], v[48:63]
	v_add_f32_e32 v80, v86, v116
	v_add_f32_e32 v80, v87, v80
	v_add_f32_e32 v80, v88, v80
	v_add_f32_e32 v80, v89, v80
	v_cvt_pk_bf16_f32 v140, v84, v85
	v_cvt_pk_bf16_f32 v141, v86, v87
	ds_read_b64_tr_b16 v[84:85], v174 offset:27648
	ds_read_b64_tr_b16 v[86:87], v174 offset:28160
	v_mfma_f32_32x32x16_bf16 v[64:79], v[170:173], v[134:137], v[64:79]
	v_add_f32_e32 v80, v90, v80
	v_add_f32_e32 v80, v91, v80
	v_add_f32_e32 v80, v92, v80
	v_add_f32_e32 v80, v93, v80
	v_cvt_pk_bf16_f32 v130, v88, v89
	v_cvt_pk_bf16_f32 v131, v90, v91
	ds_read_b64_tr_b16 v[88:89], v174 offset:31744
	ds_read_b64_tr_b16 v[90:91], v174 offset:32256
	v_mfma_f32_32x32x16_bf16 v[48:63], v[112:115], v[134:137], v[48:63]
	v_add_f32_e32 v80, v94, v80
	v_add_f32_e32 v80, v95, v80
	v_cvt_pk_bf16_f32 v132, v92, v93
	v_cvt_pk_bf16_f32 v133, v94, v95
	s_mov_b64 s[48:49], 0x10000
	v_add_f32_e32 v203, v128, v80
	s_add_i32 m0, s30, s5
	s_nop 0
	global_load_lds_dwordx4 v218, s[98:99]
	s_add_i32 m0, s21, s4
	s_nop 0
	global_load_lds_dwordx4 v219, s[100:101]
	s_waitcnt lgkmcnt(14)
	v_mfma_f32_32x32x16_bf16 v[0:15], v[154:157], v[204:207], v[0:15]
	v_exp_f32_e32 v64, v64
	v_exp_f32_e32 v65, v65
	v_exp_f32_e32 v66, v66
	v_exp_f32_e32 v67, v67
	s_waitcnt lgkmcnt(12)
	v_mfma_f32_32x32x16_bf16 v[16:31], v[154:157], v[96:99], v[16:31]
	v_exp_f32_e32 v68, v68
	v_exp_f32_e32 v69, v69
	v_exp_f32_e32 v70, v70
	v_exp_f32_e32 v71, v71
	v_add_u32_e32 v92, s21, v200
	ds_read_b128 v[80:83], v92
	ds_read_b128 v[166:169], v92 offset:512
	s_waitcnt lgkmcnt(12)
	v_mfma_f32_32x32x16_bf16 v[0:15], v[146:149], v[100:103], v[0:15]
	v_exp_f32_e32 v72, v72
	v_exp_f32_e32 v73, v73
	v_exp_f32_e32 v74, v74
	v_exp_f32_e32 v75, v75
	ds_read_b128 v[170:173], v92 offset:2048
	ds_read_b128 v[162:165], v92 offset:2560
	s_waitcnt lgkmcnt(12)
	v_mfma_f32_32x32x16_bf16 v[16:31], v[146:149], v[104:107], v[16:31]
	v_exp_f32_e32 v76, v76
	v_exp_f32_e32 v77, v77
	v_exp_f32_e32 v78, v78
	v_exp_f32_e32 v79, v79
	ds_read_b128 v[124:127], v92 offset:4096
	ds_read_b128 v[120:123], v92 offset:4608
	s_waitcnt lgkmcnt(12)
	v_mfma_f32_32x32x16_bf16 v[0:15], v[138:141], v[108:111], v[0:15]
	v_exp_f32_e32 v48, v48
	v_exp_f32_e32 v49, v49
	v_exp_f32_e32 v50, v50
	v_exp_f32_e32 v51, v51
	ds_read_b128 v[116:119], v92 offset:6144
	ds_read_b128 v[112:115], v92 offset:6656
	s_waitcnt lgkmcnt(12)
	v_mfma_f32_32x32x16_bf16 v[16:31], v[138:141], v[208:211], v[16:31]
	v_exp_f32_e32 v52, v52
	v_exp_f32_e32 v53, v53
	v_exp_f32_e32 v54, v54
	v_exp_f32_e32 v55, v55
	s_waitcnt lgkmcnt(10)
	v_mfma_f32_32x32x16_bf16 v[0:15], v[130:133], v[84:87], v[0:15]
	v_exp_f32_e32 v56, v56
	v_exp_f32_e32 v57, v57
	v_exp_f32_e32 v58, v58
	v_exp_f32_e32 v59, v59
	s_waitcnt lgkmcnt(8)
	v_mfma_f32_32x32x16_bf16 v[16:31], v[130:133], v[88:91], v[16:31]
	v_exp_f32_e32 v60, v60
	v_exp_f32_e32 v61, v61
	v_exp_f32_e32 v62, v62
	v_exp_f32_e32 v63, v63
	s_add_i32 s29, s21, 0x2000
	s_waitcnt vmcnt(2) lgkmcnt(0)
	s_barrier
	s_add_u32 s98, s98, 0x8000
	s_addc_u32 s99, s99, 0
	s_add_u32 s100, s100, 0x8000
	s_addc_u32 s101, s101, 0
	s_cmpk_lg_i32 s21, 0x4000
	s_cselect_b32 s29, s29, 0
	s_add_i32 s20, s20, 2
	s_cmpk_gt_u32 s20, 0xf8
	s_mov_b32 s31, s30
	s_cbranch_scc0 .LBB0_450
;   #define RESC() do{}while(0)
;   #define ROT() do{sl_prev=sl_cur;sl_cur=sl_next;sl_next=(sl_next==(NSLOT-1)*SLOTB)?0:sl_next+SLOTB;}while(0)
;   #define ENDW(tt) do{ if((tt)+3<NT){WAIT_BAR(2);} else if((tt)+2<NT){WAIT_BAR(1);} else {WAIT_BAR(0);} }while(0)
; template<int THRL> __device__ __forceinline__ void attn_unit(int b,int h,int qb,const bf16*Q,const bf16*__restrict__ K,const bf16*__restrict__ V,bf16*O,float*gssrow,float mref,char*shm){
;     ...
;   for(;t+1<NT;t+=2){
;     STEP(pB0,pB1,pA0,pA1,t,(t+3<NT),(t+1<NT),(t+1<NT));       ENDW(t);   RESC(); ROT();
;     STEP(pA0,pA1,pB0,pB1,t+1,(t+4<NT),(t+2<NT),(t+2<NT));     ENDW(t+1); RESC(); ROT();
	s_and_b32 s15, s15, 0x3fffffc0
	s_cmp_lg_u32 0, -1
	s_cselect_b32 s20, 0, 0
	s_lshl_b32 s15, s15, 2
	s_addk_i32 s20, 0x6000
	s_add_i32 s15, s15, 0
	v_add3_u32 v128, v202, s20, v201
	v_add_u32_e32 v174, s30, v199
	ds_read_b64_tr_b16 v[190:191], v174 offset:24576
	ds_read_b64_tr_b16 v[192:193], v174 offset:25088
	v_add_f32_e32 v84, v64, v65
	v_add_f32_e32 v84, v66, v84
	v_add_f32_e32 v84, v67, v84
	v_add_f32_e32 v84, v68, v84
	v_add_f32_e32 v84, v69, v84
	v_cvt_pk_bf16_f32 v154, v64, v65
	v_cvt_pk_bf16_f32 v155, v66, v67
	s_waitcnt lgkmcnt(9)
	v_mfma_f32_32x32x16_bf16 v[96:111], v[80:83], v[158:161], v[32:47]
	ds_read_b64_tr_b16 v[64:65], v174 offset:28672
	ds_read_b64_tr_b16 v[66:67], v174 offset:29184
	v_add_f32_e32 v80, v70, v84
	v_add_f32_e32 v80, v71, v80
	v_add_f32_e32 v80, v72, v80
	v_add_f32_e32 v130, v73, v80
	v_cvt_pk_bf16_f32 v156, v68, v69
	v_cvt_pk_bf16_f32 v157, v70, v71
	s_waitcnt lgkmcnt(10)
	v_mfma_f32_32x32x16_bf16 v[80:95], v[166:169], v[158:161], v[32:47]
	ds_read_b64_tr_b16 v[68:69], v174 offset:25600
	ds_read_b64_tr_b16 v[70:71], v174 offset:26112
	v_add_f32_e32 v130, v74, v130
	v_add_f32_e32 v130, v75, v130
	v_add_f32_e32 v130, v76, v130
	v_add_f32_e32 v130, v77, v130
	v_cvt_pk_bf16_f32 v146, v72, v73
	v_cvt_pk_bf16_f32 v147, v74, v75
	s_waitcnt lgkmcnt(11)
	v_mfma_f32_32x32x16_bf16 v[96:111], v[170:173], v[150:153], v[96:111]
	ds_read_b64_tr_b16 v[72:73], v174 offset:29696
	ds_read_b64_tr_b16 v[74:75], v174 offset:30208
	v_add_f32_e32 v130, v78, v130
	v_add_f32_e32 v130, v79, v130
	v_add_f32_e32 v130, v48, v130
	v_add_f32_e32 v130, v49, v130
	v_cvt_pk_bf16_f32 v148, v76, v77
	v_cvt_pk_bf16_f32 v149, v78, v79
	s_waitcnt lgkmcnt(12)
	v_mfma_f32_32x32x16_bf16 v[80:95], v[162:165], v[150:153], v[80:95]
	ds_read_b64_tr_b16 v[76:77], v174 offset:26624
	ds_read_b64_tr_b16 v[78:79], v174 offset:27136
	s_waitcnt lgkmcnt(13)
	v_mfma_f32_32x32x16_bf16 v[96:111], v[124:127], v[142:145], v[96:111]
	v_add_f32_e32 v124, v50, v130
	v_add_f32_e32 v124, v51, v124
	v_add_f32_e32 v124, v52, v124
	v_add_f32_e32 v124, v53, v124
	v_cvt_pk_bf16_f32 v138, v48, v49
	v_cvt_pk_bf16_f32 v139, v50, v51
	ds_read_b64_tr_b16 v[48:49], v174 offset:30720
	ds_read_b64_tr_b16 v[50:51], v174 offset:31232
	s_waitcnt lgkmcnt(14)
	v_mfma_f32_32x32x16_bf16 v[80:95], v[120:123], v[142:145], v[80:95]
	v_add_f32_e32 v120, v54, v124
	v_add_f32_e32 v120, v55, v120
	v_add_f32_e32 v120, v56, v120
	v_add_f32_e32 v120, v57, v120
	v_cvt_pk_bf16_f32 v140, v52, v53
	v_cvt_pk_bf16_f32 v141, v54, v55
	ds_read_b64_tr_b16 v[52:53], v174 offset:27648
	ds_read_b64_tr_b16 v[54:55], v174 offset:28160
	s_waitcnt lgkmcnt(14)
	v_mfma_f32_32x32x16_bf16 v[96:111], v[116:119], v[134:137], v[96:111]
	v_add_f32_e32 v116, v58, v120
	v_add_f32_e32 v116, v59, v116
	v_add_f32_e32 v116, v60, v116
	v_add_f32_e32 v116, v61, v116
	v_cvt_pk_bf16_f32 v130, v56, v57
	v_cvt_pk_bf16_f32 v131, v58, v59
	ds_read_b64_tr_b16 v[56:57], v174 offset:31744
	ds_read_b64_tr_b16 v[58:59], v174 offset:32256
	v_mfma_f32_32x32x16_bf16 v[80:95], v[112:115], v[134:137], v[80:95]
	v_add_f32_e32 v112, v62, v116
	v_add_f32_e32 v112, v63, v112
	v_add_f32_e32 v112, 0, v112
	v_cvt_pk_bf16_f32 v132, v60, v61
	v_cvt_pk_bf16_f32 v133, v62, v63
	s_mov_b64 s[12:13], 0x3f8000
	s_add_i32 s20, s21, s5
	v_lshl_add_u64 v[60:61], v[188:189], 0, s[12:13]
	s_mov_b32 s30, m0
	s_mov_b32 m0, s20
	s_nop 0
	global_load_lds_dwordx4 v[60:61], off
	s_mov_b32 m0, s30
	s_mov_b64 s[30:31], 0x3f0000
	v_lshl_add_u64 v[60:61], v[186:187], 0, s[30:31]
	s_add_i32 s20, s29, s4
	s_mov_b32 s30, m0
	s_mov_b32 m0, s20
	s_nop 0
	global_load_lds_dwordx4 v[60:61], off
	s_mov_b32 m0, s30
	v_add_f32_e32 v174, v203, v112
	s_waitcnt lgkmcnt(14)
	v_mfma_f32_32x32x16_bf16 v[0:15], v[154:157], v[190:193], v[0:15]
	v_exp_f32_e32 v96, v96
	v_exp_f32_e32 v97, v97
	v_exp_f32_e32 v98, v98
	v_exp_f32_e32 v99, v99
	s_waitcnt lgkmcnt(12)
	v_mfma_f32_32x32x16_bf16 v[16:31], v[154:157], v[64:67], v[16:31]
	v_exp_f32_e32 v100, v100
	v_exp_f32_e32 v101, v101
	v_exp_f32_e32 v102, v102
	v_exp_f32_e32 v103, v103
	v_add_u32_e32 v64, s29, v200
	ds_read_b128 v[60:63], v64
	ds_read_b128 v[162:165], v64 offset:512
	s_waitcnt lgkmcnt(12)
	v_mfma_f32_32x32x16_bf16 v[0:15], v[146:149], v[68:71], v[0:15]
	v_exp_f32_e32 v104, v104
	v_exp_f32_e32 v105, v105
	v_exp_f32_e32 v106, v106
	v_exp_f32_e32 v107, v107
	ds_read_b128 v[68:71], v64 offset:2048
	ds_read_b128 v[166:169], v64 offset:2560
	s_waitcnt lgkmcnt(12)
	v_mfma_f32_32x32x16_bf16 v[16:31], v[146:149], v[72:75], v[16:31]
	v_exp_f32_e32 v108, v108
	v_exp_f32_e32 v109, v109
	v_exp_f32_e32 v110, v110
	v_exp_f32_e32 v111, v111
	ds_read_b128 v[72:75], v64 offset:4096
	ds_read_b128 v[170:173], v64 offset:4608
	s_waitcnt lgkmcnt(12)
	v_mfma_f32_32x32x16_bf16 v[0:15], v[138:141], v[76:79], v[0:15]
	v_exp_f32_e32 v80, v80
	v_exp_f32_e32 v81, v81
	v_exp_f32_e32 v82, v82
	v_exp_f32_e32 v83, v83
	ds_read_b128 v[76:79], v64 offset:6144
	ds_read_b128 v[64:67], v64 offset:6656
	s_waitcnt lgkmcnt(12)
	v_mfma_f32_32x32x16_bf16 v[16:31], v[138:141], v[48:51], v[16:31]
	v_exp_f32_e32 v84, v84
	v_exp_f32_e32 v85, v85
	v_exp_f32_e32 v86, v86
	v_exp_f32_e32 v87, v87
	s_waitcnt lgkmcnt(10)
	v_mfma_f32_32x32x16_bf16 v[0:15], v[130:133], v[52:55], v[0:15]
	v_exp_f32_e32 v88, v88
	v_exp_f32_e32 v89, v89
	v_exp_f32_e32 v90, v90
	v_exp_f32_e32 v91, v91
	s_waitcnt lgkmcnt(8)
	v_mfma_f32_32x32x16_bf16 v[16:31], v[130:133], v[56:59], v[16:31]
	v_exp_f32_e32 v92, v92
	v_exp_f32_e32 v93, v93
	v_exp_f32_e32 v94, v94
	v_exp_f32_e32 v95, v95
	s_waitcnt vmcnt(2) lgkmcnt(0)
	s_barrier
;   #define RESC() do{}while(0)
;   #define ROT() do{sl_prev=sl_cur;sl_cur=sl_next;sl_next=(sl_next==(NSLOT-1)*SLOTB)?0:sl_next+SLOTB;}while(0)
;   #define ENDW(tt) do{ if((tt)+3<NT){WAIT_BAR(2);} else if((tt)+2<NT){WAIT_BAR(1);} else {WAIT_BAR(0);} }while(0)
; template<int THRL> __device__ __forceinline__ void attn_unit(int b,int h,int qb,const bf16*Q,const bf16*__restrict__ K,const bf16*__restrict__ V,bf16*O,float*gssrow,float mref,char*shm){
;     ...
;   for(;t+1<NT;t+=2){
;     STEP(pB0,pB1,pA0,pA1,t,(t+3<NT),(t+1<NT),(t+1<NT));       ENDW(t);   RESC(); ROT();
;     STEP(pA0,pA1,pB0,pB1,t+1,(t+4<NT),(t+2<NT),(t+2<NT));     ENDW(t+1); RESC(); ROT();
	s_add_i32 s20, s29, 0x2000
	s_cmpk_lg_i32 s29, 0x4000
	s_cselect_b32 s20, s20, 0
	v_add_u32_e32 v175, s21, v199
	ds_read_b64_tr_b16 v[190:191], v175 offset:24576
	ds_read_b64_tr_b16 v[192:193], v175 offset:25088
	v_add_f32_e32 v48, v96, v97
	v_add_f32_e32 v48, v98, v48
	v_add_f32_e32 v48, v99, v48
	v_add_f32_e32 v48, v100, v48
	v_add_f32_e32 v48, v101, v48
	v_cvt_pk_bf16_f32 v154, v96, v97
	v_cvt_pk_bf16_f32 v155, v98, v99
	s_waitcnt lgkmcnt(9)
	v_mfma_f32_32x32x16_bf16 v[112:127], v[60:63], v[158:161], v[32:47]
	ds_read_b64_tr_b16 v[96:97], v175 offset:28672
	ds_read_b64_tr_b16 v[98:99], v175 offset:29184
	v_add_f32_e32 v48, v102, v48
	v_add_f32_e32 v48, v103, v48
	v_add_f32_e32 v48, v104, v48
	v_add_f32_e32 v130, v105, v48
	s_waitcnt lgkmcnt(10)
	v_mfma_f32_32x32x16_bf16 v[48:63], v[162:165], v[158:161], v[32:47]
	v_cvt_pk_bf16_f32 v156, v100, v101
	v_cvt_pk_bf16_f32 v157, v102, v103
	ds_read_b64_tr_b16 v[100:101], v175 offset:25600
	ds_read_b64_tr_b16 v[102:103], v175 offset:26112
	s_waitcnt lgkmcnt(11)
	v_mfma_f32_32x32x16_bf16 v[112:127], v[68:71], v[150:153], v[112:127]
	v_add_f32_e32 v68, v106, v130
	v_add_f32_e32 v68, v107, v68
	v_add_f32_e32 v68, v108, v68
	v_add_f32_e32 v130, v109, v68
	v_cvt_pk_bf16_f32 v146, v104, v105
	v_cvt_pk_bf16_f32 v147, v106, v107
	ds_read_b64_tr_b16 v[68:69], v175 offset:29696
	ds_read_b64_tr_b16 v[70:71], v175 offset:30208
	s_waitcnt lgkmcnt(12)
	v_mfma_f32_32x32x16_bf16 v[48:63], v[166:169], v[150:153], v[48:63]
	v_add_f32_e32 v104, v110, v130
	v_add_f32_e32 v104, v111, v104
	v_add_f32_e32 v104, v80, v104
	v_add_f32_e32 v130, v81, v104
	v_cvt_pk_bf16_f32 v148, v108, v109
	v_cvt_pk_bf16_f32 v149, v110, v111
	ds_read_b64_tr_b16 v[104:105], v175 offset:26624
	ds_read_b64_tr_b16 v[106:107], v175 offset:27136
	s_waitcnt lgkmcnt(13)
	v_mfma_f32_32x32x16_bf16 v[112:127], v[72:75], v[142:145], v[112:127]
	v_add_f32_e32 v72, v82, v130
	v_add_f32_e32 v72, v83, v72
	v_add_f32_e32 v72, v84, v72
	v_add_f32_e32 v108, v85, v72
	v_cvt_pk_bf16_f32 v138, v80, v81
	v_cvt_pk_bf16_f32 v139, v82, v83
	ds_read_b64_tr_b16 v[72:73], v175 offset:30720
	ds_read_b64_tr_b16 v[74:75], v175 offset:31232
	s_waitcnt lgkmcnt(14)
	v_mfma_f32_32x32x16_bf16 v[48:63], v[170:173], v[142:145], v[48:63]
	v_add_f32_e32 v80, v86, v108
	v_add_f32_e32 v80, v87, v80
	v_add_f32_e32 v80, v88, v80
	v_add_f32_e32 v80, v89, v80
	v_cvt_pk_bf16_f32 v140, v84, v85
	v_cvt_pk_bf16_f32 v141, v86, v87
	ds_read_b64_tr_b16 v[84:85], v175 offset:27648
	ds_read_b64_tr_b16 v[86:87], v175 offset:28160
	s_waitcnt lgkmcnt(14)
	v_mfma_f32_32x32x16_bf16 v[112:127], v[76:79], v[134:137], v[112:127]
	v_add_f32_e32 v76, v90, v80
	v_add_f32_e32 v76, v91, v76
	v_add_f32_e32 v76, v92, v76
	v_add_f32_e32 v80, v93, v76
	v_cvt_pk_bf16_f32 v130, v88, v89
	v_cvt_pk_bf16_f32 v131, v90, v91
	ds_read_b64_tr_b16 v[76:77], v175 offset:31744
	ds_read_b64_tr_b16 v[78:79], v175 offset:32256
	v_mfma_f32_32x32x16_bf16 v[48:63], v[64:67], v[134:137], v[48:63]
	v_add_f32_e32 v64, v94, v80
	v_add_f32_e32 v64, v95, v64
	v_add_f32_e32 v64, 0, v64
	v_cvt_pk_bf16_f32 v132, v92, v93
	v_cvt_pk_bf16_f32 v133, v94, v95
	s_mov_b64 s[48:49], 0x3fc000
	v_add_f32_e32 v174, v174, v64
	s_add_i32 s5, s29, s5
	v_lshl_add_u64 v[64:65], v[188:189], 0, s[48:49]
	s_mov_b32 s21, m0
	s_mov_b32 m0, s5
	s_nop 0
	global_load_lds_dwordx4 v[64:65], off
	s_mov_b32 m0, s21
	s_mov_b64 s[30:31], 0x3f4000
	s_add_i32 s5, s20, s4
	v_lshl_add_u64 v[64:65], v[186:187], 0, s[30:31]
	s_mov_b32 s21, m0
	s_mov_b32 m0, s5
	s_nop 0
	global_load_lds_dwordx4 v[64:65], off
	s_mov_b32 m0, s21
	s_waitcnt lgkmcnt(14)
	v_mfma_f32_32x32x16_bf16 v[0:15], v[154:157], v[190:193], v[0:15]
	v_exp_f32_e32 v112, v112
	v_exp_f32_e32 v113, v113
	v_exp_f32_e32 v114, v114
	v_exp_f32_e32 v115, v115
	s_waitcnt lgkmcnt(12)
	v_mfma_f32_32x32x16_bf16 v[16:31], v[154:157], v[96:99], v[16:31]
	v_exp_f32_e32 v116, v116
	v_exp_f32_e32 v117, v117
	v_exp_f32_e32 v118, v118
	v_exp_f32_e32 v119, v119
	v_add_u32_e32 v80, s20, v200
	ds_read_b128 v[64:67], v80
	ds_read_b128 v[88:91], v80 offset:512
	s_waitcnt lgkmcnt(12)
	v_mfma_f32_32x32x16_bf16 v[0:15], v[146:149], v[100:103], v[0:15]
	v_exp_f32_e32 v120, v120
	v_exp_f32_e32 v121, v121
	v_exp_f32_e32 v122, v122
	v_exp_f32_e32 v123, v123
	ds_read_b128 v[92:95], v80 offset:2048
	ds_read_b128 v[162:165], v80 offset:2560
	s_waitcnt lgkmcnt(12)
	v_mfma_f32_32x32x16_bf16 v[16:31], v[146:149], v[68:71], v[16:31]
	v_exp_f32_e32 v124, v124
	v_exp_f32_e32 v125, v125
	v_exp_f32_e32 v126, v126
	v_exp_f32_e32 v127, v127
	ds_read_b128 v[166:169], v80 offset:4096
	ds_read_b128 v[170:173], v80 offset:4608
	s_waitcnt lgkmcnt(12)
	v_mfma_f32_32x32x16_bf16 v[0:15], v[138:141], v[104:107], v[0:15]
	v_exp_f32_e32 v48, v48
	v_exp_f32_e32 v49, v49
	v_exp_f32_e32 v50, v50
	v_exp_f32_e32 v51, v51
	ds_read_b128 v[188:191], v80 offset:6144
	ds_read_b128 v[80:83], v80 offset:6656
	s_waitcnt lgkmcnt(12)
	v_mfma_f32_32x32x16_bf16 v[16:31], v[138:141], v[72:75], v[16:31]
	v_exp_f32_e32 v52, v52
	v_exp_f32_e32 v53, v53
	v_exp_f32_e32 v54, v54
	v_exp_f32_e32 v55, v55
	s_waitcnt lgkmcnt(10)
	v_mfma_f32_32x32x16_bf16 v[0:15], v[130:133], v[84:87], v[0:15]
	v_exp_f32_e32 v56, v56
	v_exp_f32_e32 v57, v57
	v_exp_f32_e32 v58, v58
	v_exp_f32_e32 v59, v59
	s_waitcnt lgkmcnt(8)
	v_mfma_f32_32x32x16_bf16 v[16:31], v[130:133], v[76:79], v[16:31]
	v_exp_f32_e32 v60, v60
	v_exp_f32_e32 v61, v61
	v_exp_f32_e32 v62, v62
	v_exp_f32_e32 v63, v63
	s_waitcnt vmcnt(2) lgkmcnt(0)
	s_barrier
;   #define RESC() do{}while(0)
;   #define ROT() do{sl_prev=sl_cur;sl_cur=sl_next;sl_next=(sl_next==(NSLOT-1)*SLOTB)?0:sl_next+SLOTB;}while(0)
;   #define ENDW(tt) do{ if((tt)+3<NT){WAIT_BAR(2);} else if((tt)+2<NT){WAIT_BAR(1);} else {WAIT_BAR(0);} }while(0)
; template<int THRL> __device__ __forceinline__ void attn_unit(int b,int h,int qb,const bf16*Q,const bf16*__restrict__ K,const bf16*__restrict__ V,bf16*O,float*gssrow,float mref,char*shm){
;     ...
;   for(;t+1<NT;t+=2){
;     STEP(pB0,pB1,pA0,pA1,t,(t+3<NT),(t+1<NT),(t+1<NT));       ENDW(t);   RESC(); ROT();
;     STEP(pA0,pA1,pB0,pB1,t+1,(t+4<NT),(t+2<NT),(t+2<NT));     ENDW(t+1); RESC(); ROT();
	s_add_i32 s5, s20, 0x2000
	s_cmpk_lg_i32 s20, 0x4000
	s_cselect_b32 s21, s5, 0
	v_add_u32_e32 v175, s29, v199
	ds_read_b64_tr_b16 v[84:85], v175 offset:24576
	ds_read_b64_tr_b16 v[86:87], v175 offset:25088
	v_add_f32_e32 v68, v112, v113
	v_add_f32_e32 v68, v114, v68
	v_add_f32_e32 v68, v115, v68
	v_add_f32_e32 v68, v116, v68
	v_add_f32_e32 v68, v117, v68
	v_cvt_pk_bf16_f32 v154, v112, v113
	v_cvt_pk_bf16_f32 v155, v114, v115
	s_waitcnt lgkmcnt(9)
	v_mfma_f32_32x32x16_bf16 v[96:111], v[64:67], v[158:161], v[32:47]
	ds_read_b64_tr_b16 v[112:113], v175 offset:28672
	ds_read_b64_tr_b16 v[114:115], v175 offset:29184
	v_add_f32_e32 v64, v118, v68
	v_add_f32_e32 v64, v119, v64
	v_add_f32_e32 v64, v120, v64
	v_add_f32_e32 v130, v121, v64
	v_cvt_pk_bf16_f32 v156, v116, v117
	v_cvt_pk_bf16_f32 v157, v118, v119
	s_waitcnt lgkmcnt(10)
	v_mfma_f32_32x32x16_bf16 v[64:79], v[88:91], v[158:161], v[32:47]
	ds_read_b64_tr_b16 v[88:89], v175 offset:25600
	ds_read_b64_tr_b16 v[90:91], v175 offset:26112
	s_waitcnt lgkmcnt(11)
	v_mfma_f32_32x32x16_bf16 v[96:111], v[92:95], v[150:153], v[96:111]
	v_add_f32_e32 v92, v122, v130
	v_add_f32_e32 v92, v123, v92
	v_add_f32_e32 v92, v124, v92
	v_add_f32_e32 v116, v125, v92
	v_cvt_pk_bf16_f32 v146, v120, v121
	v_cvt_pk_bf16_f32 v147, v122, v123
	ds_read_b64_tr_b16 v[92:93], v175 offset:29696
	ds_read_b64_tr_b16 v[94:95], v175 offset:30208
	v_add_f32_e32 v116, v126, v116
	v_add_f32_e32 v116, v127, v116
	v_add_f32_e32 v116, v48, v116
	v_add_f32_e32 v120, v49, v116
	v_cvt_pk_bf16_f32 v148, v124, v125
	v_cvt_pk_bf16_f32 v149, v126, v127
	s_waitcnt lgkmcnt(12)
	v_mfma_f32_32x32x16_bf16 v[64:79], v[162:165], v[150:153], v[64:79]
	ds_read_b64_tr_b16 v[116:117], v175 offset:26624
	ds_read_b64_tr_b16 v[118:119], v175 offset:27136
	v_add_f32_e32 v120, v50, v120
	v_add_f32_e32 v120, v51, v120
	v_add_f32_e32 v120, v52, v120
	v_add_f32_e32 v120, v53, v120
	v_cvt_pk_bf16_f32 v138, v48, v49
	v_cvt_pk_bf16_f32 v139, v50, v51
	s_waitcnt lgkmcnt(13)
	v_mfma_f32_32x32x16_bf16 v[96:111], v[166:169], v[142:145], v[96:111]
	ds_read_b64_tr_b16 v[48:49], v175 offset:30720
	ds_read_b64_tr_b16 v[50:51], v175 offset:31232
	v_add_f32_e32 v120, v54, v120
	v_add_f32_e32 v120, v55, v120
	v_add_f32_e32 v120, v56, v120
	v_add_f32_e32 v120, v57, v120
	v_cvt_pk_bf16_f32 v140, v52, v53
	v_cvt_pk_bf16_f32 v141, v54, v55
	s_waitcnt lgkmcnt(14)
	v_mfma_f32_32x32x16_bf16 v[64:79], v[170:173], v[142:145], v[64:79]
	ds_read_b64_tr_b16 v[52:53], v175 offset:27648
	ds_read_b64_tr_b16 v[54:55], v175 offset:28160
	v_add_f32_e32 v120, v58, v120
	v_add_f32_e32 v120, v59, v120
	v_add_f32_e32 v120, v60, v120
	v_add_f32_e32 v120, v61, v120
	v_cvt_pk_bf16_f32 v130, v56, v57
	v_cvt_pk_bf16_f32 v131, v58, v59
	s_waitcnt lgkmcnt(14)
	v_mfma_f32_32x32x16_bf16 v[96:111], v[188:191], v[134:137], v[96:111]
	ds_read_b64_tr_b16 v[56:57], v175 offset:31744
	ds_read_b64_tr_b16 v[58:59], v175 offset:32256
	v_mfma_f32_32x32x16_bf16 v[64:79], v[80:83], v[134:137], v[64:79]
	v_add_f32_e32 v80, v62, v120
	v_add_f32_e32 v80, v63, v80
	v_add_f32_e32 v80, 0, v80
	v_cvt_pk_bf16_f32 v132, v60, v61
	v_cvt_pk_bf16_f32 v133, v62, v63
	v_lshl_add_u64 v[60:61], v[186:187], 0, s[12:13]
	s_add_i32 s5, s21, s4
	s_mov_b32 s29, m0
	s_mov_b32 m0, s5
	s_nop 0
	global_load_lds_dwordx4 v[60:61], off
	s_mov_b32 m0, s29
	v_add_f32_e32 v174, v174, v80
	s_waitcnt lgkmcnt(14)
	v_mfma_f32_32x32x16_bf16 v[0:15], v[154:157], v[84:87], v[0:15]
	v_exp_f32_e32 v96, v96
	v_exp_f32_e32 v97, v97
	v_exp_f32_e32 v98, v98
	v_exp_f32_e32 v99, v99
	s_waitcnt lgkmcnt(12)
	v_mfma_f32_32x32x16_bf16 v[16:31], v[154:157], v[112:115], v[16:31]
	v_exp_f32_e32 v100, v100
	v_exp_f32_e32 v101, v101
	v_exp_f32_e32 v102, v102
	v_exp_f32_e32 v103, v103
	v_add_u32_e32 v80, s21, v200
	ds_read_b128 v[60:63], v80
	ds_read_b128 v[120:123], v80 offset:512
	s_waitcnt lgkmcnt(12)
	v_mfma_f32_32x32x16_bf16 v[0:15], v[146:149], v[88:91], v[0:15]
	v_exp_f32_e32 v104, v104
	v_exp_f32_e32 v105, v105
	v_exp_f32_e32 v106, v106
	v_exp_f32_e32 v107, v107
	ds_read_b128 v[124:127], v80 offset:2048
	ds_read_b128 v[162:165], v80 offset:2560
	s_waitcnt lgkmcnt(12)
	v_mfma_f32_32x32x16_bf16 v[16:31], v[146:149], v[92:95], v[16:31]
	v_exp_f32_e32 v108, v108
	v_exp_f32_e32 v109, v109
	v_exp_f32_e32 v110, v110
	v_exp_f32_e32 v111, v111
	ds_read_b128 v[166:169], v80 offset:4096
	ds_read_b128 v[170:173], v80 offset:4608
	s_waitcnt lgkmcnt(12)
	v_mfma_f32_32x32x16_bf16 v[0:15], v[138:141], v[116:119], v[0:15]
	v_exp_f32_e32 v64, v64
	v_exp_f32_e32 v65, v65
	v_exp_f32_e32 v66, v66
	v_exp_f32_e32 v67, v67
	ds_read_b128 v[116:119], v80 offset:6144
	ds_read_b128 v[112:115], v80 offset:6656
	s_waitcnt lgkmcnt(12)
	v_mfma_f32_32x32x16_bf16 v[16:31], v[138:141], v[48:51], v[16:31]
	v_exp_f32_e32 v68, v68
	v_exp_f32_e32 v69, v69
	v_exp_f32_e32 v70, v70
	v_exp_f32_e32 v71, v71
	s_waitcnt lgkmcnt(10)
	v_mfma_f32_32x32x16_bf16 v[0:15], v[130:133], v[52:55], v[0:15]
	v_exp_f32_e32 v72, v72
	v_exp_f32_e32 v73, v73
	v_exp_f32_e32 v74, v74
	v_exp_f32_e32 v75, v75
	s_waitcnt lgkmcnt(8)
	v_mfma_f32_32x32x16_bf16 v[16:31], v[130:133], v[56:59], v[16:31]
	v_exp_f32_e32 v76, v76
	v_exp_f32_e32 v77, v77
	v_exp_f32_e32 v78, v78
	v_exp_f32_e32 v79, v79
	s_waitcnt vmcnt(1) lgkmcnt(0)
	s_barrier
	s_add_i32 s5, s21, 0x2000
	s_cmpk_lg_i32 s21, 0x4000
	s_cselect_b32 s5, s5, 0
	v_add_u32_e32 v175, s20, v199
	ds_read_b64_tr_b16 v[188:189], v175 offset:24576
	ds_read_b64_tr_b16 v[190:191], v175 offset:25088
	v_add_f32_e32 v48, v96, v97
	v_add_f32_e32 v48, v98, v48
	v_add_f32_e32 v48, v99, v48
	v_add_f32_e32 v48, v100, v48
	v_add_f32_e32 v48, v101, v48
	v_cvt_pk_bf16_f32 v154, v96, v97
	v_cvt_pk_bf16_f32 v155, v98, v99
	s_waitcnt lgkmcnt(9)
	v_mfma_f32_32x32x16_bf16 v[80:95], v[60:63], v[158:161], v[32:47]
	ds_read_b64_tr_b16 v[96:97], v175 offset:28672
	ds_read_b64_tr_b16 v[98:99], v175 offset:29184
	v_add_f32_e32 v48, v102, v48
	v_add_f32_e32 v48, v103, v48
	v_add_f32_e32 v48, v104, v48
	v_add_f32_e32 v130, v105, v48
	s_waitcnt lgkmcnt(10)
	v_mfma_f32_32x32x16_bf16 v[48:63], v[120:123], v[158:161], v[32:47]
	v_cvt_pk_bf16_f32 v156, v100, v101
	v_cvt_pk_bf16_f32 v157, v102, v103
	ds_read_b64_tr_b16 v[120:121], v175 offset:25600
	ds_read_b64_tr_b16 v[122:123], v175 offset:26112
	v_add_f32_e32 v100, v106, v130
	v_add_f32_e32 v100, v107, v100
	v_add_f32_e32 v100, v108, v100
	v_add_f32_e32 v100, v109, v100
	v_cvt_pk_bf16_f32 v146, v104, v105
	v_cvt_pk_bf16_f32 v147, v106, v107
	s_waitcnt lgkmcnt(11)
	v_mfma_f32_32x32x16_bf16 v[80:95], v[124:127], v[150:153], v[80:95]
	ds_read_b64_tr_b16 v[102:103], v175 offset:29696
	ds_read_b64_tr_b16 v[104:105], v175 offset:30208
	s_waitcnt lgkmcnt(12)
	v_mfma_f32_32x32x16_bf16 v[48:63], v[162:165], v[150:153], v[48:63]
	v_add_f32_e32 v100, v110, v100
	v_add_f32_e32 v100, v111, v100
	v_add_f32_e32 v100, v64, v100
	v_add_f32_e32 v100, v65, v100
	v_cvt_pk_bf16_f32 v148, v108, v109
	v_cvt_pk_bf16_f32 v149, v110, v111
	ds_read_b64_tr_b16 v[106:107], v175 offset:26624
	ds_read_b64_tr_b16 v[108:109], v175 offset:27136
	v_add_f32_e32 v100, v66, v100
	v_add_f32_e32 v100, v67, v100
	v_add_f32_e32 v100, v68, v100
	v_add_f32_e32 v100, v69, v100
	v_cvt_pk_bf16_f32 v138, v64, v65
	v_cvt_pk_bf16_f32 v139, v66, v67
	s_waitcnt lgkmcnt(13)
	v_mfma_f32_32x32x16_bf16 v[80:95], v[166:169], v[142:145], v[80:95]
	ds_read_b64_tr_b16 v[64:65], v175 offset:30720
	ds_read_b64_tr_b16 v[66:67], v175 offset:31232
	s_waitcnt lgkmcnt(14)
	v_mfma_f32_32x32x16_bf16 v[48:63], v[170:173], v[142:145], v[48:63]
	v_add_f32_e32 v100, v70, v100
	v_add_f32_e32 v100, v71, v100
	v_add_f32_e32 v100, v72, v100
	v_add_f32_e32 v100, v73, v100
	v_cvt_pk_bf16_f32 v140, v68, v69
	v_cvt_pk_bf16_f32 v141, v70, v71
	ds_read_b64_tr_b16 v[68:69], v175 offset:27648
	ds_read_b64_tr_b16 v[70:71], v175 offset:28160
	v_add_f32_e32 v100, v74, v100
	v_add_f32_e32 v100, v75, v100
	v_add_f32_e32 v100, v76, v100
	v_add_f32_e32 v100, v77, v100
	v_cvt_pk_bf16_f32 v130, v72, v73
	v_cvt_pk_bf16_f32 v131, v74, v75
	s_waitcnt lgkmcnt(14)
	v_mfma_f32_32x32x16_bf16 v[80:95], v[116:119], v[134:137], v[80:95]
	ds_read_b64_tr_b16 v[72:73], v175 offset:31744
	ds_read_b64_tr_b16 v[74:75], v175 offset:32256
	v_mfma_f32_32x32x16_bf16 v[48:63], v[112:115], v[134:137], v[48:63]
	v_add_f32_e32 v100, v78, v100
	v_add_f32_e32 v100, v79, v100
	v_add_f32_e32 v100, 0, v100
	v_cvt_pk_bf16_f32 v132, v76, v77
	v_cvt_pk_bf16_f32 v133, v78, v79
	s_add_i32 s4, s5, s4
	v_lshl_add_u64 v[76:77], v[186:187], 0, s[48:49]
	s_mov_b32 s20, m0
	s_mov_b32 m0, s4
	s_nop 0
	global_load_lds_dwordx4 v[76:77], off
	s_mov_b32 m0, s20
	v_add_f32_e32 v100, v174, v100
	s_waitcnt lgkmcnt(14)
	v_mfma_f32_32x32x16_bf16 v[0:15], v[154:157], v[188:191], v[0:15]
	v_exp_f32_e32 v80, v80
	v_exp_f32_e32 v81, v81
	v_exp_f32_e32 v82, v82
	v_exp_f32_e32 v83, v83
	s_waitcnt lgkmcnt(12)
	v_mfma_f32_32x32x16_bf16 v[16:31], v[154:157], v[96:99], v[16:31]
	v_exp_f32_e32 v84, v84
	v_exp_f32_e32 v85, v85
	v_exp_f32_e32 v86, v86
	v_exp_f32_e32 v87, v87
	v_add_u32_e32 v76, s5, v200
	ds_read_b128 v[110:113], v76
	ds_read_b128 v[114:117], v76 offset:512
	s_waitcnt lgkmcnt(12)
	v_mfma_f32_32x32x16_bf16 v[0:15], v[146:149], v[120:123], v[0:15]
	v_exp_f32_e32 v88, v88
	v_exp_f32_e32 v89, v89
	v_exp_f32_e32 v90, v90
	v_exp_f32_e32 v91, v91
	ds_read_b128 v[118:121], v76 offset:2048
	ds_read_b128 v[122:125], v76 offset:2560
	s_waitcnt lgkmcnt(12)
	v_mfma_f32_32x32x16_bf16 v[16:31], v[146:149], v[102:105], v[16:31]
	v_exp_f32_e32 v92, v92
	v_exp_f32_e32 v93, v93
	v_exp_f32_e32 v94, v94
	v_exp_f32_e32 v95, v95
	ds_read_b128 v[102:105], v76 offset:4096
	ds_read_b128 v[162:165], v76 offset:4608
	s_waitcnt lgkmcnt(12)
	v_mfma_f32_32x32x16_bf16 v[0:15], v[138:141], v[106:109], v[0:15]
	v_exp_f32_e32 v48, v48
	v_exp_f32_e32 v49, v49
	v_exp_f32_e32 v50, v50
	v_exp_f32_e32 v51, v51
	ds_read_b128 v[106:109], v76 offset:6144
	ds_read_b128 v[96:99], v76 offset:6656
	s_waitcnt lgkmcnt(12)
	v_mfma_f32_32x32x16_bf16 v[16:31], v[138:141], v[64:67], v[16:31]
	v_exp_f32_e32 v52, v52
	v_exp_f32_e32 v53, v53
	v_exp_f32_e32 v54, v54
	v_exp_f32_e32 v55, v55
	s_waitcnt lgkmcnt(10)
	v_mfma_f32_32x32x16_bf16 v[0:15], v[130:133], v[68:71], v[0:15]
	v_exp_f32_e32 v56, v56
	v_exp_f32_e32 v57, v57
	v_exp_f32_e32 v58, v58
	v_exp_f32_e32 v59, v59
	s_waitcnt lgkmcnt(8)
	v_mfma_f32_32x32x16_bf16 v[16:31], v[130:133], v[72:75], v[16:31]
	v_exp_f32_e32 v60, v60
	v_exp_f32_e32 v61, v61
	v_exp_f32_e32 v62, v62
	v_exp_f32_e32 v63, v63
	s_waitcnt vmcnt(0) lgkmcnt(0)
	s_barrier
; #define SBAR() __builtin_amdgcn_sched_barrier(0)
; #define WAIT_BAR(N) asm volatile("s_waitcnt vmcnt(" #N ") lgkmcnt(0)\n\ts_barrier":::"memory")
;   #define RESC() do{}while(0)
;   #define ROT() do{sl_prev=sl_cur;sl_cur=sl_next;sl_next=(sl_next==(NSLOT-1)*SLOTB)?0:sl_next+SLOTB;}while(0)
;   #define PKW(P,B) cvtpk_s(P[B],P[B+1])
;   #define ENDW(tt) do{ if((tt)+3<NT){WAIT_BAR(2);} else if((tt)+2<NT){WAIT_BAR(1);} else {WAIT_BAR(0);} }while(0)
; template<int THRL> __device__ __forceinline__ void attn_unit(int b,int h,int qb,const bf16*Q,const bf16*__restrict__ K,const bf16*__restrict__ V,bf16*O,float*gssrow,float mref,char*shm){
;     ...
;   if(wid>=4)__builtin_amdgcn_s_setprio(1);
;   int t=1;
;     ...
;   for(;t+5<NT;t+=2){
;     STEP(pB0,pB1,pA0,pA1,t,true,true,true);     WAIT_BAR(2); RESC(); ROT();
;     STEP(pA0,pA1,pB0,pB1,t+1,true,true,true);   WAIT_BAR(2); RESC(); ROT();
;   }
;     ...
;   for(;t+1<NT;t+=2){
;     STEP(pB0,pB1,pA0,pA1,t,(t+3<NT),(t+1<NT),(t+1<NT));       ENDW(t);   RESC(); ROT();
;     STEP(pA0,pA1,pB0,pB1,t+1,(t+4<NT),(t+2<NT),(t+2<NT));     ENDW(t+1); RESC(); ROT();
;   }
;   STEP(pB0,pB1,pA0,pA1,NT-1,false,false,false); RESC();
;   { float sacc=pB0[0]+pB0[1]; _Pragma("unroll") for(int r=2;r<16;++r)sacc+=pB0[r]; _Pragma("unroll") for(int r=0;r<16;++r)sacc+=pB1[r]; l_reg+=sacc;
;     pw0=(u32x4){PKW(pB0,0),PKW(pB0,2),PKW(pB0,4),PKW(pB0,6)};pw1=(u32x4){PKW(pB0,8),PKW(pB0,10),PKW(pB0,12),PKW(pB0,14)};pw2=(u32x4){PKW(pB1,0),PKW(pB1,2),PKW(pB1,4),PKW(pB1,6)};pw3=(u32x4){PKW(pB1,8),PKW(pB1,10),PKW(pB1,12),PKW(pB1,14)};
;     SBAR(); pv(o,vb0+sl_cur,PAF(0),PAF(1),PAF(2),PAF(3)); }
	v_add_u32_e32 v101, s21, v199
	ds_read_b64_tr_b16 v[166:167], v101 offset:24576
	ds_read_b64_tr_b16 v[168:169], v101 offset:25088
	v_add_f32_e32 v64, v80, v81
	v_add_f32_e32 v64, v82, v64
	v_add_f32_e32 v64, v83, v64
	v_add_f32_e32 v64, v84, v64
	v_add_f32_e32 v126, v85, v64
	v_cvt_pk_bf16_f32 v154, v80, v81
	v_cvt_pk_bf16_f32 v155, v82, v83
	s_waitcnt lgkmcnt(9)
	v_mfma_f32_32x32x16_bf16 v[64:79], v[110:113], v[158:161], v[32:47]
	ds_read_b64_tr_b16 v[80:81], v101 offset:28672
	ds_read_b64_tr_b16 v[82:83], v101 offset:29184
	s_waitcnt lgkmcnt(10)
	v_mfma_f32_32x32x16_bf16 v[32:47], v[114:117], v[158:161], v[32:47]
	v_add_f32_e32 v110, v86, v126
	v_add_f32_e32 v110, v87, v110
	v_add_f32_e32 v110, v88, v110
	v_add_f32_e32 v110, v89, v110
	v_cvt_pk_bf16_f32 v156, v84, v85
	v_cvt_pk_bf16_f32 v157, v86, v87
	ds_read_b64_tr_b16 v[84:85], v101 offset:25600
	ds_read_b64_tr_b16 v[86:87], v101 offset:26112
	v_add_f32_e32 v110, v90, v110
	v_add_f32_e32 v110, v91, v110
	v_add_f32_e32 v110, v92, v110
	v_add_f32_e32 v110, v93, v110
	v_cvt_pk_bf16_f32 v146, v88, v89
	v_cvt_pk_bf16_f32 v147, v90, v91
	s_waitcnt lgkmcnt(11)
	v_mfma_f32_32x32x16_bf16 v[64:79], v[118:121], v[150:153], v[64:79]
	ds_read_b64_tr_b16 v[88:89], v101 offset:29696
	ds_read_b64_tr_b16 v[90:91], v101 offset:30208
	s_waitcnt lgkmcnt(12)
	v_mfma_f32_32x32x16_bf16 v[32:47], v[122:125], v[150:153], v[32:47]
	v_add_f32_e32 v110, v94, v110
	v_add_f32_e32 v110, v95, v110
	v_add_f32_e32 v110, v48, v110
	v_add_f32_e32 v110, v49, v110
	v_cvt_pk_bf16_f32 v148, v92, v93
	v_cvt_pk_bf16_f32 v149, v94, v95
	ds_read_b64_tr_b16 v[92:93], v101 offset:26624
	ds_read_b64_tr_b16 v[94:95], v101 offset:27136
	s_waitcnt lgkmcnt(13)
	v_mfma_f32_32x32x16_bf16 v[64:79], v[102:105], v[142:145], v[64:79]
	v_add_f32_e32 v102, v50, v110
	v_add_f32_e32 v102, v51, v102
	v_add_f32_e32 v102, v52, v102
	v_add_f32_e32 v102, v53, v102
	v_cvt_pk_bf16_f32 v138, v48, v49
	v_cvt_pk_bf16_f32 v139, v50, v51
	ds_read_b64_tr_b16 v[48:49], v101 offset:30720
	ds_read_b64_tr_b16 v[50:51], v101 offset:31232
	s_waitcnt lgkmcnt(14)
	v_mfma_f32_32x32x16_bf16 v[32:47], v[162:165], v[142:145], v[32:47]
	v_add_f32_e32 v102, v54, v102
	v_add_f32_e32 v102, v55, v102
	v_add_f32_e32 v102, v56, v102
	v_add_f32_e32 v102, v57, v102
	v_cvt_pk_bf16_f32 v140, v52, v53
	v_cvt_pk_bf16_f32 v141, v54, v55
	ds_read_b64_tr_b16 v[52:53], v101 offset:27648
	ds_read_b64_tr_b16 v[54:55], v101 offset:28160
	v_add_f32_e32 v102, v58, v102
	v_add_f32_e32 v102, v59, v102
	v_add_f32_e32 v102, v60, v102
	v_add_f32_e32 v102, v61, v102
	v_cvt_pk_bf16_f32 v130, v56, v57
	v_cvt_pk_bf16_f32 v131, v58, v59
	s_waitcnt lgkmcnt(14)
	v_mfma_f32_32x32x16_bf16 v[64:79], v[106:109], v[134:137], v[64:79]
	ds_read_b64_tr_b16 v[56:57], v101 offset:31744
	ds_read_b64_tr_b16 v[58:59], v101 offset:32256
	v_mfma_f32_32x32x16_bf16 v[32:47], v[96:99], v[134:137], v[32:47]
	v_add_f32_e32 v96, v62, v102
	v_add_f32_e32 v96, v63, v96
	v_add_f32_e32 v96, 0, v96
	v_cvt_pk_bf16_f32 v132, v60, v61
	v_cvt_pk_bf16_f32 v133, v62, v63
	s_waitcnt lgkmcnt(14)
	v_mfma_f32_32x32x16_bf16 v[0:15], v[154:157], v[166:169], v[0:15]
	s_nop 1
	v_exp_f32_e32 v64, v64
	v_exp_f32_e32 v65, v65
	v_exp_f32_e32 v66, v66
	v_exp_f32_e32 v67, v67
	s_waitcnt lgkmcnt(12)
	v_mfma_f32_32x32x16_bf16 v[16:31], v[154:157], v[80:83], v[16:31]
	v_exp_f32_e32 v68, v68
	v_exp_f32_e32 v69, v69
	v_exp_f32_e32 v70, v70
	v_exp_f32_e32 v71, v71
	s_waitcnt lgkmcnt(10)
	v_mfma_f32_32x32x16_bf16 v[0:15], v[146:149], v[84:87], v[0:15]
	v_exp_f32_e32 v72, v72
	v_exp_f32_e32 v73, v73
	v_exp_f32_e32 v74, v74
	v_exp_f32_e32 v75, v75
	s_waitcnt lgkmcnt(8)
	v_mfma_f32_32x32x16_bf16 v[16:31], v[146:149], v[88:91], v[16:31]
	v_exp_f32_e32 v76, v76
	v_exp_f32_e32 v77, v77
	v_exp_f32_e32 v78, v78
	v_exp_f32_e32 v79, v79
	s_waitcnt lgkmcnt(6)
	v_mfma_f32_32x32x16_bf16 v[0:15], v[138:141], v[92:95], v[0:15]
	v_exp_f32_e32 v32, v32
	v_exp_f32_e32 v33, v33
	v_exp_f32_e32 v34, v34
	v_exp_f32_e32 v35, v35
	s_waitcnt lgkmcnt(4)
	v_mfma_f32_32x32x16_bf16 v[16:31], v[138:141], v[48:51], v[16:31]
	v_exp_f32_e32 v36, v36
	v_exp_f32_e32 v37, v37
	v_exp_f32_e32 v38, v38
	v_exp_f32_e32 v39, v39
	s_waitcnt lgkmcnt(2)
	v_mfma_f32_32x32x16_bf16 v[0:15], v[130:133], v[52:55], v[0:15]
	v_exp_f32_e32 v40, v40
	v_exp_f32_e32 v41, v41
	v_exp_f32_e32 v42, v42
	v_exp_f32_e32 v43, v43
	s_waitcnt lgkmcnt(0)
	v_mfma_f32_32x32x16_bf16 v[16:31], v[130:133], v[56:59], v[16:31]
	v_exp_f32_e32 v44, v44
	v_exp_f32_e32 v45, v45
	v_exp_f32_e32 v46, v46
	v_exp_f32_e32 v47, v47
	v_add_f32_e32 v48, v64, v65
	v_add_f32_e32 v48, v66, v48
	v_add_f32_e32 v48, v67, v48
	v_add_f32_e32 v48, v68, v48
	v_add_f32_e32 v48, v69, v48
	v_add_f32_e32 v48, v70, v48
	v_add_f32_e32 v48, v71, v48
	v_add_f32_e32 v48, v72, v48
	v_add_f32_e32 v48, v73, v48
	v_add_f32_e32 v48, v74, v48
	v_add_f32_e32 v48, v75, v48
	v_add_f32_e32 v48, v76, v48
	v_add_f32_e32 v48, v77, v48
	v_add_f32_e32 v48, v78, v48
	v_add_f32_e32 v48, v79, v48
	v_add_f32_e32 v48, v32, v48
	v_add_f32_e32 v48, v33, v48
	v_add_f32_e32 v48, v34, v48
	v_add_f32_e32 v48, v35, v48
	v_add_f32_e32 v48, v36, v48
	v_add_f32_e32 v48, v37, v48
	v_add_f32_e32 v48, v38, v48
	v_add_f32_e32 v48, v39, v48
	v_add_f32_e32 v48, v40, v48
	v_add_f32_e32 v48, v41, v48
	v_add_f32_e32 v48, v42, v48
	v_add_f32_e32 v48, v43, v48
	v_add_f32_e32 v48, v44, v48
	v_add_f32_e32 v48, v45, v48
	v_add_f32_e32 v48, v46, v48
	v_add_f32_e32 v48, v47, v48
	v_add_f32_e32 v49, v100, v96
	v_add_f32_e32 v48, v49, v48
	v_cvt_pk_bf16_f32 v32, v32, v33
	v_cvt_pk_bf16_f32 v50, v64, v65
	v_cvt_pk_bf16_f32 v51, v66, v67
	v_cvt_pk_bf16_f32 v52, v68, v69
	v_cvt_pk_bf16_f32 v53, v70, v71
	v_cvt_pk_bf16_f32 v54, v72, v73
	v_cvt_pk_bf16_f32 v55, v74, v75
	v_cvt_pk_bf16_f32 v56, v76, v77
	v_cvt_pk_bf16_f32 v57, v78, v79
	v_cvt_pk_bf16_f32 v33, v34, v35
	v_cvt_pk_bf16_f32 v34, v36, v37
	v_cvt_pk_bf16_f32 v35, v38, v39
	v_cvt_pk_bf16_f32 v36, v40, v41
	v_cvt_pk_bf16_f32 v37, v42, v43
	v_cvt_pk_bf16_f32 v38, v44, v45
	v_cvt_pk_bf16_f32 v39, v46, v47
	v_add3_u32 v49, v128, v198, s5
	ds_read_b64_tr_b16 v[40:41],v49 offset:0
	ds_read_b64_tr_b16 v[42:43],v49 offset:512
	ds_read_b64_tr_b16 v[44:45],v49 offset:1024
	ds_read_b64_tr_b16 v[46:47],v49 offset:1536
	ds_read_b64_tr_b16 v[58:59],v49 offset:2048
	ds_read_b64_tr_b16 v[60:61],v49 offset:2560
	ds_read_b64_tr_b16 v[62:63],v49 offset:3072
	ds_read_b64_tr_b16 v[64:65],v49 offset:3584
	s_waitcnt lgkmcnt(0)
; __device__ __forceinline__ int crow(int r,int hi){return (r&3)+8*(r>>2)+4*hi;}
; #define SBAR() __builtin_amdgcn_sched_barrier(0)
; template<int THRL> __device__ __forceinline__ void attn_unit(int b,int h,int qb,const bf16*Q,const bf16*__restrict__ K,const bf16*__restrict__ V,bf16*O,float*gssrow,float mref,char*shm){
;     ...
;     SBAR(); pv(o,vb0+sl_cur,PAF(0),PAF(1),PAF(2),PAF(3)); }
;     ...
;   __builtin_amdgcn_s_setprio(0);
;   {auto rr=__builtin_amdgcn_permlane32_swap(__float_as_uint(l_reg),__float_as_uint(l_reg),false,false);l_reg=__uint_as_float(rr[0])+__uint_as_float(rr[1]);}
;   if(hi==0)wsf[32+r32]=l_reg;asm volatile("s_waitcnt lgkmcnt(0)":::"memory");
;   float rli[16];
;   #pragma unroll
;   for(int r=0;r<16;++r)rli[r]=__builtin_amdgcn_rcpf(wsf[32+crow(r,hi)]);
;   bf16*Ow=O+(rowbase+q0+wid*QBLK)*OP+h*D;
;   { bf16*stg=(bf16*)(shm+LDS_OST)+wid*2048;
;     #pragma unroll
;     for(int r=0;r<16;++r){const int orow=crow(r,hi);
;       #pragma unroll
;       for(int d0=0;d0<2;++d0)stg[orow*64+d0*32+r32]=__float2bfloat16(o[d0][r]*rli[r]);}
;     asm volatile("s_waitcnt lgkmcnt(0)":::"memory");
;     #pragma unroll
;     for(int i=0;i<4;++i){const int row=i*8+(lane>>3),ch=lane&7; const u32x4 v=*(const u32x4*)(stg+row*64+ch*8); ATTN_STORE16(Ow+(long)row*OP+ch*8,v);
	s_nop 0
	v_mfma_f32_32x32x16_bf16 v[0:15], v[50:53], v[40:43], v[0:15]
	ds_read_b64_tr_b16 v[40:41],v49 offset:4096
	ds_read_b64_tr_b16 v[42:43],v49 offset:4608
	v_mfma_f32_32x32x16_bf16 v[0:15], v[54:57], v[44:47], v[0:15]
	ds_read_b64_tr_b16 v[44:45],v49 offset:5120
	ds_read_b64_tr_b16 v[46:47],v49 offset:5632
	v_mfma_f32_32x32x16_bf16 v[0:15], v[32:35], v[58:61], v[0:15]
	ds_read_b64_tr_b16 v[58:59],v49 offset:6144
	ds_read_b64_tr_b16 v[60:61],v49 offset:6656
	v_mfma_f32_32x32x16_bf16 v[0:15], v[36:39], v[62:65], v[0:15]
	ds_read_b64_tr_b16 v[62:63],v49 offset:7168
	ds_read_b64_tr_b16 v[64:65],v49 offset:7680
	s_waitcnt lgkmcnt(0)
	v_mfma_f32_32x32x16_bf16 v[16:31], v[50:53], v[40:43], v[16:31]
	v_mfma_f32_32x32x16_bf16 v[16:31], v[54:57], v[44:47], v[16:31]
	v_mfma_f32_32x32x16_bf16 v[16:31], v[32:35], v[58:61], v[16:31]
	v_mfma_f32_32x32x16_bf16 v[16:31], v[36:39], v[62:65], v[16:31]
	s_setprio 0
	v_mov_b32_e32 v32, v48
	s_nop 1
	v_permlane32_swap_b32_e32 v48, v32
	v_cmp_gt_u32_e32 vcc, 32, v195
	s_and_saveexec_b64 s[4:5], vcc
	v_add_f32_e32 v32, v48, v32
	v_lshl_add_u32 v33, v196, 2, s15
	ds_write_b32 v33, v32 offset:49280
	s_or_b64 exec, exec, s[4:5]
	s_waitcnt lgkmcnt(0)
	v_lshl_add_u32 v40, v197, 4, s15
	ds_read_b128 v[32:35], v40 offset:49280
	ds_read_b128 v[36:39], v40 offset:49312
	s_lshl_b64 s[4:5], s[46:47], 11
	v_readlane_b32 s12, v253, 63
	s_add_u32 s4, s12, s4
	s_waitcnt lgkmcnt(1)
	v_rcp_f32_e32 v41, v32
	v_readlane_b32 s12, v254, 0
	s_addc_u32 s5, s12, s5
	s_lshl_b32 s14, s14, 12
	v_rcp_f32_e32 v42, v33
	v_rcp_f32_e32 v43, v34
	v_rcp_f32_e32 v44, v35
	s_waitcnt lgkmcnt(0)
	v_rcp_f32_e32 v45, v36
	ds_read_b128 v[32:35], v40 offset:49344
	v_rcp_f32_e32 v46, v37
	v_rcp_f32_e32 v47, v38
	v_rcp_f32_e32 v48, v39
	ds_read_b128 v[36:39], v40 offset:49376
	s_add_i32 s14, s14, 0
	v_lshlrev_b32_e32 v40, 9, v197
	v_lshlrev_b32_e32 v49, 1, v196
	v_mul_f32_e32 v0, v0, v41
	v_add3_u32 v40, s14, v40, v49
	v_cvt_pk_bf16_f32 v0, v0, s0
	ds_write_b16 v40, v0 offset:51200
	v_mul_f32_e32 v0, v16, v41
	v_cvt_pk_bf16_f32 v0, v0, s0
	ds_write_b16 v40, v0 offset:51264
	v_mul_f32_e32 v0, v1, v42
	v_cvt_pk_bf16_f32 v0, v0, s0
	ds_write_b16 v40, v0 offset:51328
	v_mul_f32_e32 v0, v17, v42
	v_cvt_pk_bf16_f32 v0, v0, s0
	ds_write_b16 v40, v0 offset:51392
	v_mul_f32_e32 v0, v2, v43
	v_cvt_pk_bf16_f32 v0, v0, s0
	ds_write_b16 v40, v0 offset:51456
	v_mul_f32_e32 v0, v18, v43
	v_cvt_pk_bf16_f32 v0, v0, s0
	ds_write_b16 v40, v0 offset:51520
	v_mul_f32_e32 v0, v3, v44
	v_cvt_pk_bf16_f32 v0, v0, s0
	ds_write_b16 v40, v0 offset:51584
	v_mul_f32_e32 v0, v19, v44
	v_cvt_pk_bf16_f32 v0, v0, s0
	ds_write_b16 v40, v0 offset:51648
	v_mul_f32_e32 v0, v4, v45
	v_cvt_pk_bf16_f32 v0, v0, s0
	ds_write_b16 v40, v0 offset:52224
	v_mul_f32_e32 v0, v20, v45
	v_cvt_pk_bf16_f32 v0, v0, s0
	ds_write_b16 v40, v0 offset:52288
	v_mul_f32_e32 v0, v5, v46
	v_cvt_pk_bf16_f32 v0, v0, s0
	ds_write_b16 v40, v0 offset:52352
	v_mul_f32_e32 v0, v21, v46
	v_cvt_pk_bf16_f32 v0, v0, s0
	ds_write_b16 v40, v0 offset:52416
	v_mul_f32_e32 v0, v6, v47
	v_cvt_pk_bf16_f32 v0, v0, s0
	ds_write_b16 v40, v0 offset:52480
	v_mul_f32_e32 v0, v22, v47
	v_cvt_pk_bf16_f32 v0, v0, s0
	s_waitcnt lgkmcnt(14)
	v_rcp_f32_e32 v32, v32
	ds_write_b16 v40, v0 offset:52544
	v_mul_f32_e32 v0, v7, v48
	v_cvt_pk_bf16_f32 v0, v0, s0
	ds_write_b16 v40, v0 offset:52608
	v_mul_f32_e32 v0, v23, v48
	v_cvt_pk_bf16_f32 v0, v0, s0
	v_rcp_f32_e32 v33, v33
	ds_write_b16 v40, v0 offset:52672
	v_mul_f32_e32 v0, v8, v32
	v_cvt_pk_bf16_f32 v0, v0, s0
	ds_write_b16 v40, v0 offset:53248
	v_mul_f32_e32 v0, v24, v32
	v_cvt_pk_bf16_f32 v0, v0, s0
	v_rcp_f32_e32 v34, v34
	ds_write_b16 v40, v0 offset:53312
	v_mul_f32_e32 v0, v9, v33
	v_cvt_pk_bf16_f32 v0, v0, s0
	ds_write_b16 v40, v0 offset:53376
	v_mul_f32_e32 v0, v25, v33
	v_cvt_pk_bf16_f32 v0, v0, s0
	v_rcp_f32_e32 v35, v35
	ds_write_b16 v40, v0 offset:53440
	v_mul_f32_e32 v0, v10, v34
	v_cvt_pk_bf16_f32 v0, v0, s0
	ds_write_b16 v40, v0 offset:53504
	v_mul_f32_e32 v0, v26, v34
	v_cvt_pk_bf16_f32 v0, v0, s0
	s_waitcnt lgkmcnt(14)
	v_rcp_f32_e32 v36, v36
	ds_write_b16 v40, v0 offset:53568
	v_mul_f32_e32 v0, v11, v35
	v_cvt_pk_bf16_f32 v0, v0, s0
	ds_write_b16 v40, v0 offset:53632
	v_mul_f32_e32 v0, v27, v35
	v_cvt_pk_bf16_f32 v0, v0, s0
	v_rcp_f32_e32 v37, v37
	ds_write_b16 v40, v0 offset:53696
	v_mul_f32_e32 v0, v12, v36
	v_cvt_pk_bf16_f32 v0, v0, s0
	ds_write_b16 v40, v0 offset:54272
	v_mul_f32_e32 v0, v28, v36
	v_cvt_pk_bf16_f32 v0, v0, s0
	v_rcp_f32_e32 v38, v38
	ds_write_b16 v40, v0 offset:54336
	v_mul_f32_e32 v0, v13, v37
	v_cvt_pk_bf16_f32 v0, v0, s0
	ds_write_b16 v40, v0 offset:54400
	v_mul_f32_e32 v0, v29, v37
	v_cvt_pk_bf16_f32 v0, v0, s0
	v_rcp_f32_e32 v39, v39
	ds_write_b16 v40, v0 offset:54464
	v_mul_f32_e32 v0, v14, v38
	v_cvt_pk_bf16_f32 v0, v0, s0
	ds_write_b16 v40, v0 offset:54528
	v_mul_f32_e32 v0, v30, v38
	v_cvt_pk_bf16_f32 v0, v0, s0
	ds_write_b16 v40, v0 offset:54592
	v_mul_f32_e32 v0, v15, v39
	v_cvt_pk_bf16_f32 v0, v0, s0
	ds_write_b16 v40, v0 offset:54656
	v_mul_f32_e32 v0, v31, v39
	v_and_b32_e32 v6, 7, v194
	v_cvt_pk_bf16_f32 v0, v0, s0
	v_lshlrev_b32_e32 v128, 4, v6
	ds_write_b16 v40, v0 offset:54720
	v_lshrrev_b32_e32 v5, 3, v195
	v_add_u32_e32 v7, s14, v128
	s_waitcnt lgkmcnt(0)
	v_lshl_add_u32 v9, v5, 7, v7
	v_and_b32_e32 v3, 64, v230
	ds_read_b128 v[10:13], v9 offset:51200
	v_xor_b32_e32 v2, 1, v230
	v_add_u32_e32 v4, 64, v3
	v_cmp_lt_i32_e32 vcc, v2, v4
	v_xor_b32_e32 v3, 2, v230
	v_xor_b32_e32 v8, 4, v230
	v_cndmask_b32_e32 v2, v230, v2, vcc
	v_cmp_lt_i32_e32 vcc, v3, v4
	s_waitcnt lgkmcnt(0)
; template<int THRL> __device__ __forceinline__ void attn_unit(int b,int h,int qb,const bf16*Q,const bf16*__restrict__ K,const bf16*__restrict__ V,bf16*O,float*gssrow,float mref,char*shm){
;     ...
;     for(int i=0;i<4;++i){const int row=i*8+(lane>>3),ch=lane&7; const u32x4 v=*(const u32x4*)(stg+row*64+ch*8); ATTN_STORE16(Ow+(long)row*OP+ch*8,v);
;       float ss=0.f;
;       #pragma unroll
;       for(int e=0;e<4;++e){const float lo=__uint_as_float(v[e]<<16),hi_=__uint_as_float(v[e]&0xffff0000u); ss+=lo*lo+hi_*hi_;}
;       ss+=__shfl_xor(ss,1); ss+=__shfl_xor(ss,2); ss+=__shfl_xor(ss,4);
;       if(ch==0)atomicAdd(gssrow+rowbase+q0+wid*QBLK+row,ss);} }
	v_and_b32_e32 v9, 0xffff0000, v11
	v_mul_f32_e32 v9, v9, v9
	v_cndmask_b32_e32 v3, v230, v3, vcc
	v_cmp_lt_i32_e32 vcc, v8, v4
	v_lshlrev_b32_e32 v2, 2, v2
	v_lshlrev_b32_e32 v3, 2, v3
	v_cndmask_b32_e32 v4, v230, v8, vcc
	v_and_b32_e32 v8, 0xffff0000, v10
	v_cmp_eq_u32_e32 vcc, 0, v6
	v_lshlrev_b32_e32 v6, 16, v10
	v_mul_f32_e32 v8, v8, v8
	v_fmac_f32_e32 v8, v6, v6
	v_lshlrev_b32_e32 v6, 16, v11
	v_fmac_f32_e32 v9, v6, v6
	v_add_f32_e32 v6, v8, v9
	v_and_b32_e32 v9, 0xffff0000, v12
	v_lshlrev_b32_e32 v8, 16, v12
	v_mul_f32_e32 v9, v9, v9
	v_fmac_f32_e32 v9, v8, v8
	v_add_f32_e32 v6, v9, v6
	v_and_b32_e32 v9, 0xffff0000, v13
	v_lshlrev_b32_e32 v8, 16, v13
	v_mul_f32_e32 v9, v9, v9
	v_fmac_f32_e32 v9, v8, v8
	v_add_f32_e32 v6, v9, v6
	s_nop 1
	v_mov_b32_dpp v8, v6 quad_perm:[1,0,3,2] row_mask:0xf bank_mask:0xf
	s_add_u32 s4, s4, s44
	s_addc_u32 s5, s5, s45
	v_lshl_add_u64 v[0:1], s[4:5], 0, v[128:129]
	s_lshl_b64 s[4:5], s[42:43], 2
	s_waitcnt lgkmcnt(0)
	v_add_f32_e32 v6, v6, v8
	s_nop 1
	v_mov_b32_dpp v8, v6 quad_perm:[2,3,0,1] row_mask:0xf bank_mask:0xf
	v_lshlrev_b32_e32 v4, 2, v4
	s_add_u32 s14, s8, s4
	s_addc_u32 s15, s9, s5
	s_lshl_b64 s[4:5], s[34:35], 2
	s_waitcnt lgkmcnt(0)
	v_add_f32_e32 v8, v6, v8
	s_nop 1
	v_mov_b32_dpp v9, v8 row_half_mirror row_mask:0xf bank_mask:0xf
	s_add_u32 s14, s14, s4
	s_addc_u32 s15, s15, s5
	s_lshl_b64 s[4:5], s[40:41], 2
	s_add_u32 s40, s14, s4
	v_lshlrev_b32_e32 v128, 11, v5
	s_addc_u32 s41, s15, s5
	v_lshl_add_u64 v[14:15], v[0:1], 0, v[128:129]
	v_lshlrev_b32_e32 v6, 2, v5
	global_store_dwordx4 v[14:15], v[10:13], off
	s_and_saveexec_b64 s[4:5], vcc
	s_mov_b32 s13, s95
	s_cbranch_execz .LBB0_455
	s_waitcnt lgkmcnt(0)
	v_add_f32_e32 v8, v8, v9
	global_atomic_add_f32 v6, v8, s[40:41]
.LBB0_455:
	s_or_b64 exec, exec, s[4:5]
	v_or_b32_e32 v12, 8, v5
	v_lshl_add_u32 v8, v12, 7, v7
	s_waitcnt lgkmcnt(0)
	ds_read_b128 v[8:11], v8 offset:51200
	v_lshlrev_b32_e32 v128, 11, v12
	v_lshl_add_u64 v[12:13], v[0:1], 0, v[128:129]
	s_waitcnt lgkmcnt(0)
	global_store_dwordx4 v[12:13], v[8:11], off
	v_lshlrev_b32_e32 v12, 16, v8
	s_nop 0
	v_and_b32_e32 v8, 0xffff0000, v8
	v_mul_f32_e32 v8, v8, v8
	v_fmac_f32_e32 v8, v12, v12
	v_lshlrev_b32_e32 v12, 16, v9
	v_and_b32_e32 v9, 0xffff0000, v9
	v_mul_f32_e32 v9, v9, v9
	v_fmac_f32_e32 v9, v12, v12
	v_add_f32_e32 v8, v8, v9
	v_lshlrev_b32_e32 v9, 16, v10
	v_and_b32_e32 v10, 0xffff0000, v10
	v_mul_f32_e32 v10, v10, v10
	v_fmac_f32_e32 v10, v9, v9
	v_add_f32_e32 v8, v10, v8
	v_and_b32_e32 v10, 0xffff0000, v11
	v_lshlrev_b32_e32 v9, 16, v11
	v_mul_f32_e32 v10, v10, v10
	v_fmac_f32_e32 v10, v9, v9
	v_add_f32_e32 v8, v10, v8
	s_nop 1
	v_mov_b32_dpp v9, v8 quad_perm:[1,0,3,2] row_mask:0xf bank_mask:0xf
	s_waitcnt lgkmcnt(0)
	v_add_f32_e32 v8, v8, v9
	s_nop 1
	v_mov_b32_dpp v9, v8 quad_perm:[2,3,0,1] row_mask:0xf bank_mask:0xf
	s_waitcnt lgkmcnt(0)
	v_add_f32_e32 v8, v8, v9
	s_nop 1
	v_mov_b32_dpp v9, v8 row_half_mirror row_mask:0xf bank_mask:0xf
	s_and_saveexec_b64 s[4:5], vcc
	s_cbranch_execz .LBB0_457
	s_waitcnt lgkmcnt(0)
	v_add_f32_e32 v8, v8, v9
	global_atomic_add_f32 v6, v8, s[40:41] offset:32
.LBB0_457:
	s_or_b64 exec, exec, s[4:5]
	v_or_b32_e32 v12, 16, v5
	v_lshl_add_u32 v8, v12, 7, v7
	s_waitcnt lgkmcnt(0)
	ds_read_b128 v[8:11], v8 offset:51200
	v_lshlrev_b32_e32 v128, 11, v12
	v_lshl_add_u64 v[12:13], v[0:1], 0, v[128:129]
	s_waitcnt lgkmcnt(0)
	global_store_dwordx4 v[12:13], v[8:11], off
	v_lshlrev_b32_e32 v12, 16, v8
	s_nop 0
	v_and_b32_e32 v8, 0xffff0000, v8
	v_mul_f32_e32 v8, v8, v8
	v_fmac_f32_e32 v8, v12, v12
	v_lshlrev_b32_e32 v12, 16, v9
	v_and_b32_e32 v9, 0xffff0000, v9
	v_mul_f32_e32 v9, v9, v9
	v_fmac_f32_e32 v9, v12, v12
	v_add_f32_e32 v8, v8, v9
	v_lshlrev_b32_e32 v9, 16, v10
	v_and_b32_e32 v10, 0xffff0000, v10
	v_mul_f32_e32 v10, v10, v10
	v_fmac_f32_e32 v10, v9, v9
	v_add_f32_e32 v8, v10, v8
	v_and_b32_e32 v10, 0xffff0000, v11
	v_lshlrev_b32_e32 v9, 16, v11
	v_mul_f32_e32 v10, v10, v10
	v_fmac_f32_e32 v10, v9, v9
	v_add_f32_e32 v8, v10, v8
	s_nop 1
	v_mov_b32_dpp v9, v8 quad_perm:[1,0,3,2] row_mask:0xf bank_mask:0xf
	s_waitcnt lgkmcnt(0)
	v_add_f32_e32 v8, v8, v9
	s_nop 1
	v_mov_b32_dpp v9, v8 quad_perm:[2,3,0,1] row_mask:0xf bank_mask:0xf
	s_waitcnt lgkmcnt(0)
	v_add_f32_e32 v8, v8, v9
	s_nop 1
	v_mov_b32_dpp v9, v8 row_half_mirror row_mask:0xf bank_mask:0xf
	s_and_saveexec_b64 s[4:5], vcc
	s_cbranch_execz .LBB0_459
	s_waitcnt lgkmcnt(0)
	v_add_f32_e32 v8, v8, v9
	global_atomic_add_f32 v6, v8, s[40:41] offset:64
.LBB0_459:
	s_or_b64 exec, exec, s[4:5]
	v_or_b32_e32 v5, 24, v5
	v_lshl_add_u32 v7, v5, 7, v7
	s_waitcnt lgkmcnt(0)
	ds_read_b128 v[8:11], v7 offset:51200
	v_lshlrev_b32_e32 v128, 11, v5
	v_lshl_add_u64 v[0:1], v[0:1], 0, v[128:129]
	s_waitcnt lgkmcnt(0)
	global_store_dwordx4 v[0:1], v[8:11], off
	v_and_b32_e32 v1, 0xffff0000, v8
	v_lshlrev_b32_e32 v0, 16, v8
	v_mul_f32_e32 v1, v1, v1
	v_and_b32_e32 v5, 0xffff0000, v9
	v_fmac_f32_e32 v1, v0, v0
	v_lshlrev_b32_e32 v0, 16, v9
	v_mul_f32_e32 v5, v5, v5
	v_fmac_f32_e32 v5, v0, v0
	v_add_f32_e32 v0, v1, v5
	v_and_b32_e32 v5, 0xffff0000, v10
	v_lshlrev_b32_e32 v1, 16, v10
	v_mul_f32_e32 v5, v5, v5
	v_fmac_f32_e32 v5, v1, v1
	v_add_f32_e32 v0, v5, v0
	v_and_b32_e32 v5, 0xffff0000, v11
	v_lshlrev_b32_e32 v1, 16, v11
	v_mul_f32_e32 v5, v5, v5
	v_fmac_f32_e32 v5, v1, v1
	v_add_f32_e32 v0, v5, v0
	s_nop 1
	v_mov_b32_dpp v1, v0 quad_perm:[1,0,3,2] row_mask:0xf bank_mask:0xf
	s_waitcnt lgkmcnt(0)
	v_add_f32_e32 v0, v0, v1
	s_nop 1
	v_mov_b32_dpp v1, v0 quad_perm:[2,3,0,1] row_mask:0xf bank_mask:0xf
	s_waitcnt lgkmcnt(0)
	v_add_f32_e32 v0, v0, v1
	s_nop 1
	v_mov_b32_dpp v1, v0 row_half_mirror row_mask:0xf bank_mask:0xf
	s_and_saveexec_b64 s[4:5], vcc
	s_cbranch_execz .LBB0_443
	s_waitcnt lgkmcnt(0)
	v_add_f32_e32 v0, v0, v1
	global_atomic_add_f32 v6, v0, s[40:41] offset:96
	s_branch .LBB0_443

; __device__ __forceinline__ unsigned pk_f16(float lo, float hi) { f32x2 v = {lo, hi}; f16x2_t h = __builtin_convertvector(v, f16x2_t); return __builtin_bit_cast(unsigned, h); }
; __device__ __forceinline__ f32x2 up_f16(unsigned w) { return __builtin_convertvector(__builtin_bit_cast(f16x2_t, w), f32x2); }
;     __device__ __forceinline__ void operator()(const f32x4 (&acc)[2][2][4][2], const Unit& u, int wr, int wc, int fr, int fq) const {
;         const int row0 = u.pm * BM + wr * 64 + fr; const int b = (u.pm * BM) >> 14;
;         int fqo = fq; asm volatile("" : "+v"(fqo));
;         const int col0 = u.pn * BM + wc * 32 + 8 * fqo;
;         float ss[2][4];
; #pragma unroll
;         for (int ai = 0; ai < 2; ++ai)
; #pragma unroll
;             for (int m = 0; m < 4; ++m) ss[ai][m] = 0.f;
; #pragma unroll
;         for (int bj = 0; bj < 2; ++bj) {
;             f32x4 gv[2];
; #pragma unroll
;             for (int n = 0; n < 2; ++n) gv[n] = *(const f32x4*)(gate + (size_t)b * gstride + col0 + bj * HALF + 4 * n);
;             u32x4 pq[2][4];
; #pragma unroll
;             for (int ai = 0; ai < 2; ++ai)
; #pragma unroll
;                 for (int m = 0; m < 4; ++m) pq[ai][m] = *(const u32x4*)(base + (size_t)(row0 + ai * HALF + m * 16) * 1024 + col0 + bj * HALF);
;             asm volatile("" ::: "memory");
; #pragma unroll
;             for (int ai = 0; ai < 2; ++ai) {
; #pragma unroll
;                 for (int m = 0; m < 4; ++m) { const size_t off = (size_t)(row0 + ai * HALF + m * 16) * 1024 + col0 + bj * HALF;
;                     float rc = 1.0f; if constexpr (GN) rc = rsqrtf(gss[2 * 32768 + row0 + ai * HALF + m * 16] * (1.0f / 384.0f) + 1e-6f);
;                     const u32x4 q = pq[ai][m];
;                     const f32x2 qa_ = up_f16(q.x), qb_ = up_f16(q.y), qc_ = up_f16(q.z), qd_ = up_f16(q.w);
;                     const f32x4 x0 = (f32x4){qa_[0], qa_[1], qb_[0], qb_[1]} + gv[0] * (acc[ai][bj][m][0] * rc),
;                                 x1 = (f32x4){qc_[0], qc_[1], qd_[0], qd_[1]} + gv[1] * (acc[ai][bj][m][1] * rc);
;                     { u32x4 wx; wx.x = pk_f16(x0[0], x0[1]); wx.y = pk_f16(x0[2], x0[3]); wx.z = pk_f16(x1[0], x1[1]); wx.w = pk_f16(x1[2], x1[3]); *(u32x4*)(out + off) = wx; }
.LBB0_806:
	s_lshl_b32 s1, s68, 8
	v_mov_b32_e32 v128, v237
	s_ashr_i32 s0, s69, 6
	s_or_b32 s1, s1, s29
	v_or_b32_e32 v140, 16, v186
	v_lshl_add_u32 v138, v128, 3, s1
	s_mul_hi_i32 s1, s0, 0x6000
	s_mulk_i32 s0, 0x6000
	s_add_u32 s0, s20, s0
	v_ashrrev_i32_e32 v139, 31, v138
	s_addc_u32 s1, s21, s1
	v_ashrrev_i32_e32 v141, 31, v140
	v_lshlrev_b64 v[208:209], 11, v[186:187]
	v_lshl_add_u64 v[190:191], v[138:139], 2, s[0:1]
	v_lshlrev_b64 v[246:247], 11, v[140:141]
	v_or_b32_e32 v140, 32, v186
	s_mov_b64 s[0:1], 0x48000
	v_ashrrev_i32_e32 v141, 31, v140
	v_lshl_add_u64 v[220:221], v[208:209], 0, s[0:1]
	s_mov_b64 s[0:1], 0x50000
	s_mov_b64 s[4:5], 0x40000
	v_lshlrev_b64 v[206:207], 1, v[138:139]
	v_lshlrev_b64 v[248:249], 11, v[140:141]
	v_or_b32_e32 v140, 48, v186
	v_lshl_add_u64 v[222:223], v[208:209], 0, s[0:1]
	s_mov_b64 s[0:1], 0x58000
	v_lshl_add_u64 v[218:219], v[208:209], 0, s[4:5]
	v_lshl_add_u64 v[138:139], s[96:97], 0, v[206:207]
	v_ashrrev_i32_e32 v141, 31, v140
	v_lshl_add_u64 v[216:217], v[208:209], 0, s[0:1]
	s_mov_b32 s0, 0x40000
	v_lshl_add_u64 v[192:193], v[138:139], 0, v[208:209]
	v_lshl_add_u64 v[196:197], v[138:139], 0, v[248:249]
	v_lshlrev_b64 v[224:225], 11, v[140:141]
	v_lshl_add_u64 v[200:201], v[138:139], 0, v[218:219]
	v_lshl_add_u64 v[204:205], v[138:139], 0, v[222:223]
	v_add_co_u32_e32 v188, vcc, s0, v188
	global_load_dwordx4 v[130:133], v[190:191], off offset:16
	global_load_dwordx4 v[134:137], v[190:191], off
	v_lshl_add_u64 v[194:195], v[138:139], 0, v[246:247]
	global_load_dwordx4 v[212:215], v[192:193], off
	global_load_dwordx4 v[242:245], v[194:195], off
	v_lshl_add_u64 v[198:199], v[138:139], 0, v[224:225]
	global_load_dwordx4 v[158:161], v[196:197], off
	global_load_dwordx4 v[154:157], v[198:199], off
	v_lshl_add_u64 v[202:203], v[138:139], 0, v[220:221]
	global_load_dwordx4 v[150:153], v[200:201], off
	global_load_dwordx4 v[146:149], v[202:203], off
	v_lshl_add_u64 v[210:211], v[138:139], 0, v[216:217]
	global_load_dwordx4 v[142:145], v[204:205], off
	global_load_dwordx4 v[138:141], v[210:211], off
	v_addc_co_u32_e32 v189, vcc, 0, v189, vcc
	global_load_dword v128, v[188:189], off
	global_load_dword v163, v[188:189], off offset:64
	global_load_dword v165, v[188:189], off offset:128
	global_load_dword v167, v[188:189], off offset:192
	global_load_dword v169, v[188:189], off offset:512
	global_load_dword v171, v[188:189], off offset:576
	global_load_dword v173, v[188:189], off offset:640
	v_lshl_add_u64 v[208:209], s[96:97], 0, v[208:209]
	v_lshl_add_u64 v[208:209], v[208:209], 0, v[206:207]
	s_waitcnt vmcnt(0)
	v_cvt_f32_f16_e32 v250, v212
	v_cvt_f32_f16_sdwa v251, v212 dst_sel:DWORD dst_unused:UNUSED_PAD src0_sel:WORD_1
	v_cvt_f32_f16_e32 v212, v213
	v_cvt_f32_f16_sdwa v213, v213 dst_sel:DWORD dst_unused:UNUSED_PAD src0_sel:WORD_1
	v_cvt_f32_f16_e32 v174, v214
	v_fmamk_f32 v128, v128, 0x3b2aaaab, v227
	s_nop 1
	v_rsq_f32_e32 v128, v128
	v_cvt_f32_f16_sdwa v175, v214 dst_sel:DWORD dst_unused:UNUSED_PAD src0_sel:WORD_1
	v_cvt_f32_f16_e32 v214, v215
	v_cvt_f32_f16_sdwa v215, v215 dst_sel:DWORD dst_unused:UNUSED_PAD src0_sel:WORD_1
	v_pk_mul_f32 v[124:125], v[124:125], v[128:129] op_sel_hi:[1,0]
	v_pk_mul_f32 v[126:127], v[126:127], v[128:129] op_sel_hi:[1,0]
	v_pk_mul_f32 v[176:177], v[120:121], v[128:129] op_sel_hi:[1,0]
	v_pk_mul_f32 v[122:123], v[122:123], v[128:129] op_sel_hi:[1,0]
	v_pk_fma_f32 v[120:121], v[136:137], v[126:127], v[212:213]
	v_pk_fma_f32 v[124:125], v[134:135], v[124:125], v[250:251]
	v_pk_fma_f32 v[122:123], v[132:133], v[122:123], v[214:215]
	v_pk_fma_f32 v[126:127], v[130:131], v[176:177], v[174:175]
	v_cvt_pk_f16_f32 v212, v124, v125
	v_cvt_pk_f16_f32 v213, v120, v121
	v_cvt_pk_f16_f32 v214, v126, v127
	v_cvt_pk_f16_f32 v215, v122, v123
	global_store_dwordx4 v[208:209], v[212:215], off
	s_nop 0
	v_lshl_add_u64 v[174:175], s[96:97], 0, v[246:247]
	v_lshl_add_u64 v[212:213], v[174:175], 0, v[206:207]
	v_cvt_f32_f16_e32 v174, v242
	v_cvt_f32_f16_sdwa v175, v242 dst_sel:DWORD dst_unused:UNUSED_PAD src0_sel:WORD_1
	v_cvt_f32_f16_e32 v176, v243
	v_cvt_f32_f16_sdwa v177, v243 dst_sel:DWORD dst_unused:UNUSED_PAD src0_sel:WORD_1
	v_cvt_f32_f16_e32 v214, v244
	v_cvt_f32_f16_e32 v242, v245
	v_cvt_f32_f16_sdwa v243, v245 dst_sel:DWORD dst_unused:UNUSED_PAD src0_sel:WORD_1
	v_fmamk_f32 v128, v163, 0x3b2aaaab, v227
	s_nop 1
	v_rsq_f32_e32 v128, v128
	v_cvt_f32_f16_sdwa v215, v244 dst_sel:DWORD dst_unused:UNUSED_PAD src0_sel:WORD_1
	v_pk_mul_f32 v[244:245], v[116:117], v[128:129] op_sel_hi:[1,0]
	v_pk_mul_f32 v[116:117], v[118:119], v[128:129] op_sel_hi:[1,0]
	v_pk_mul_f32 v[246:247], v[112:113], v[128:129] op_sel_hi:[1,0]
	v_pk_mul_f32 v[112:113], v[114:115], v[128:129] op_sel_hi:[1,0]
	v_pk_fma_f32 v[116:117], v[136:137], v[116:117], v[176:177]
	v_pk_fma_f32 v[118:119], v[134:135], v[244:245], v[174:175]
	v_pk_fma_f32 v[112:113], v[132:133], v[112:113], v[242:243]
	v_pk_fma_f32 v[114:115], v[130:131], v[246:247], v[214:215]
	v_cvt_pk_f16_f32 v242, v118, v119
	v_cvt_pk_f16_f32 v243, v116, v117
	v_cvt_pk_f16_f32 v244, v114, v115
	v_cvt_pk_f16_f32 v245, v112, v113
	global_store_dwordx4 v[212:213], v[242:245], off
	s_nop 0
	v_lshl_add_u64 v[174:175], s[96:97], 0, v[248:249]
	v_lshl_add_u64 v[214:215], v[174:175], 0, v[206:207]
	v_cvt_f32_f16_e32 v174, v158
	v_cvt_f32_f16_sdwa v175, v158 dst_sel:DWORD dst_unused:UNUSED_PAD src0_sel:WORD_1
	v_cvt_f32_f16_e32 v158, v159
	v_cvt_f32_f16_sdwa v159, v159 dst_sel:DWORD dst_unused:UNUSED_PAD src0_sel:WORD_1
	v_cvt_f32_f16_e32 v176, v160
	v_fmamk_f32 v128, v165, 0x3b2aaaab, v227
	s_nop 1
	v_rsq_f32_e32 v128, v128
; __device__ __forceinline__ unsigned pk_f16(float lo, float hi) { f32x2 v = {lo, hi}; f16x2_t h = __builtin_convertvector(v, f16x2_t); return __builtin_bit_cast(unsigned, h); }
; __device__ __forceinline__ f32x2 up_f16(unsigned w) { return __builtin_convertvector(__builtin_bit_cast(f16x2_t, w), f32x2); }
;     __device__ __forceinline__ void operator()(const f32x4 (&acc)[2][2][4][2], const Unit& u, int wr, int wc, int fr, int fq) const {
;     ...
;             for (int n = 0; n < 2; ++n) gv[n] = *(const f32x4*)(gate + (size_t)b * gstride + col0 + bj * HALF + 4 * n);
;             u32x4 pq[2][4];
; #pragma unroll
;             for (int ai = 0; ai < 2; ++ai)
; #pragma unroll
;                 for (int m = 0; m < 4; ++m) pq[ai][m] = *(const u32x4*)(base + (size_t)(row0 + ai * HALF + m * 16) * 1024 + col0 + bj * HALF);
;             asm volatile("" ::: "memory");
; #pragma unroll
;             for (int ai = 0; ai < 2; ++ai) {
; #pragma unroll
;                 for (int m = 0; m < 4; ++m) { const size_t off = (size_t)(row0 + ai * HALF + m * 16) * 1024 + col0 + bj * HALF;
;                     float rc = 1.0f; if constexpr (GN) rc = rsqrtf(gss[2 * 32768 + row0 + ai * HALF + m * 16] * (1.0f / 384.0f) + 1e-6f);
;                     const u32x4 q = pq[ai][m];
;                     const f32x2 qa_ = up_f16(q.x), qb_ = up_f16(q.y), qc_ = up_f16(q.z), qd_ = up_f16(q.w);
;                     const f32x4 x0 = (f32x4){qa_[0], qa_[1], qb_[0], qb_[1]} + gv[0] * (acc[ai][bj][m][0] * rc),
;                                 x1 = (f32x4){qc_[0], qc_[1], qd_[0], qd_[1]} + gv[1] * (acc[ai][bj][m][1] * rc);
;                     { u32x4 wx; wx.x = pk_f16(x0[0], x0[1]); wx.y = pk_f16(x0[2], x0[3]); wx.z = pk_f16(x1[0], x1[1]); wx.w = pk_f16(x1[2], x1[3]); *(u32x4*)(out + off) = wx; }
	v_cvt_f32_f16_sdwa v177, v160 dst_sel:DWORD dst_unused:UNUSED_PAD src0_sel:WORD_1
	v_cvt_f32_f16_e32 v160, v161
	v_cvt_f32_f16_sdwa v161, v161 dst_sel:DWORD dst_unused:UNUSED_PAD src0_sel:WORD_1
	v_pk_mul_f32 v[242:243], v[108:109], v[128:129] op_sel_hi:[1,0]
	v_pk_mul_f32 v[108:109], v[110:111], v[128:129] op_sel_hi:[1,0]
	v_pk_mul_f32 v[244:245], v[104:105], v[128:129] op_sel_hi:[1,0]
	v_pk_mul_f32 v[104:105], v[106:107], v[128:129] op_sel_hi:[1,0]
	v_pk_fma_f32 v[108:109], v[136:137], v[108:109], v[158:159]
	v_pk_fma_f32 v[110:111], v[134:135], v[242:243], v[174:175]
	v_pk_fma_f32 v[104:105], v[132:133], v[104:105], v[160:161]
	v_pk_fma_f32 v[106:107], v[130:131], v[244:245], v[176:177]
	v_cvt_pk_f16_f32 v158, v110, v111
	v_cvt_pk_f16_f32 v159, v108, v109
	v_cvt_pk_f16_f32 v160, v106, v107
	v_cvt_pk_f16_f32 v161, v104, v105
	global_store_dwordx4 v[214:215], v[158:161], off
	s_nop 0
	v_cvt_f32_f16_e32 v174, v156
	v_cvt_f32_f16_e32 v160, v154
	v_cvt_f32_f16_sdwa v161, v154 dst_sel:DWORD dst_unused:UNUSED_PAD src0_sel:WORD_1
	v_cvt_f32_f16_e32 v154, v155
	v_cvt_f32_f16_sdwa v155, v155 dst_sel:DWORD dst_unused:UNUSED_PAD src0_sel:WORD_1
	v_lshl_add_u64 v[158:159], s[96:97], 0, v[224:225]
	v_lshl_add_u64 v[158:159], v[158:159], 0, v[206:207]
	v_fmamk_f32 v128, v167, 0x3b2aaaab, v227
	s_nop 1
	v_rsq_f32_e32 v128, v128
	v_cvt_f32_f16_sdwa v175, v156 dst_sel:DWORD dst_unused:UNUSED_PAD src0_sel:WORD_1
	v_cvt_f32_f16_e32 v156, v157
	v_cvt_f32_f16_sdwa v157, v157 dst_sel:DWORD dst_unused:UNUSED_PAD src0_sel:WORD_1
	v_pk_mul_f32 v[176:177], v[100:101], v[128:129] op_sel_hi:[1,0]
	v_pk_mul_f32 v[100:101], v[102:103], v[128:129] op_sel_hi:[1,0]
	v_pk_mul_f32 v[224:225], v[96:97], v[128:129] op_sel_hi:[1,0]
	v_pk_mul_f32 v[96:97], v[98:99], v[128:129] op_sel_hi:[1,0]
	v_pk_fma_f32 v[100:101], v[136:137], v[100:101], v[154:155]
	v_pk_fma_f32 v[102:103], v[134:135], v[176:177], v[160:161]
	v_pk_fma_f32 v[96:97], v[132:133], v[96:97], v[156:157]
	v_pk_fma_f32 v[98:99], v[130:131], v[224:225], v[174:175]
	v_cvt_pk_f16_f32 v154, v102, v103
	v_cvt_pk_f16_f32 v155, v100, v101
	v_cvt_pk_f16_f32 v156, v98, v99
	v_cvt_pk_f16_f32 v157, v96, v97
	global_store_dwordx4 v[158:159], v[154:157], off
	s_nop 0
	v_fmamk_f32 v128, v169, 0x3b2aaaab, v227
	v_lshl_add_u64 v[154:155], s[96:97], 0, v[218:219]
	v_lshl_add_u64 v[218:219], v[154:155], 0, v[206:207]
	v_rsq_f32_e32 v128, v128
	v_cvt_f32_f16_e32 v154, v150
	v_cvt_f32_f16_sdwa v155, v150 dst_sel:DWORD dst_unused:UNUSED_PAD src0_sel:WORD_1
	v_cvt_f32_f16_e32 v150, v151
	v_cvt_f32_f16_sdwa v151, v151 dst_sel:DWORD dst_unused:UNUSED_PAD src0_sel:WORD_1
	v_cvt_f32_f16_e32 v156, v152
	v_cvt_f32_f16_sdwa v157, v152 dst_sel:DWORD dst_unused:UNUSED_PAD src0_sel:WORD_1
	v_cvt_f32_f16_e32 v152, v153
	v_cvt_f32_f16_sdwa v153, v153 dst_sel:DWORD dst_unused:UNUSED_PAD src0_sel:WORD_1
	v_pk_mul_f32 v[160:161], v[92:93], v[128:129] op_sel_hi:[1,0]
	v_pk_mul_f32 v[92:93], v[94:95], v[128:129] op_sel_hi:[1,0]
	v_pk_mul_f32 v[174:175], v[88:89], v[128:129] op_sel_hi:[1,0]
	v_pk_mul_f32 v[88:89], v[90:91], v[128:129] op_sel_hi:[1,0]
	v_pk_fma_f32 v[92:93], v[136:137], v[92:93], v[150:151]
	v_pk_fma_f32 v[94:95], v[134:135], v[160:161], v[154:155]
	v_pk_fma_f32 v[88:89], v[132:133], v[88:89], v[152:153]
	v_pk_fma_f32 v[90:91], v[130:131], v[174:175], v[156:157]
	v_cvt_pk_f16_f32 v150, v94, v95
	v_cvt_pk_f16_f32 v151, v92, v93
	v_cvt_pk_f16_f32 v152, v90, v91
	v_cvt_pk_f16_f32 v153, v88, v89
	global_store_dwordx4 v[218:219], v[150:153], off
	s_nop 0
	v_cvt_f32_f16_e32 v154, v148
	v_lshl_add_u64 v[150:151], s[96:97], 0, v[220:221]
	v_lshl_add_u64 v[220:221], v[150:151], 0, v[206:207]
	v_cvt_f32_f16_e32 v152, v146
	v_cvt_f32_f16_sdwa v153, v146 dst_sel:DWORD dst_unused:UNUSED_PAD src0_sel:WORD_1
	v_cvt_f32_f16_e32 v146, v147
	v_cvt_f32_f16_sdwa v147, v147 dst_sel:DWORD dst_unused:UNUSED_PAD src0_sel:WORD_1
	v_cvt_f32_f16_sdwa v155, v148 dst_sel:DWORD dst_unused:UNUSED_PAD src0_sel:WORD_1
	v_cvt_f32_f16_e32 v148, v149
	v_cvt_f32_f16_sdwa v149, v149 dst_sel:DWORD dst_unused:UNUSED_PAD src0_sel:WORD_1
	v_fmamk_f32 v128, v171, 0x3b2aaaab, v227
	s_nop 1
	v_rsq_f32_e32 v128, v128
	s_nop 0
	v_pk_mul_f32 v[84:85], v[84:85], v[128:129] op_sel_hi:[1,0]
	v_pk_mul_f32 v[86:87], v[86:87], v[128:129] op_sel_hi:[1,0]
	v_pk_mul_f32 v[80:81], v[80:81], v[128:129] op_sel_hi:[1,0]
	v_pk_mul_f32 v[82:83], v[82:83], v[128:129] op_sel_hi:[1,0]
	v_pk_fma_f32 v[150:151], v[136:137], v[86:87], v[146:147]
	v_pk_fma_f32 v[152:153], v[134:135], v[84:85], v[152:153]
	v_pk_fma_f32 v[146:147], v[132:133], v[82:83], v[148:149]
	v_pk_fma_f32 v[148:149], v[130:131], v[80:81], v[154:155]
	v_cvt_pk_f16_f32 v80, v152, v153
	v_cvt_pk_f16_f32 v81, v150, v151
	v_cvt_pk_f16_f32 v82, v148, v149
	v_cvt_pk_f16_f32 v83, v146, v147
	global_store_dwordx4 v[220:221], v[80:83], off
	s_nop 0
	v_cvt_f32_f16_e32 v84, v144
	v_lshl_add_u64 v[80:81], s[96:97], 0, v[222:223]
	v_lshl_add_u64 v[222:223], v[80:81], 0, v[206:207]
	v_cvt_f32_f16_e32 v80, v142
	v_cvt_f32_f16_sdwa v81, v142 dst_sel:DWORD dst_unused:UNUSED_PAD src0_sel:WORD_1
	v_cvt_f32_f16_e32 v82, v143
	v_cvt_f32_f16_sdwa v83, v143 dst_sel:DWORD dst_unused:UNUSED_PAD src0_sel:WORD_1
	v_cvt_f32_f16_sdwa v87, v145 dst_sel:DWORD dst_unused:UNUSED_PAD src0_sel:WORD_1
	v_fmamk_f32 v85, v173, 0x3b2aaaab, v227
	s_nop 1
	v_rsq_f32_e32 v128, v85
	v_cvt_f32_f16_sdwa v85, v144 dst_sel:DWORD dst_unused:UNUSED_PAD src0_sel:WORD_1
	v_cvt_f32_f16_e32 v86, v145
	v_pk_mul_f32 v[76:77], v[76:77], v[128:129] op_sel_hi:[1,0]
	v_pk_mul_f32 v[78:79], v[78:79], v[128:129] op_sel_hi:[1,0]
	v_pk_mul_f32 v[72:73], v[72:73], v[128:129] op_sel_hi:[1,0]
	v_pk_mul_f32 v[74:75], v[74:75], v[128:129] op_sel_hi:[1,0]
	v_pk_fma_f32 v[154:155], v[136:137], v[78:79], v[82:83]
	v_pk_fma_f32 v[156:157], v[134:135], v[76:77], v[80:81]
	v_pk_fma_f32 v[142:143], v[132:133], v[74:75], v[86:87]
	v_pk_fma_f32 v[144:145], v[130:131], v[72:73], v[84:85]
	v_cvt_pk_f16_f32 v72, v156, v157
	v_cvt_pk_f16_f32 v73, v154, v155
	v_cvt_pk_f16_f32 v74, v144, v145
	v_cvt_pk_f16_f32 v75, v142, v143
	global_store_dwordx4 v[222:223], v[72:75], off
	global_load_dword v77, v[188:189], off offset:704
	v_cvt_f32_f16_e32 v76, v140
	v_lshl_add_u64 v[72:73], s[96:97], 0, v[216:217]
	v_lshl_add_u64 v[160:161], v[72:73], 0, v[206:207]
	v_cvt_f32_f16_e32 v72, v138
	v_cvt_f32_f16_sdwa v73, v138 dst_sel:DWORD dst_unused:UNUSED_PAD src0_sel:WORD_1
	v_cvt_f32_f16_e32 v74, v139
	v_cvt_f32_f16_sdwa v75, v139 dst_sel:DWORD dst_unused:UNUSED_PAD src0_sel:WORD_1
	v_cvt_f32_f16_sdwa v79, v141 dst_sel:DWORD dst_unused:UNUSED_PAD src0_sel:WORD_1
	s_waitcnt vmcnt(0)
; __device__ __forceinline__ unsigned pk_f16(float lo, float hi) { f32x2 v = {lo, hi}; f16x2_t h = __builtin_convertvector(v, f16x2_t); return __builtin_bit_cast(unsigned, h); }
; __device__ __forceinline__ f32x2 up_f16(unsigned w) { return __builtin_convertvector(__builtin_bit_cast(f16x2_t, w), f32x2); }
;     __device__ __forceinline__ void operator()(const f32x4 (&acc)[2][2][4][2], const Unit& u, int wr, int wc, int fr, int fq) const {
;     ...
;         for (int bj = 0; bj < 2; ++bj) {
;             f32x4 gv[2];
; #pragma unroll
;             for (int n = 0; n < 2; ++n) gv[n] = *(const f32x4*)(gate + (size_t)b * gstride + col0 + bj * HALF + 4 * n);
;             u32x4 pq[2][4];
; #pragma unroll
;             for (int ai = 0; ai < 2; ++ai)
; #pragma unroll
;                 for (int m = 0; m < 4; ++m) pq[ai][m] = *(const u32x4*)(base + (size_t)(row0 + ai * HALF + m * 16) * 1024 + col0 + bj * HALF);
;             asm volatile("" ::: "memory");
; #pragma unroll
;             for (int ai = 0; ai < 2; ++ai) {
; #pragma unroll
;                 for (int m = 0; m < 4; ++m) { const size_t off = (size_t)(row0 + ai * HALF + m * 16) * 1024 + col0 + bj * HALF;
;                     float rc = 1.0f; if constexpr (GN) rc = rsqrtf(gss[2 * 32768 + row0 + ai * HALF + m * 16] * (1.0f / 384.0f) + 1e-6f);
;                     const u32x4 q = pq[ai][m];
;                     const f32x2 qa_ = up_f16(q.x), qb_ = up_f16(q.y), qc_ = up_f16(q.z), qd_ = up_f16(q.w);
;                     const f32x4 x0 = (f32x4){qa_[0], qa_[1], qb_[0], qb_[1]} + gv[0] * (acc[ai][bj][m][0] * rc),
;                                 x1 = (f32x4){qc_[0], qc_[1], qd_[0], qd_[1]} + gv[1] * (acc[ai][bj][m][1] * rc);
;                     { u32x4 wx; wx.x = pk_f16(x0[0], x0[1]); wx.y = pk_f16(x0[2], x0[3]); wx.z = pk_f16(x1[0], x1[1]); wx.w = pk_f16(x1[2], x1[3]); *(u32x4*)(out + off) = wx; }
;                     ss[ai][m] += ((x0[0] * x0[0] + x0[1] * x0[1]) + (x0[2] * x0[2] + x0[3] * x0[3])) + ((x1[0] * x1[0] + x1[1] * x1[1]) + (x1[2] * x1[2] + x1[3] * x1[3]));
	v_fmamk_f32 v77, v77, 0x3b2aaaab, v227
	s_nop 1
	v_rsq_f32_e32 v80, v77
	v_cvt_f32_f16_sdwa v77, v140 dst_sel:DWORD dst_unused:UNUSED_PAD src0_sel:WORD_1
	v_cvt_f32_f16_e32 v78, v141
	v_pk_mul_f32 v[68:69], v[68:69], v[80:81] op_sel_hi:[1,0]
	v_pk_mul_f32 v[70:71], v[70:71], v[80:81] op_sel_hi:[1,0]
	v_pk_mul_f32 v[64:65], v[64:65], v[80:81] op_sel_hi:[1,0]
	v_pk_mul_f32 v[66:67], v[66:67], v[80:81] op_sel_hi:[1,0]
	v_pk_fma_f32 v[136:137], v[136:137], v[70:71], v[74:75]
	v_pk_fma_f32 v[134:135], v[134:135], v[68:69], v[72:73]
	v_pk_fma_f32 v[132:133], v[132:133], v[66:67], v[78:79]
	v_pk_fma_f32 v[130:131], v[130:131], v[64:65], v[76:77]
	v_cvt_pk_f16_f32 v64, v134, v135
	v_cvt_pk_f16_f32 v65, v136, v137
	v_cvt_pk_f16_f32 v66, v130, v131
	v_cvt_pk_f16_f32 v67, v132, v133
	global_store_dwordx4 v[160:161], v[64:67], off
	global_load_dwordx4 v[64:67], v[190:191], off offset:528
	global_load_dwordx4 v[68:71], v[190:191], off offset:512
	global_load_dwordx4 v[138:141], v[192:193], off offset:256
	s_nop 0
	global_load_dwordx4 v[190:193], v[194:195], off offset:256
	s_nop 0
	global_load_dwordx4 v[194:197], v[196:197], off offset:256
	s_nop 0
	global_load_dwordx4 v[242:245], v[198:199], off offset:256
	global_load_dwordx4 v[84:87], v[200:201], off offset:256
	global_load_dwordx4 v[80:83], v[202:203], off offset:256
	global_load_dwordx4 v[76:79], v[204:205], off offset:256
	global_load_dwordx4 v[72:75], v[210:211], off offset:256
	global_load_dword v128, v[188:189], off
	s_waitcnt vmcnt(8)
	v_cvt_f32_f16_e32 v174, v138
	v_cvt_f32_f16_sdwa v175, v138 dst_sel:DWORD dst_unused:UNUSED_PAD src0_sel:WORD_1
	v_cvt_f32_f16_e32 v138, v139
	v_cvt_f32_f16_sdwa v139, v139 dst_sel:DWORD dst_unused:UNUSED_PAD src0_sel:WORD_1
	v_cvt_f32_f16_e32 v176, v140
	s_waitcnt vmcnt(0)
	v_fmamk_f32 v128, v128, 0x3b2aaaab, v227
	s_nop 1
	v_rsq_f32_e32 v128, v128
	v_cvt_f32_f16_sdwa v177, v140 dst_sel:DWORD dst_unused:UNUSED_PAD src0_sel:WORD_1
	v_cvt_f32_f16_e32 v140, v141
	v_cvt_f32_f16_sdwa v141, v141 dst_sel:DWORD dst_unused:UNUSED_PAD src0_sel:WORD_1
	v_pk_mul_f32 v[60:61], v[60:61], v[128:129] op_sel_hi:[1,0]
	v_pk_mul_f32 v[62:63], v[62:63], v[128:129] op_sel_hi:[1,0]
	v_pk_mul_f32 v[198:199], v[56:57], v[128:129] op_sel_hi:[1,0]
	v_pk_mul_f32 v[200:201], v[58:59], v[128:129] op_sel_hi:[1,0]
	v_pk_fma_f32 v[56:57], v[70:71], v[62:63], v[138:139]
	v_pk_fma_f32 v[58:59], v[68:69], v[60:61], v[174:175]
	v_pk_fma_f32 v[60:61], v[66:67], v[200:201], v[140:141]
	v_pk_fma_f32 v[62:63], v[64:65], v[198:199], v[176:177]
	v_cvt_pk_f16_f32 v138, v58, v59
	v_cvt_pk_f16_f32 v139, v56, v57
	v_cvt_pk_f16_f32 v140, v62, v63
	v_cvt_pk_f16_f32 v141, v60, v61
	global_store_dwordx4 v[208:209], v[138:141], off offset:256
	s_nop 0
	v_cvt_f32_f16_e32 v174, v192
	v_cvt_f32_f16_e32 v138, v190
	v_cvt_f32_f16_sdwa v139, v190 dst_sel:DWORD dst_unused:UNUSED_PAD src0_sel:WORD_1
	v_cvt_f32_f16_e32 v140, v191
	v_cvt_f32_f16_sdwa v141, v191 dst_sel:DWORD dst_unused:UNUSED_PAD src0_sel:WORD_1
	v_cvt_f32_f16_e32 v176, v193
	v_cvt_f32_f16_sdwa v177, v193 dst_sel:DWORD dst_unused:UNUSED_PAD src0_sel:WORD_1
	v_mul_f32_e32 v59, v59, v59
	v_mul_f32_e32 v57, v57, v57
	v_mul_f32_e32 v63, v63, v63
	v_mul_f32_e32 v61, v61, v61
	v_fmac_f32_e32 v59, v58, v58
	v_fmac_f32_e32 v57, v56, v56
	v_fmac_f32_e32 v63, v62, v62
	v_fmac_f32_e32 v61, v60, v60
	v_add_f32_e32 v56, v59, v57
	v_add_f32_e32 v57, v63, v61
	v_add_f32_e32 v56, v56, v57
	v_cvt_f32_f16_e32 v60, v75
	v_cvt_f32_f16_sdwa v61, v75 dst_sel:DWORD dst_unused:UNUSED_PAD src0_sel:WORD_1
	v_fmamk_f32 v128, v163, 0x3b2aaaab, v227
	s_nop 1
	v_rsq_f32_e32 v128, v128
	v_cvt_f32_f16_sdwa v175, v192 dst_sel:DWORD dst_unused:UNUSED_PAD src0_sel:WORD_1
	v_pk_mul_f32 v[190:191], v[52:53], v[128:129] op_sel_hi:[1,0]
	v_pk_mul_f32 v[52:53], v[54:55], v[128:129] op_sel_hi:[1,0]
	v_pk_mul_f32 v[192:193], v[48:49], v[128:129] op_sel_hi:[1,0]
	v_pk_mul_f32 v[48:49], v[50:51], v[128:129] op_sel_hi:[1,0]
	v_pk_fma_f32 v[52:53], v[70:71], v[52:53], v[140:141]
	v_pk_fma_f32 v[54:55], v[68:69], v[190:191], v[138:139]
	v_pk_fma_f32 v[48:49], v[66:67], v[48:49], v[176:177]
	v_pk_fma_f32 v[50:51], v[64:65], v[192:193], v[174:175]
	v_cvt_pk_f16_f32 v138, v54, v55
	v_cvt_pk_f16_f32 v139, v52, v53
	v_cvt_pk_f16_f32 v140, v50, v51
	v_cvt_pk_f16_f32 v141, v48, v49
	global_store_dwordx4 v[212:213], v[138:141], off offset:256
	s_nop 0
	v_cvt_f32_f16_e32 v174, v196
	v_cvt_f32_f16_e32 v138, v194
	v_cvt_f32_f16_sdwa v139, v194 dst_sel:DWORD dst_unused:UNUSED_PAD src0_sel:WORD_1
	v_cvt_f32_f16_e32 v140, v195
	v_cvt_f32_f16_sdwa v141, v195 dst_sel:DWORD dst_unused:UNUSED_PAD src0_sel:WORD_1
	v_cvt_f32_f16_e32 v176, v197
	v_cvt_f32_f16_sdwa v177, v197 dst_sel:DWORD dst_unused:UNUSED_PAD src0_sel:WORD_1
	v_fmamk_f32 v128, v165, 0x3b2aaaab, v227
	s_nop 1
	v_rsq_f32_e32 v128, v128
	v_cvt_f32_f16_sdwa v175, v196 dst_sel:DWORD dst_unused:UNUSED_PAD src0_sel:WORD_1
	v_pk_mul_f32 v[190:191], v[44:45], v[128:129] op_sel_hi:[1,0]
	v_pk_mul_f32 v[44:45], v[46:47], v[128:129] op_sel_hi:[1,0]
	v_pk_mul_f32 v[192:193], v[40:41], v[128:129] op_sel_hi:[1,0]
	v_pk_mul_f32 v[40:41], v[42:43], v[128:129] op_sel_hi:[1,0]
	v_pk_fma_f32 v[44:45], v[70:71], v[44:45], v[140:141]
	v_pk_fma_f32 v[46:47], v[68:69], v[190:191], v[138:139]
	v_pk_fma_f32 v[40:41], v[66:67], v[40:41], v[176:177]
	v_pk_fma_f32 v[42:43], v[64:65], v[192:193], v[174:175]
	v_cvt_pk_f16_f32 v138, v46, v47
	v_cvt_pk_f16_f32 v139, v44, v45
	v_cvt_pk_f16_f32 v140, v42, v43
	v_cvt_pk_f16_f32 v141, v40, v41
	global_store_dwordx4 v[214:215], v[138:141], off offset:256
	s_nop 0
	v_cvt_f32_f16_e32 v174, v244
	v_cvt_f32_f16_e32 v138, v242
; __device__ __forceinline__ unsigned pk_f16(float lo, float hi) { f32x2 v = {lo, hi}; f16x2_t h = __builtin_convertvector(v, f16x2_t); return __builtin_bit_cast(unsigned, h); }
; __device__ __forceinline__ f32x2 up_f16(unsigned w) { return __builtin_convertvector(__builtin_bit_cast(f16x2_t, w), f32x2); }
;     __device__ __forceinline__ void operator()(const f32x4 (&acc)[2][2][4][2], const Unit& u, int wr, int wc, int fr, int fq) const {
;     ...
;                 for (int m = 0; m < 4; ++m) { const size_t off = (size_t)(row0 + ai * HALF + m * 16) * 1024 + col0 + bj * HALF;
;                     float rc = 1.0f; if constexpr (GN) rc = rsqrtf(gss[2 * 32768 + row0 + ai * HALF + m * 16] * (1.0f / 384.0f) + 1e-6f);
;                     const u32x4 q = pq[ai][m];
;                     const f32x2 qa_ = up_f16(q.x), qb_ = up_f16(q.y), qc_ = up_f16(q.z), qd_ = up_f16(q.w);
;                     const f32x4 x0 = (f32x4){qa_[0], qa_[1], qb_[0], qb_[1]} + gv[0] * (acc[ai][bj][m][0] * rc),
;                                 x1 = (f32x4){qc_[0], qc_[1], qd_[0], qd_[1]} + gv[1] * (acc[ai][bj][m][1] * rc);
;                     { u32x4 wx; wx.x = pk_f16(x0[0], x0[1]); wx.y = pk_f16(x0[2], x0[3]); wx.z = pk_f16(x1[0], x1[1]); wx.w = pk_f16(x1[2], x1[3]); *(u32x4*)(out + off) = wx; }
;                     ss[ai][m] += ((x0[0] * x0[0] + x0[1] * x0[1]) + (x0[2] * x0[2] + x0[3] * x0[3])) + ((x1[0] * x1[0] + x1[1] * x1[1]) + (x1[2] * x1[2] + x1[3] * x1[3]));
;                 }
;                 asm volatile("" ::: "memory");
;             }
;         }
; #pragma unroll
;         for (int ai = 0; ai < 2; ++ai)
; #pragma unroll
;             for (int m = 0; m < 4; ++m) { float t = ss[ai][m]; t += __shfl_xor(t, 16); t += __shfl_xor(t, 32);
;                 if (fq == 0) atomicAdd(rowss + row0 + ai * HALF + m * 16, t); }
	v_cvt_f32_f16_sdwa v139, v242 dst_sel:DWORD dst_unused:UNUSED_PAD src0_sel:WORD_1
	v_cvt_f32_f16_e32 v140, v243
	v_cvt_f32_f16_sdwa v141, v243 dst_sel:DWORD dst_unused:UNUSED_PAD src0_sel:WORD_1
	v_cvt_f32_f16_e32 v176, v245
	v_cvt_f32_f16_sdwa v177, v245 dst_sel:DWORD dst_unused:UNUSED_PAD src0_sel:WORD_1
	v_fmamk_f32 v128, v167, 0x3b2aaaab, v227
	s_nop 1
	v_rsq_f32_e32 v128, v128
	v_cvt_f32_f16_sdwa v175, v244 dst_sel:DWORD dst_unused:UNUSED_PAD src0_sel:WORD_1
	v_pk_mul_f32 v[190:191], v[36:37], v[128:129] op_sel_hi:[1,0]
	v_pk_mul_f32 v[36:37], v[38:39], v[128:129] op_sel_hi:[1,0]
	v_pk_mul_f32 v[192:193], v[32:33], v[128:129] op_sel_hi:[1,0]
	v_pk_mul_f32 v[32:33], v[34:35], v[128:129] op_sel_hi:[1,0]
	v_pk_fma_f32 v[36:37], v[70:71], v[36:37], v[140:141]
	v_pk_fma_f32 v[38:39], v[68:69], v[190:191], v[138:139]
	v_pk_fma_f32 v[32:33], v[66:67], v[32:33], v[176:177]
	v_pk_fma_f32 v[34:35], v[64:65], v[192:193], v[174:175]
	v_cvt_pk_f16_f32 v138, v38, v39
	v_cvt_pk_f16_f32 v139, v36, v37
	v_cvt_pk_f16_f32 v140, v34, v35
	v_cvt_pk_f16_f32 v141, v32, v33
	global_store_dwordx4 v[158:159], v[138:141], off offset:256
	s_nop 0
	v_fmamk_f32 v128, v169, 0x3b2aaaab, v227
	v_cvt_f32_f16_e32 v138, v84
	v_cvt_f32_f16_sdwa v139, v84 dst_sel:DWORD dst_unused:UNUSED_PAD src0_sel:WORD_1
	v_rsq_f32_e32 v128, v128
	v_cvt_f32_f16_e32 v84, v85
	v_cvt_f32_f16_sdwa v85, v85 dst_sel:DWORD dst_unused:UNUSED_PAD src0_sel:WORD_1
	v_cvt_f32_f16_e32 v140, v86
	v_cvt_f32_f16_sdwa v141, v86 dst_sel:DWORD dst_unused:UNUSED_PAD src0_sel:WORD_1
	v_cvt_f32_f16_e32 v86, v87
	v_cvt_f32_f16_sdwa v87, v87 dst_sel:DWORD dst_unused:UNUSED_PAD src0_sel:WORD_1
	v_pk_mul_f32 v[158:159], v[28:29], v[128:129] op_sel_hi:[1,0]
	v_pk_mul_f32 v[28:29], v[30:31], v[128:129] op_sel_hi:[1,0]
	v_pk_mul_f32 v[174:175], v[24:25], v[128:129] op_sel_hi:[1,0]
	v_pk_mul_f32 v[24:25], v[26:27], v[128:129] op_sel_hi:[1,0]
	v_pk_fma_f32 v[28:29], v[70:71], v[28:29], v[84:85]
	v_pk_fma_f32 v[30:31], v[68:69], v[158:159], v[138:139]
	v_pk_fma_f32 v[24:25], v[66:67], v[24:25], v[86:87]
	v_pk_fma_f32 v[26:27], v[64:65], v[174:175], v[140:141]
	v_cvt_pk_f16_f32 v84, v30, v31
	v_cvt_pk_f16_f32 v85, v28, v29
	v_cvt_pk_f16_f32 v86, v26, v27
	v_cvt_pk_f16_f32 v87, v24, v25
	global_store_dwordx4 v[218:219], v[84:87], off offset:256
	s_nop 0
	s_nop 0
	v_cvt_f32_f16_e32 v84, v80
	v_cvt_f32_f16_sdwa v85, v80 dst_sel:DWORD dst_unused:UNUSED_PAD src0_sel:WORD_1
	v_cvt_f32_f16_e32 v80, v81
	v_cvt_f32_f16_sdwa v81, v81 dst_sel:DWORD dst_unused:UNUSED_PAD src0_sel:WORD_1
	v_cvt_f32_f16_e32 v86, v82
	v_fmamk_f32 v87, v171, 0x3b2aaaab, v227
	s_nop 1
	v_rsq_f32_e32 v128, v87
	v_cvt_f32_f16_sdwa v87, v82 dst_sel:DWORD dst_unused:UNUSED_PAD src0_sel:WORD_1
	v_cvt_f32_f16_e32 v82, v83
	v_cvt_f32_f16_sdwa v83, v83 dst_sel:DWORD dst_unused:UNUSED_PAD src0_sel:WORD_1
	v_pk_mul_f32 v[138:139], v[20:21], v[128:129] op_sel_hi:[1,0]
	v_pk_mul_f32 v[20:21], v[22:23], v[128:129] op_sel_hi:[1,0]
	v_pk_mul_f32 v[140:141], v[16:17], v[128:129] op_sel_hi:[1,0]
	v_pk_mul_f32 v[16:17], v[18:19], v[128:129] op_sel_hi:[1,0]
	v_pk_fma_f32 v[20:21], v[70:71], v[20:21], v[80:81]
	v_pk_fma_f32 v[22:23], v[68:69], v[138:139], v[84:85]
	v_pk_fma_f32 v[16:17], v[66:67], v[16:17], v[82:83]
	v_pk_fma_f32 v[18:19], v[64:65], v[140:141], v[86:87]
	v_cvt_pk_f16_f32 v80, v22, v23
	v_cvt_pk_f16_f32 v81, v20, v21
	v_cvt_pk_f16_f32 v82, v18, v19
	v_cvt_pk_f16_f32 v83, v16, v17
	global_store_dwordx4 v[220:221], v[80:83], off offset:256
	s_nop 0
	s_nop 0
	v_cvt_f32_f16_e32 v80, v76
	v_cvt_f32_f16_sdwa v81, v76 dst_sel:DWORD dst_unused:UNUSED_PAD src0_sel:WORD_1
	v_cvt_f32_f16_e32 v76, v77
	v_cvt_f32_f16_sdwa v77, v77 dst_sel:DWORD dst_unused:UNUSED_PAD src0_sel:WORD_1
	v_cvt_f32_f16_e32 v82, v78
	v_fmamk_f32 v83, v173, 0x3b2aaaab, v227
	v_mov_b32_e32 v163, v129
	v_mov_b32_e32 v165, v129
	v_mov_b32_e32 v167, v129
	v_mov_b32_e32 v169, v129
	v_mov_b32_e32 v171, v129
	v_mov_b32_e32 v173, v129
	s_nop 1
	v_rsq_f32_e32 v84, v83
	v_cvt_f32_f16_sdwa v83, v78 dst_sel:DWORD dst_unused:UNUSED_PAD src0_sel:WORD_1
	v_cvt_f32_f16_e32 v78, v79
	v_cvt_f32_f16_sdwa v79, v79 dst_sel:DWORD dst_unused:UNUSED_PAD src0_sel:WORD_1
	v_pk_mul_f32 v[86:87], v[12:13], v[84:85] op_sel_hi:[1,0]
	v_pk_mul_f32 v[12:13], v[14:15], v[84:85] op_sel_hi:[1,0]
	v_pk_mul_f32 v[138:139], v[8:9], v[84:85] op_sel_hi:[1,0]
	v_pk_mul_f32 v[8:9], v[10:11], v[84:85] op_sel_hi:[1,0]
	v_pk_fma_f32 v[12:13], v[70:71], v[12:13], v[76:77]
	v_pk_fma_f32 v[14:15], v[68:69], v[86:87], v[80:81]
	v_pk_fma_f32 v[8:9], v[66:67], v[8:9], v[78:79]
	v_pk_fma_f32 v[10:11], v[64:65], v[138:139], v[82:83]
	v_cvt_pk_f16_f32 v76, v14, v15
	v_cvt_pk_f16_f32 v77, v12, v13
	v_cvt_pk_f16_f32 v78, v10, v11
	v_cvt_pk_f16_f32 v79, v8, v9
	global_store_dwordx4 v[222:223], v[76:79], off offset:256
	global_load_dword v82, v[188:189], off offset:704
	v_mul_f32_e32 v80, v127, v127
	v_and_b32_e32 v77, 64, v230
	v_xor_b32_e32 v76, 16, v230
	v_add_u32_e32 v77, 64, v77
	v_xor_b32_e32 v78, 32, v230
	v_cmp_lt_i32_e32 vcc, v76, v77
	v_mul_f32_e32 v79, v121, v121
	v_mul_f32_e32 v81, v123, v123
	v_cndmask_b32_e32 v76, v230, v76, vcc
	v_cmp_lt_i32_e32 vcc, v78, v77
	v_lshlrev_b32_e32 v77, 2, v76
	v_fmac_f32_e32 v79, v120, v120
	v_cndmask_b32_e32 v78, v230, v78, vcc
	v_lshlrev_b32_e32 v76, 2, v78
	v_mul_f32_e32 v78, v125, v125
	v_fmac_f32_e32 v78, v124, v124
	v_fmac_f32_e32 v80, v126, v126
	v_fmac_f32_e32 v81, v122, v122
	v_add_f32_e32 v78, v78, v79
	v_add_f32_e32 v79, v80, v81
	v_add_f32_e32 v83, v78, v79
	v_add_f32_e32 v56, v83, v56
	v_mov_b32_e32 v57, v56
	s_nop 1
	v_permlane16_swap_b32_e32 v57, v56
	v_cvt_f32_f16_e32 v78, v72
	v_cvt_f32_f16_sdwa v79, v72 dst_sel:DWORD dst_unused:UNUSED_PAD src0_sel:WORD_1
	v_cvt_f32_f16_e32 v72, v73
	v_cvt_f32_f16_sdwa v73, v73 dst_sel:DWORD dst_unused:UNUSED_PAD src0_sel:WORD_1
	v_cvt_f32_f16_e32 v80, v74
	v_cvt_f32_f16_sdwa v81, v74 dst_sel:DWORD dst_unused:UNUSED_PAD src0_sel:WORD_1
	s_waitcnt vmcnt(0)
	v_fmamk_f32 v58, v82, 0x3b2aaaab, v227
	s_nop 1
	v_rsq_f32_e32 v59, v58
	s_waitcnt lgkmcnt(0)
	v_add_f32_e32 v58, v56, v57
	v_mov_b32_e32 v56, v59
	v_pk_mul_f32 v[4:5], v[4:5], v[56:57] op_sel_hi:[1,0]
	v_pk_mul_f32 v[6:7], v[6:7], v[56:57] op_sel_hi:[1,0]
	v_pk_mul_f32 v[0:1], v[0:1], v[56:57] op_sel_hi:[1,0]
	v_pk_mul_f32 v[2:3], v[2:3], v[56:57] op_sel_hi:[1,0]
	v_pk_fma_f32 v[6:7], v[70:71], v[6:7], v[72:73]
	v_pk_fma_f32 v[56:57], v[68:69], v[4:5], v[78:79]
	v_pk_fma_f32 v[2:3], v[66:67], v[2:3], v[60:61]
	v_pk_fma_f32 v[4:5], v[64:65], v[0:1], v[80:81]
	v_cvt_pk_f16_f32 v60, v56, v57
	v_cvt_pk_f16_f32 v61, v6, v7
	v_cvt_pk_f16_f32 v62, v4, v5
	v_cvt_pk_f16_f32 v63, v2, v3
	v_mov_b32_e32 v59, v58
	s_nop 1
	v_permlane32_swap_b32_e32 v59, v58
	global_store_dwordx4 v[160:161], v[60:63], off offset:256
	v_lshl_add_u64 v[0:1], v[186:187], 2, s[46:47]
	s_and_saveexec_b64 s[0:1], s[40:41]
	s_cbranch_execz .LBB0_808
	s_waitcnt lgkmcnt(0)
	v_add_f32_e32 v58, v58, v59
	global_atomic_add_f32 v[0:1], v58, off
;     __device__ __forceinline__ void operator()(const f32x4 (&acc)[2][2][4][2], const Unit& u, int wr, int wc, int fr, int fq) const {
;     ...
;                     ss[ai][m] += ((x0[0] * x0[0] + x0[1] * x0[1]) + (x0[2] * x0[2] + x0[3] * x0[3])) + ((x1[0] * x1[0] + x1[1] * x1[1]) + (x1[2] * x1[2] + x1[3] * x1[3]));
;                 }
;                 asm volatile("" ::: "memory");
;             }
;         }
; #pragma unroll
;         for (int ai = 0; ai < 2; ++ai)
; #pragma unroll
;             for (int m = 0; m < 4; ++m) { float t = ss[ai][m]; t += __shfl_xor(t, 16); t += __shfl_xor(t, 32);
;                 if (fq == 0) atomicAdd(rowss + row0 + ai * HALF + m * 16, t); }
.LBB0_808:
	s_or_b64 exec, exec, s[0:1]
	v_mul_f32_e32 v58, v119, v119
	s_waitcnt lgkmcnt(0)
	v_mul_f32_e32 v59, v117, v117
	v_fmac_f32_e32 v58, v118, v118
	v_fmac_f32_e32 v59, v116, v116
	v_add_f32_e32 v58, v58, v59
	v_mul_f32_e32 v59, v115, v115
	v_mul_f32_e32 v60, v113, v113
	v_mul_f32_e32 v55, v55, v55
	v_mul_f32_e32 v53, v53, v53
	v_mul_f32_e32 v51, v51, v51
	v_mul_f32_e32 v49, v49, v49
	v_fmac_f32_e32 v59, v114, v114
	v_fmac_f32_e32 v60, v112, v112
	v_fmac_f32_e32 v55, v54, v54
	v_fmac_f32_e32 v53, v52, v52
	v_fmac_f32_e32 v51, v50, v50
	v_fmac_f32_e32 v49, v48, v48
	v_add_f32_e32 v59, v59, v60
	v_add_f32_e32 v52, v55, v53
	v_add_f32_e32 v48, v51, v49
	v_add_f32_e32 v58, v58, v59
	v_add_f32_e32 v48, v52, v48
	v_add_f32_e32 v48, v58, v48
	v_mov_b32_e32 v49, v48
	s_nop 1
	v_permlane16_swap_b32_e32 v49, v48
	s_waitcnt lgkmcnt(0)
	v_add_f32_e32 v48, v48, v49
	v_mov_b32_e32 v49, v48
	s_nop 1
	v_permlane32_swap_b32_e32 v49, v48
	s_and_saveexec_b64 s[0:1], s[40:41]
	s_cbranch_execz .LBB0_810
	s_waitcnt lgkmcnt(0)
	v_add_f32_e32 v48, v48, v49
	global_atomic_add_f32 v[0:1], v48, off offset:64
.LBB0_810:
	s_or_b64 exec, exec, s[0:1]
	v_mul_f32_e32 v48, v111, v111
	s_waitcnt lgkmcnt(0)
	v_mul_f32_e32 v49, v109, v109
	v_fmac_f32_e32 v48, v110, v110
	v_fmac_f32_e32 v49, v108, v108
	v_add_f32_e32 v48, v48, v49
	v_mul_f32_e32 v49, v107, v107
	v_mul_f32_e32 v50, v105, v105
	v_mul_f32_e32 v47, v47, v47
	v_mul_f32_e32 v45, v45, v45
	v_mul_f32_e32 v43, v43, v43
	v_mul_f32_e32 v41, v41, v41
	v_fmac_f32_e32 v49, v106, v106
	v_fmac_f32_e32 v50, v104, v104
	v_fmac_f32_e32 v47, v46, v46
	v_fmac_f32_e32 v45, v44, v44
	v_fmac_f32_e32 v43, v42, v42
	v_fmac_f32_e32 v41, v40, v40
	v_add_f32_e32 v49, v49, v50
	v_add_f32_e32 v44, v47, v45
	v_add_f32_e32 v40, v43, v41
	v_add_f32_e32 v48, v48, v49
	v_add_f32_e32 v40, v44, v40
	v_add_f32_e32 v40, v48, v40
	v_mov_b32_e32 v41, v40
	s_nop 1
	v_permlane16_swap_b32_e32 v41, v40
	s_waitcnt lgkmcnt(0)
	v_add_f32_e32 v40, v40, v41
	v_mov_b32_e32 v41, v40
	s_nop 1
	v_permlane32_swap_b32_e32 v41, v40
	s_and_saveexec_b64 s[0:1], s[40:41]
	s_cbranch_execz .LBB0_812
	s_waitcnt lgkmcnt(0)
	v_add_f32_e32 v40, v40, v41
	global_atomic_add_f32 v[0:1], v40, off offset:128
.LBB0_812:
	s_or_b64 exec, exec, s[0:1]
	v_mul_f32_e32 v40, v103, v103
	s_waitcnt lgkmcnt(0)
	v_mul_f32_e32 v41, v101, v101
	v_fmac_f32_e32 v40, v102, v102
	v_fmac_f32_e32 v41, v100, v100
	v_add_f32_e32 v40, v40, v41
	v_mul_f32_e32 v41, v99, v99
	v_mul_f32_e32 v42, v97, v97
	v_mul_f32_e32 v39, v39, v39
	v_mul_f32_e32 v37, v37, v37
	v_mul_f32_e32 v35, v35, v35
	v_mul_f32_e32 v33, v33, v33
	v_fmac_f32_e32 v41, v98, v98
	v_fmac_f32_e32 v42, v96, v96
	v_fmac_f32_e32 v39, v38, v38
	v_fmac_f32_e32 v37, v36, v36
	v_fmac_f32_e32 v35, v34, v34
	v_fmac_f32_e32 v33, v32, v32
	v_add_f32_e32 v41, v41, v42
	v_add_f32_e32 v36, v39, v37
	v_add_f32_e32 v32, v35, v33
	v_add_f32_e32 v40, v40, v41
	v_add_f32_e32 v32, v36, v32
	v_add_f32_e32 v32, v40, v32
	v_mov_b32_e32 v33, v32
	s_nop 1
	v_permlane16_swap_b32_e32 v33, v32
	s_waitcnt lgkmcnt(0)
	v_add_f32_e32 v32, v32, v33
	v_mov_b32_e32 v33, v32
	s_nop 1
	v_permlane32_swap_b32_e32 v33, v32
	s_and_saveexec_b64 s[0:1], s[40:41]
	s_cbranch_execz .LBB0_814
	s_waitcnt lgkmcnt(0)
	v_add_f32_e32 v32, v32, v33
	global_atomic_add_f32 v[0:1], v32, off offset:192
;     __device__ __forceinline__ void operator()(const f32x4 (&acc)[2][2][4][2], const Unit& u, int wr, int wc, int fr, int fq) const {
;     ...
;                     ss[ai][m] += ((x0[0] * x0[0] + x0[1] * x0[1]) + (x0[2] * x0[2] + x0[3] * x0[3])) + ((x1[0] * x1[0] + x1[1] * x1[1]) + (x1[2] * x1[2] + x1[3] * x1[3]));
;                 }
;                 asm volatile("" ::: "memory");
;             }
;         }
; #pragma unroll
;         for (int ai = 0; ai < 2; ++ai)
; #pragma unroll
;             for (int m = 0; m < 4; ++m) { float t = ss[ai][m]; t += __shfl_xor(t, 16); t += __shfl_xor(t, 32);
;                 if (fq == 0) atomicAdd(rowss + row0 + ai * HALF + m * 16, t); }
.LBB0_814:
	s_or_b64 exec, exec, s[0:1]
	v_mul_f32_e32 v32, v95, v95
	s_waitcnt lgkmcnt(0)
	v_mul_f32_e32 v33, v93, v93
	v_fmac_f32_e32 v32, v94, v94
	v_fmac_f32_e32 v33, v92, v92
	v_add_f32_e32 v32, v32, v33
	v_mul_f32_e32 v33, v91, v91
	v_mul_f32_e32 v34, v89, v89
	v_mul_f32_e32 v31, v31, v31
	v_mul_f32_e32 v29, v29, v29
	v_mul_f32_e32 v27, v27, v27
	v_mul_f32_e32 v25, v25, v25
	v_fmac_f32_e32 v33, v90, v90
	v_fmac_f32_e32 v34, v88, v88
	v_fmac_f32_e32 v31, v30, v30
	v_fmac_f32_e32 v29, v28, v28
	v_fmac_f32_e32 v27, v26, v26
	v_fmac_f32_e32 v25, v24, v24
	v_add_f32_e32 v33, v33, v34
	v_add_f32_e32 v28, v31, v29
	v_add_f32_e32 v24, v27, v25
	v_add_f32_e32 v32, v32, v33
	v_add_f32_e32 v24, v28, v24
	v_add_f32_e32 v24, v32, v24
	v_mov_b32_e32 v25, v24
	s_nop 1
	v_permlane16_swap_b32_e32 v25, v24
	s_waitcnt lgkmcnt(0)
	v_add_f32_e32 v24, v24, v25
	v_mov_b32_e32 v25, v24
	s_nop 1
	v_permlane32_swap_b32_e32 v25, v24
	s_and_saveexec_b64 s[0:1], s[40:41]
	s_cbranch_execz .LBB0_816
	s_waitcnt lgkmcnt(0)
	v_add_f32_e32 v24, v24, v25
	global_atomic_add_f32 v[0:1], v24, off offset:512
.LBB0_816:
	s_or_b64 exec, exec, s[0:1]
	v_mul_f32_e32 v24, v153, v153
	s_waitcnt lgkmcnt(0)
	v_mul_f32_e32 v25, v151, v151
	v_fmac_f32_e32 v24, v152, v152
	v_fmac_f32_e32 v25, v150, v150
	v_add_f32_e32 v24, v24, v25
	v_mul_f32_e32 v25, v149, v149
	v_mul_f32_e32 v26, v147, v147
	v_mul_f32_e32 v23, v23, v23
	v_mul_f32_e32 v21, v21, v21
	v_mul_f32_e32 v19, v19, v19
	v_mul_f32_e32 v17, v17, v17
	v_fmac_f32_e32 v25, v148, v148
	v_fmac_f32_e32 v26, v146, v146
	v_fmac_f32_e32 v23, v22, v22
	v_fmac_f32_e32 v21, v20, v20
	v_fmac_f32_e32 v19, v18, v18
	v_fmac_f32_e32 v17, v16, v16
	v_add_f32_e32 v25, v25, v26
	v_add_f32_e32 v20, v23, v21
	v_add_f32_e32 v16, v19, v17
	v_add_f32_e32 v24, v24, v25
	v_add_f32_e32 v16, v20, v16
	v_add_f32_e32 v16, v24, v16
	v_mov_b32_e32 v17, v16
	s_nop 1
	v_permlane16_swap_b32_e32 v17, v16
	s_waitcnt lgkmcnt(0)
	v_add_f32_e32 v16, v16, v17
	v_mov_b32_e32 v17, v16
	s_nop 1
	v_permlane32_swap_b32_e32 v17, v16
	s_and_saveexec_b64 s[0:1], s[40:41]
	s_cbranch_execz .LBB0_818
	s_waitcnt lgkmcnt(0)
	v_add_f32_e32 v16, v16, v17
	global_atomic_add_f32 v[0:1], v16, off offset:576
.LBB0_818:
	s_or_b64 exec, exec, s[0:1]
	v_mul_f32_e32 v16, v157, v157
	s_waitcnt lgkmcnt(0)
	v_mul_f32_e32 v17, v155, v155
	v_fmac_f32_e32 v16, v156, v156
	v_fmac_f32_e32 v17, v154, v154
	v_add_f32_e32 v16, v16, v17
	v_mul_f32_e32 v17, v145, v145
	v_mul_f32_e32 v18, v143, v143
	v_mul_f32_e32 v15, v15, v15
	v_mul_f32_e32 v13, v13, v13
	v_mul_f32_e32 v11, v11, v11
	v_mul_f32_e32 v9, v9, v9
	v_fmac_f32_e32 v17, v144, v144
	v_fmac_f32_e32 v18, v142, v142
	v_fmac_f32_e32 v15, v14, v14
	v_fmac_f32_e32 v13, v12, v12
	v_fmac_f32_e32 v11, v10, v10
	v_fmac_f32_e32 v9, v8, v8
	v_add_f32_e32 v17, v17, v18
	v_add_f32_e32 v12, v15, v13
	v_add_f32_e32 v8, v11, v9
	v_add_f32_e32 v16, v16, v17
	v_add_f32_e32 v8, v12, v8
	v_add_f32_e32 v8, v16, v8
	v_mov_b32_e32 v9, v8
	s_nop 1
	v_permlane16_swap_b32_e32 v9, v8
	s_waitcnt lgkmcnt(0)
	v_add_f32_e32 v8, v8, v9
	v_mov_b32_e32 v9, v8
	s_nop 1
	v_permlane32_swap_b32_e32 v9, v8
	s_and_saveexec_b64 s[0:1], s[40:41]
	s_cbranch_execz .LBB0_820
	s_waitcnt lgkmcnt(0)
	v_add_f32_e32 v8, v8, v9
	global_atomic_add_f32 v[0:1], v8, off offset:640
.LBB0_820:
	s_or_b64 exec, exec, s[0:1]
	v_mul_f32_e32 v8, v135, v135
	s_waitcnt lgkmcnt(0)
	v_mul_f32_e32 v9, v137, v137
	v_fmac_f32_e32 v8, v134, v134
	v_fmac_f32_e32 v9, v136, v136
	v_add_f32_e32 v8, v8, v9
	v_mul_f32_e32 v9, v131, v131
	v_mul_f32_e32 v10, v133, v133
	v_fmac_f32_e32 v9, v130, v130
	v_fmac_f32_e32 v10, v132, v132
	v_add_f32_e32 v9, v9, v10
	v_add_f32_e32 v8, v8, v9
	v_mul_f32_e32 v9, v57, v57
	v_mul_f32_e32 v7, v7, v7
	v_mul_f32_e32 v5, v5, v5
	v_mul_f32_e32 v3, v3, v3
	v_fmac_f32_e32 v9, v56, v56
	v_fmac_f32_e32 v7, v6, v6
	v_fmac_f32_e32 v5, v4, v4
	v_fmac_f32_e32 v3, v2, v2
	v_add_f32_e32 v6, v9, v7
	v_add_f32_e32 v2, v5, v3
	v_add_f32_e32 v2, v6, v2
	v_add_f32_e32 v2, v8, v2
	v_mov_b32_e32 v3, v2
	s_nop 1
	v_permlane16_swap_b32_e32 v3, v2
	s_waitcnt lgkmcnt(0)
	v_add_f32_e32 v2, v2, v3
	v_mov_b32_e32 v3, v2
	s_nop 1
	v_permlane32_swap_b32_e32 v3, v2
	s_and_saveexec_b64 s[0:1], s[40:41]
	s_cbranch_execz .LBB0_822
	s_waitcnt lgkmcnt(0)
	v_add_f32_e32 v2, v2, v3
	global_atomic_add_f32 v[0:1], v2, off offset:704

; __device__ __forceinline__ unsigned pk_f16(float lo, float hi) { f32x2 v = {lo, hi}; f16x2_t h = __builtin_convertvector(v, f16x2_t); return __builtin_bit_cast(unsigned, h); }
;     __device__ __forceinline__ void operator()(const f32x4 (&acc)[2][2][4][2], const Unit& u, int wr, int wc, int fr, int fq) const {
;         const int row0 = u.pm * BM + wr * 64 + fr; const int b = (u.pm * BM) >> 14;
;         int fqo = fq; asm volatile("" : "+v"(fqo));
;         const int col0 = u.pn * BM + wc * 32 + 8 * fqo;
;         float ss[2][4];
; #pragma unroll
;         for (int ai = 0; ai < 2; ++ai)
; #pragma unroll
;             for (int m = 0; m < 4; ++m) ss[ai][m] = 0.f;
; #pragma unroll
;         for (int bj = 0; bj < 2; ++bj) {
;             f32x4 gv[2];
; #pragma unroll
;             for (int n = 0; n < 2; ++n) gv[n] = *(const f32x4*)(gate + (size_t)b * gstride + col0 + bj * HALF + 4 * n);
;             u32x4 pq[2][4];
; #pragma unroll
;             for (int ai = 0; ai < 2; ++ai)
; #pragma unroll
;                 for (int m = 0; m < 4; ++m) pq[ai][m] = *(const u32x4*)(base + (size_t)(row0 + ai * HALF + m * 16) * 1024 + col0 + bj * HALF);
;             asm volatile("" ::: "memory");
; #pragma unroll
;             for (int ai = 0; ai < 2; ++ai) {
; #pragma unroll
;                 for (int m = 0; m < 4; ++m) { const size_t off = (size_t)(row0 + ai * HALF + m * 16) * 1024 + col0 + bj * HALF;
;                     float rc = 1.0f; if constexpr (GN) rc = rsqrtf(gss[2 * 32768 + row0 + ai * HALF + m * 16] * (1.0f / 384.0f) + 1e-6f);
;                     const u32x4 q = pq[ai][m];
;                     const f32x2 qa_ = up_f16(q.x), qb_ = up_f16(q.y), qc_ = up_f16(q.z), qd_ = up_f16(q.w);
;                     const f32x4 x0 = (f32x4){qa_[0], qa_[1], qb_[0], qb_[1]} + gv[0] * (acc[ai][bj][m][0] * rc),
;                                 x1 = (f32x4){qc_[0], qc_[1], qd_[0], qd_[1]} + gv[1] * (acc[ai][bj][m][1] * rc);
;                     { u32x4 wx; wx.x = pk_f16(x0[0], x0[1]); wx.y = pk_f16(x0[2], x0[3]); wx.z = pk_f16(x1[0], x1[1]); wx.w = pk_f16(x1[2], x1[3]); *(u32x4*)(out + off) = wx; }
;                     ss[ai][m] += ((x0[0] * x0[0] + x0[1] * x0[1]) + (x0[2] * x0[2] + x0[3] * x0[3])) + ((x1[0] * x1[0] + x1[1] * x1[1]) + (x1[2] * x1[2] + x1[3] * x1[3]));
.LBB0_1000:
	s_lshl_b32 s5, s56, 8
	v_mov_b32_e32 v130, v222
	s_ashr_i32 s4, s57, 6
	s_or_b32 s5, s5, s21
	v_lshl_add_u32 v172, s57, 8, v223
	v_lshl_add_u32 v138, v130, 3, s5
	s_mul_hi_i32 s5, s4, 0x6000
	s_mulk_i32 s4, 0x6000
	v_ashrrev_i32_e32 v139, 31, v138
	s_add_u32 s4, s15, s4
	v_ashrrev_i32_e32 v173, 31, v172
	s_addc_u32 s5, s20, s5
	v_lshlrev_b64 v[196:197], 1, v[138:139]
	v_lshlrev_b64 v[208:209], 11, v[172:173]
	v_lshl_add_u64 v[186:187], v[138:139], 2, s[4:5]
	v_lshl_add_u64 v[138:139], s[96:97], 0, v[196:197]
	v_lshl_add_u64 v[192:193], v[138:139], 0, v[208:209]
	global_load_dwordx4 v[130:133], v[186:187], off offset:16
	global_load_dwordx4 v[134:137], v[186:187], off
	global_load_dwordx4 v[238:241], v[192:193], off
	v_or_b32_e32 v140, 16, v172
	v_ashrrev_i32_e32 v141, 31, v140
	v_lshlrev_b64 v[216:217], 11, v[140:141]
	v_lshl_add_u64 v[188:189], v[138:139], 0, v[216:217]
	global_load_dwordx4 v[242:245], v[188:189], off
	v_or_b32_e32 v140, 32, v172
	v_ashrrev_i32_e32 v141, 31, v140
	v_lshlrev_b64 v[220:221], 11, v[140:141]
	v_lshl_add_u64 v[194:195], v[138:139], 0, v[220:221]
	global_load_dwordx4 v[158:161], v[194:195], off
	v_or_b32_e32 v140, 48, v172
	v_ashrrev_i32_e32 v141, 31, v140
	v_lshlrev_b64 v[218:219], 11, v[140:141]
	v_lshl_add_u64 v[204:205], v[138:139], 0, v[218:219]
	global_load_dwordx4 v[154:157], v[204:205], off
	s_mov_b64 s[48:49], 0x40000
	v_lshl_add_u64 v[206:207], v[208:209], 0, s[48:49]
	v_lshl_add_u64 v[190:191], v[138:139], 0, v[206:207]
	global_load_dwordx4 v[150:153], v[190:191], off
	s_mov_b64 s[4:5], 0x48000
	v_lshl_add_u64 v[214:215], v[208:209], 0, s[4:5]
	v_lshl_add_u64 v[198:199], v[138:139], 0, v[214:215]
	global_load_dwordx4 v[146:149], v[198:199], off
	s_mov_b64 s[4:5], 0x50000
	v_lshl_add_u64 v[212:213], v[208:209], 0, s[4:5]
	v_lshl_add_u64 v[200:201], v[138:139], 0, v[212:213]
	global_load_dwordx4 v[142:145], v[200:201], off
	s_mov_b64 s[4:5], 0x58000
	v_lshl_add_u64 v[210:211], v[208:209], 0, s[4:5]
	v_lshl_add_u64 v[202:203], v[138:139], 0, v[210:211]
	global_load_dwordx4 v[138:141], v[202:203], off
	v_lshl_add_u64 v[208:209], s[96:97], 0, v[208:209]
	v_lshl_add_u64 v[208:209], v[208:209], 0, v[196:197]
	s_waitcnt vmcnt(0)
	v_cvt_f32_f16_e32 v174, v238
	v_cvt_f32_f16_sdwa v175, v238 dst_sel:DWORD dst_unused:UNUSED_PAD src0_sel:WORD_1
	v_cvt_f32_f16_e32 v176, v239
	v_cvt_f32_f16_sdwa v177, v239 dst_sel:DWORD dst_unused:UNUSED_PAD src0_sel:WORD_1
	v_cvt_f32_f16_e32 v238, v240
	v_cvt_f32_f16_sdwa v239, v240 dst_sel:DWORD dst_unused:UNUSED_PAD src0_sel:WORD_1
	v_cvt_f32_f16_e32 v240, v241
	v_cvt_f32_f16_sdwa v241, v241 dst_sel:DWORD dst_unused:UNUSED_PAD src0_sel:WORD_1
	v_pk_fma_f32 v[126:127], v[126:127], v[136:137], v[176:177]
	v_pk_fma_f32 v[124:125], v[124:125], v[134:135], v[174:175]
	v_pk_fma_f32 v[176:177], v[120:121], v[130:131], v[238:239]
	v_pk_fma_f32 v[174:175], v[122:123], v[132:133], v[240:241]
	v_cvt_pk_f16_f32 v120, v124, v125
	v_cvt_pk_f16_f32 v121, v126, v127
	v_cvt_pk_f16_f32 v122, v176, v177
	v_cvt_pk_f16_f32 v123, v174, v175
	global_store_dwordx4 v[208:209], v[120:123], off
	s_nop 1
	v_mul_f32_e32 v120, v125, v125
	v_mul_f32_e32 v121, v127, v127
	v_fmac_f32_e32 v120, v124, v124
	v_fmac_f32_e32 v121, v126, v126
	v_add_f32_e32 v120, v120, v121
	v_mul_f32_e32 v121, v177, v177
	v_mul_f32_e32 v122, v175, v175
	v_fmac_f32_e32 v121, v176, v176
	v_fmac_f32_e32 v122, v174, v174
	v_add_f32_e32 v121, v121, v122
	v_add_f32_e32 v237, v120, v121
	v_cvt_f32_f16_e32 v120, v242
	v_cvt_f32_f16_sdwa v121, v242 dst_sel:DWORD dst_unused:UNUSED_PAD src0_sel:WORD_1
	v_cvt_f32_f16_e32 v122, v243
	v_cvt_f32_f16_sdwa v123, v243 dst_sel:DWORD dst_unused:UNUSED_PAD src0_sel:WORD_1
	v_cvt_f32_f16_e32 v124, v244
	v_cvt_f32_f16_sdwa v125, v244 dst_sel:DWORD dst_unused:UNUSED_PAD src0_sel:WORD_1
	v_cvt_f32_f16_e32 v126, v245
	v_cvt_f32_f16_sdwa v127, v245 dst_sel:DWORD dst_unused:UNUSED_PAD src0_sel:WORD_1
	v_pk_fma_f32 v[118:119], v[118:119], v[136:137], v[122:123]
	v_pk_fma_f32 v[116:117], v[116:117], v[134:135], v[120:121]
	v_pk_fma_f32 v[112:113], v[112:113], v[130:131], v[124:125]
	v_pk_fma_f32 v[114:115], v[114:115], v[132:133], v[126:127]
	v_lshl_add_u64 v[124:125], s[96:97], 0, v[216:217]
	v_cvt_pk_f16_f32 v120, v116, v117
	v_cvt_pk_f16_f32 v121, v118, v119
	v_cvt_pk_f16_f32 v122, v112, v113
	v_cvt_pk_f16_f32 v123, v114, v115
	v_lshl_add_u64 v[216:217], v[124:125], 0, v[196:197]
	global_store_dwordx4 v[216:217], v[120:123], off
	v_cvt_f32_f16_e32 v124, v160
	v_cvt_f32_f16_sdwa v125, v160 dst_sel:DWORD dst_unused:UNUSED_PAD src0_sel:WORD_1
	v_cvt_f32_f16_e32 v120, v158
	v_cvt_f32_f16_sdwa v121, v158 dst_sel:DWORD dst_unused:UNUSED_PAD src0_sel:WORD_1
	v_cvt_f32_f16_e32 v122, v159
	v_cvt_f32_f16_sdwa v123, v159 dst_sel:DWORD dst_unused:UNUSED_PAD src0_sel:WORD_1
	v_cvt_f32_f16_e32 v126, v161
	v_cvt_f32_f16_sdwa v127, v161 dst_sel:DWORD dst_unused:UNUSED_PAD src0_sel:WORD_1
	v_pk_fma_f32 v[158:159], v[108:109], v[134:135], v[120:121]
	v_pk_fma_f32 v[110:111], v[110:111], v[136:137], v[122:123]
	v_pk_fma_f32 v[124:125], v[104:105], v[130:131], v[124:125]
	v_pk_fma_f32 v[106:107], v[106:107], v[132:133], v[126:127]
	v_lshl_add_u64 v[104:105], s[96:97], 0, v[220:221]
	v_cvt_pk_f16_f32 v120, v158, v159
	v_cvt_pk_f16_f32 v121, v110, v111
	v_cvt_pk_f16_f32 v122, v124, v125
	v_cvt_pk_f16_f32 v123, v106, v107
	v_lshl_add_u64 v[160:161], v[104:105], 0, v[196:197]
	global_store_dwordx4 v[160:161], v[120:123], off
	v_cvt_f32_f16_e32 v104, v154
	v_cvt_f32_f16_sdwa v105, v154 dst_sel:DWORD dst_unused:UNUSED_PAD src0_sel:WORD_1
	v_cvt_f32_f16_e32 v108, v155
	v_cvt_f32_f16_sdwa v109, v155 dst_sel:DWORD dst_unused:UNUSED_PAD src0_sel:WORD_1
; __device__ __forceinline__ unsigned pk_f16(float lo, float hi) { f32x2 v = {lo, hi}; f16x2_t h = __builtin_convertvector(v, f16x2_t); return __builtin_bit_cast(unsigned, h); }
; __device__ __forceinline__ f32x2 up_f16(unsigned w) { return __builtin_convertvector(__builtin_bit_cast(f16x2_t, w), f32x2); }
;     __device__ __forceinline__ void operator()(const f32x4 (&acc)[2][2][4][2], const Unit& u, int wr, int wc, int fr, int fq) const {
;     ...
;         for (int bj = 0; bj < 2; ++bj) {
;             f32x4 gv[2];
; #pragma unroll
;             for (int n = 0; n < 2; ++n) gv[n] = *(const f32x4*)(gate + (size_t)b * gstride + col0 + bj * HALF + 4 * n);
;             u32x4 pq[2][4];
; #pragma unroll
;             for (int ai = 0; ai < 2; ++ai)
; #pragma unroll
;                 for (int m = 0; m < 4; ++m) pq[ai][m] = *(const u32x4*)(base + (size_t)(row0 + ai * HALF + m * 16) * 1024 + col0 + bj * HALF);
;             asm volatile("" ::: "memory");
; #pragma unroll
;             for (int ai = 0; ai < 2; ++ai) {
; #pragma unroll
;                 for (int m = 0; m < 4; ++m) { const size_t off = (size_t)(row0 + ai * HALF + m * 16) * 1024 + col0 + bj * HALF;
;                     float rc = 1.0f; if constexpr (GN) rc = rsqrtf(gss[2 * 32768 + row0 + ai * HALF + m * 16] * (1.0f / 384.0f) + 1e-6f);
;                     const u32x4 q = pq[ai][m];
;                     const f32x2 qa_ = up_f16(q.x), qb_ = up_f16(q.y), qc_ = up_f16(q.z), qd_ = up_f16(q.w);
;                     const f32x4 x0 = (f32x4){qa_[0], qa_[1], qb_[0], qb_[1]} + gv[0] * (acc[ai][bj][m][0] * rc),
;                                 x1 = (f32x4){qc_[0], qc_[1], qd_[0], qd_[1]} + gv[1] * (acc[ai][bj][m][1] * rc);
;                     { u32x4 wx; wx.x = pk_f16(x0[0], x0[1]); wx.y = pk_f16(x0[2], x0[3]); wx.z = pk_f16(x1[0], x1[1]); wx.w = pk_f16(x1[2], x1[3]); *(u32x4*)(out + off) = wx; }
	v_cvt_f32_f16_e32 v120, v156
	v_cvt_f32_f16_sdwa v121, v156 dst_sel:DWORD dst_unused:UNUSED_PAD src0_sel:WORD_1
	v_cvt_f32_f16_e32 v122, v157
	v_cvt_f32_f16_sdwa v123, v157 dst_sel:DWORD dst_unused:UNUSED_PAD src0_sel:WORD_1
	v_pk_fma_f32 v[102:103], v[102:103], v[136:137], v[108:109]
	v_pk_fma_f32 v[154:155], v[100:101], v[134:135], v[104:105]
	v_pk_fma_f32 v[108:109], v[96:97], v[130:131], v[120:121]
	v_pk_fma_f32 v[98:99], v[98:99], v[132:133], v[122:123]
	v_lshl_add_u64 v[96:97], s[96:97], 0, v[218:219]
	v_cvt_pk_f16_f32 v120, v154, v155
	v_cvt_pk_f16_f32 v121, v102, v103
	v_cvt_pk_f16_f32 v122, v108, v109
	v_cvt_pk_f16_f32 v123, v98, v99
	v_lshl_add_u64 v[156:157], v[96:97], 0, v[196:197]
	global_store_dwordx4 v[156:157], v[120:123], off
	v_cvt_f32_f16_e32 v96, v150
	v_cvt_f32_f16_sdwa v97, v150 dst_sel:DWORD dst_unused:UNUSED_PAD src0_sel:WORD_1
	v_cvt_f32_f16_e32 v100, v151
	v_cvt_f32_f16_sdwa v101, v151 dst_sel:DWORD dst_unused:UNUSED_PAD src0_sel:WORD_1
	v_cvt_f32_f16_e32 v104, v152
	v_cvt_f32_f16_sdwa v105, v152 dst_sel:DWORD dst_unused:UNUSED_PAD src0_sel:WORD_1
	v_cvt_f32_f16_e32 v120, v153
	v_cvt_f32_f16_sdwa v121, v153 dst_sel:DWORD dst_unused:UNUSED_PAD src0_sel:WORD_1
	v_pk_fma_f32 v[100:101], v[94:95], v[136:137], v[100:101]
	v_pk_fma_f32 v[150:151], v[92:93], v[134:135], v[96:97]
	v_cvt_pk_f16_f32 v93, v100, v101
	v_pk_fma_f32 v[90:91], v[90:91], v[132:133], v[120:121]
	v_pk_fma_f32 v[120:121], v[88:89], v[130:131], v[104:105]
	v_lshl_add_u64 v[88:89], s[96:97], 0, v[206:207]
	v_cvt_pk_f16_f32 v92, v150, v151
	v_cvt_pk_f16_f32 v94, v120, v121
	v_cvt_pk_f16_f32 v95, v90, v91
	v_lshl_add_u64 v[152:153], v[88:89], 0, v[196:197]
	global_store_dwordx4 v[152:153], v[92:95], off
	v_cvt_f32_f16_e32 v88, v146
	v_cvt_f32_f16_sdwa v89, v146 dst_sel:DWORD dst_unused:UNUSED_PAD src0_sel:WORD_1
	v_cvt_f32_f16_e32 v92, v147
	v_cvt_f32_f16_sdwa v93, v147 dst_sel:DWORD dst_unused:UNUSED_PAD src0_sel:WORD_1
	v_cvt_f32_f16_e32 v96, v148
	v_cvt_f32_f16_sdwa v97, v148 dst_sel:DWORD dst_unused:UNUSED_PAD src0_sel:WORD_1
	v_cvt_f32_f16_e32 v104, v149
	v_cvt_f32_f16_sdwa v105, v149 dst_sel:DWORD dst_unused:UNUSED_PAD src0_sel:WORD_1
	v_pk_fma_f32 v[94:95], v[86:87], v[136:137], v[92:93]
	v_pk_fma_f32 v[146:147], v[84:85], v[134:135], v[88:89]
	v_lshl_add_u64 v[86:87], s[96:97], 0, v[214:215]
	v_pk_fma_f32 v[84:85], v[82:83], v[132:133], v[104:105]
	v_pk_fma_f32 v[104:105], v[80:81], v[130:131], v[96:97]
	v_cvt_pk_f16_f32 v80, v146, v147
	v_cvt_pk_f16_f32 v81, v94, v95
	v_cvt_pk_f16_f32 v82, v104, v105
	v_cvt_pk_f16_f32 v83, v84, v85
	v_lshl_add_u64 v[148:149], v[86:87], 0, v[196:197]
	global_store_dwordx4 v[148:149], v[80:83], off
	v_cvt_f32_f16_e32 v86, v144
	v_cvt_f32_f16_sdwa v87, v144 dst_sel:DWORD dst_unused:UNUSED_PAD src0_sel:WORD_1
	v_cvt_f32_f16_e32 v80, v142
	v_cvt_f32_f16_sdwa v81, v142 dst_sel:DWORD dst_unused:UNUSED_PAD src0_sel:WORD_1
	v_cvt_f32_f16_e32 v82, v143
	v_cvt_f32_f16_sdwa v83, v143 dst_sel:DWORD dst_unused:UNUSED_PAD src0_sel:WORD_1
	v_cvt_f32_f16_e32 v92, v145
	v_cvt_f32_f16_sdwa v93, v145 dst_sel:DWORD dst_unused:UNUSED_PAD src0_sel:WORD_1
	v_pk_fma_f32 v[126:127], v[76:77], v[134:135], v[80:81]
	v_pk_fma_f32 v[88:89], v[78:79], v[136:137], v[82:83]
	v_pk_fma_f32 v[96:97], v[72:73], v[130:131], v[86:87]
	v_pk_fma_f32 v[82:83], v[74:75], v[132:133], v[92:93]
	v_lshl_add_u64 v[76:77], s[96:97], 0, v[212:213]
	v_cvt_pk_f16_f32 v72, v126, v127
	v_cvt_pk_f16_f32 v73, v88, v89
	v_cvt_pk_f16_f32 v74, v96, v97
	v_cvt_pk_f16_f32 v75, v82, v83
	v_lshl_add_u64 v[142:143], v[76:77], 0, v[196:197]
	global_store_dwordx4 v[142:143], v[72:75], off
	v_cvt_f32_f16_e32 v76, v140
	v_cvt_f32_f16_sdwa v77, v140 dst_sel:DWORD dst_unused:UNUSED_PAD src0_sel:WORD_1
	v_cvt_f32_f16_e32 v72, v138
	v_cvt_f32_f16_sdwa v73, v138 dst_sel:DWORD dst_unused:UNUSED_PAD src0_sel:WORD_1
	v_cvt_f32_f16_e32 v74, v139
	v_cvt_f32_f16_sdwa v75, v139 dst_sel:DWORD dst_unused:UNUSED_PAD src0_sel:WORD_1
	v_cvt_f32_f16_e32 v78, v141
	v_cvt_f32_f16_sdwa v79, v141 dst_sel:DWORD dst_unused:UNUSED_PAD src0_sel:WORD_1
	v_pk_fma_f32 v[122:123], v[68:69], v[134:135], v[72:73]
	v_pk_fma_f32 v[86:87], v[70:71], v[136:137], v[74:75]
	v_pk_fma_f32 v[92:93], v[64:65], v[130:131], v[76:77]
	v_pk_fma_f32 v[80:81], v[66:67], v[132:133], v[78:79]
	v_lshl_add_u64 v[68:69], s[96:97], 0, v[210:211]
	v_cvt_pk_f16_f32 v64, v122, v123
	v_cvt_pk_f16_f32 v65, v86, v87
	v_cvt_pk_f16_f32 v66, v92, v93
	v_cvt_pk_f16_f32 v67, v80, v81
	v_lshl_add_u64 v[130:131], v[68:69], 0, v[196:197]
	global_store_dwordx4 v[130:131], v[64:67], off
	global_load_dwordx4 v[64:67], v[186:187], off offset:528
	global_load_dwordx4 v[68:71], v[186:187], off offset:512
	global_load_dwordx4 v[132:135], v[192:193], off offset:256
	global_load_dwordx4 v[136:139], v[188:189], off offset:256
	s_nop 0
	global_load_dwordx4 v[186:189], v[194:195], off offset:256
	s_nop 0
	global_load_dwordx4 v[192:195], v[204:205], off offset:256
	s_nop 0
	global_load_dwordx4 v[204:207], v[190:191], off offset:256
	s_nop 0
	global_load_dwordx4 v[196:199], v[198:199], off offset:256
	s_nop 0
	global_load_dwordx4 v[76:79], v[200:201], off offset:256
	global_load_dwordx4 v[72:75], v[202:203], off offset:256
	s_waitcnt vmcnt(7)
; __device__ __forceinline__ unsigned pk_f16(float lo, float hi) { f32x2 v = {lo, hi}; f16x2_t h = __builtin_convertvector(v, f16x2_t); return __builtin_bit_cast(unsigned, h); }
; __device__ __forceinline__ f32x2 up_f16(unsigned w) { return __builtin_convertvector(__builtin_bit_cast(f16x2_t, w), f32x2); }
;     __device__ __forceinline__ void operator()(const f32x4 (&acc)[2][2][4][2], const Unit& u, int wr, int wc, int fr, int fq) const {
;     ...
;             for (int ai = 0; ai < 2; ++ai) {
; #pragma unroll
;                 for (int m = 0; m < 4; ++m) { const size_t off = (size_t)(row0 + ai * HALF + m * 16) * 1024 + col0 + bj * HALF;
;                     float rc = 1.0f; if constexpr (GN) rc = rsqrtf(gss[2 * 32768 + row0 + ai * HALF + m * 16] * (1.0f / 384.0f) + 1e-6f);
;                     const u32x4 q = pq[ai][m];
;                     const f32x2 qa_ = up_f16(q.x), qb_ = up_f16(q.y), qc_ = up_f16(q.z), qd_ = up_f16(q.w);
;                     const f32x4 x0 = (f32x4){qa_[0], qa_[1], qb_[0], qb_[1]} + gv[0] * (acc[ai][bj][m][0] * rc),
;                                 x1 = (f32x4){qc_[0], qc_[1], qd_[0], qd_[1]} + gv[1] * (acc[ai][bj][m][1] * rc);
;                     { u32x4 wx; wx.x = pk_f16(x0[0], x0[1]); wx.y = pk_f16(x0[2], x0[3]); wx.z = pk_f16(x1[0], x1[1]); wx.w = pk_f16(x1[2], x1[3]); *(u32x4*)(out + off) = wx; }
;                     ss[ai][m] += ((x0[0] * x0[0] + x0[1] * x0[1]) + (x0[2] * x0[2] + x0[3] * x0[3])) + ((x1[0] * x1[0] + x1[1] * x1[1]) + (x1[2] * x1[2] + x1[3] * x1[3]));
	v_cvt_f32_f16_e32 v140, v132
	v_cvt_f32_f16_sdwa v141, v132 dst_sel:DWORD dst_unused:UNUSED_PAD src0_sel:WORD_1
	v_cvt_f32_f16_e32 v132, v133
	v_cvt_f32_f16_sdwa v133, v133 dst_sel:DWORD dst_unused:UNUSED_PAD src0_sel:WORD_1
	v_cvt_f32_f16_e32 v144, v134
	v_cvt_f32_f16_sdwa v145, v134 dst_sel:DWORD dst_unused:UNUSED_PAD src0_sel:WORD_1
	v_cvt_f32_f16_e32 v134, v135
	v_cvt_f32_f16_sdwa v135, v135 dst_sel:DWORD dst_unused:UNUSED_PAD src0_sel:WORD_1
	v_pk_fma_f32 v[62:63], v[62:63], v[70:71], v[132:133]
	v_pk_fma_f32 v[60:61], v[60:61], v[68:69], v[140:141]
	v_pk_fma_f32 v[132:133], v[58:59], v[66:67], v[134:135]
	v_pk_fma_f32 v[134:135], v[56:57], v[64:65], v[144:145]
	v_cvt_pk_f16_f32 v56, v60, v61
	v_cvt_pk_f16_f32 v57, v62, v63
	v_cvt_pk_f16_f32 v58, v134, v135
	v_cvt_pk_f16_f32 v59, v132, v133
	global_store_dwordx4 v[208:209], v[56:59], off offset:256
	s_nop 1
	v_mul_f32_e32 v56, v61, v61
	v_mul_f32_e32 v57, v63, v63
	v_fmac_f32_e32 v56, v60, v60
	v_fmac_f32_e32 v57, v62, v62
	v_add_f32_e32 v56, v56, v57
	v_mul_f32_e32 v57, v135, v135
	v_mul_f32_e32 v58, v133, v133
	v_fmac_f32_e32 v57, v134, v134
	v_fmac_f32_e32 v58, v132, v132
	v_add_f32_e32 v57, v57, v58
	v_add_f32_e32 v56, v56, v57
	v_add_f32_e32 v132, v237, v56
	s_waitcnt vmcnt(7)
	v_cvt_f32_f16_e32 v56, v136
	v_cvt_f32_f16_sdwa v57, v136 dst_sel:DWORD dst_unused:UNUSED_PAD src0_sel:WORD_1
	v_cvt_f32_f16_e32 v58, v137
	v_cvt_f32_f16_sdwa v59, v137 dst_sel:DWORD dst_unused:UNUSED_PAD src0_sel:WORD_1
	v_cvt_f32_f16_e32 v60, v138
	v_cvt_f32_f16_sdwa v61, v138 dst_sel:DWORD dst_unused:UNUSED_PAD src0_sel:WORD_1
	v_cvt_f32_f16_e32 v62, v139
	v_cvt_f32_f16_sdwa v63, v139 dst_sel:DWORD dst_unused:UNUSED_PAD src0_sel:WORD_1
	v_pk_fma_f32 v[54:55], v[54:55], v[70:71], v[58:59]
	v_pk_fma_f32 v[52:53], v[52:53], v[68:69], v[56:57]
	v_pk_fma_f32 v[48:49], v[48:49], v[64:65], v[60:61]
	v_pk_fma_f32 v[50:51], v[50:51], v[66:67], v[62:63]
	v_cvt_pk_f16_f32 v56, v52, v53
	v_cvt_pk_f16_f32 v57, v54, v55
	v_cvt_pk_f16_f32 v58, v48, v49
	v_cvt_pk_f16_f32 v59, v50, v51
	global_store_dwordx4 v[216:217], v[56:59], off offset:256
	s_waitcnt vmcnt(7)
	v_cvt_f32_f16_e32 v60, v188
	v_cvt_f32_f16_sdwa v61, v188 dst_sel:DWORD dst_unused:UNUSED_PAD src0_sel:WORD_1
	v_cvt_f32_f16_e32 v56, v186
	v_cvt_f32_f16_sdwa v57, v186 dst_sel:DWORD dst_unused:UNUSED_PAD src0_sel:WORD_1
	v_cvt_f32_f16_e32 v58, v187
	v_cvt_f32_f16_sdwa v59, v187 dst_sel:DWORD dst_unused:UNUSED_PAD src0_sel:WORD_1
	v_cvt_f32_f16_e32 v62, v189
	v_cvt_f32_f16_sdwa v63, v189 dst_sel:DWORD dst_unused:UNUSED_PAD src0_sel:WORD_1
	v_pk_fma_f32 v[44:45], v[44:45], v[68:69], v[56:57]
	v_pk_fma_f32 v[46:47], v[46:47], v[70:71], v[58:59]
	v_pk_fma_f32 v[40:41], v[40:41], v[64:65], v[60:61]
	v_pk_fma_f32 v[42:43], v[42:43], v[66:67], v[62:63]
	v_cvt_pk_f16_f32 v56, v44, v45
	v_cvt_pk_f16_f32 v57, v46, v47
	v_cvt_pk_f16_f32 v58, v40, v41
	v_cvt_pk_f16_f32 v59, v42, v43
	global_store_dwordx4 v[160:161], v[56:59], off offset:256
	s_waitcnt vmcnt(7)
	v_cvt_f32_f16_e32 v60, v194
	v_cvt_f32_f16_sdwa v61, v194 dst_sel:DWORD dst_unused:UNUSED_PAD src0_sel:WORD_1
	v_cvt_f32_f16_e32 v56, v192
	v_cvt_f32_f16_sdwa v57, v192 dst_sel:DWORD dst_unused:UNUSED_PAD src0_sel:WORD_1
	v_cvt_f32_f16_e32 v58, v193
	v_cvt_f32_f16_sdwa v59, v193 dst_sel:DWORD dst_unused:UNUSED_PAD src0_sel:WORD_1
	v_cvt_f32_f16_e32 v62, v195
	v_cvt_f32_f16_sdwa v63, v195 dst_sel:DWORD dst_unused:UNUSED_PAD src0_sel:WORD_1
	v_pk_fma_f32 v[36:37], v[36:37], v[68:69], v[56:57]
	v_pk_fma_f32 v[38:39], v[38:39], v[70:71], v[58:59]
	v_pk_fma_f32 v[32:33], v[32:33], v[64:65], v[60:61]
	v_pk_fma_f32 v[34:35], v[34:35], v[66:67], v[62:63]
	v_cvt_pk_f16_f32 v56, v36, v37
	v_cvt_pk_f16_f32 v57, v38, v39
	v_cvt_pk_f16_f32 v58, v32, v33
	v_cvt_pk_f16_f32 v59, v34, v35
	global_store_dwordx4 v[156:157], v[56:59], off offset:256
	s_waitcnt vmcnt(7)
	v_cvt_f32_f16_e32 v60, v206
	v_cvt_f32_f16_sdwa v61, v206 dst_sel:DWORD dst_unused:UNUSED_PAD src0_sel:WORD_1
	v_cvt_f32_f16_e32 v56, v204
	v_cvt_f32_f16_sdwa v57, v204 dst_sel:DWORD dst_unused:UNUSED_PAD src0_sel:WORD_1
	v_cvt_f32_f16_e32 v58, v205
	v_cvt_f32_f16_sdwa v59, v205 dst_sel:DWORD dst_unused:UNUSED_PAD src0_sel:WORD_1
	v_cvt_f32_f16_e32 v62, v207
	v_cvt_f32_f16_sdwa v63, v207 dst_sel:DWORD dst_unused:UNUSED_PAD src0_sel:WORD_1
	v_pk_fma_f32 v[28:29], v[28:29], v[68:69], v[56:57]
	v_pk_fma_f32 v[30:31], v[30:31], v[70:71], v[58:59]
	v_pk_fma_f32 v[24:25], v[24:25], v[64:65], v[60:61]
	v_pk_fma_f32 v[26:27], v[26:27], v[66:67], v[62:63]
	v_cvt_pk_f16_f32 v56, v28, v29
	v_cvt_pk_f16_f32 v57, v30, v31
	v_cvt_pk_f16_f32 v58, v24, v25
	v_cvt_pk_f16_f32 v59, v26, v27
	global_store_dwordx4 v[152:153], v[56:59], off offset:256
	s_waitcnt vmcnt(7)
	v_cvt_f32_f16_e32 v60, v198
	v_cvt_f32_f16_sdwa v61, v198 dst_sel:DWORD dst_unused:UNUSED_PAD src0_sel:WORD_1
	v_cvt_f32_f16_e32 v56, v196
	v_cvt_f32_f16_sdwa v57, v196 dst_sel:DWORD dst_unused:UNUSED_PAD src0_sel:WORD_1
	v_cvt_f32_f16_e32 v58, v197
	v_cvt_f32_f16_sdwa v59, v197 dst_sel:DWORD dst_unused:UNUSED_PAD src0_sel:WORD_1
	v_cvt_f32_f16_e32 v62, v199
	v_cvt_f32_f16_sdwa v63, v199 dst_sel:DWORD dst_unused:UNUSED_PAD src0_sel:WORD_1
	v_pk_fma_f32 v[20:21], v[20:21], v[68:69], v[56:57]
	v_pk_fma_f32 v[22:23], v[22:23], v[70:71], v[58:59]
	v_pk_fma_f32 v[16:17], v[16:17], v[64:65], v[60:61]
	v_pk_fma_f32 v[18:19], v[18:19], v[66:67], v[62:63]
	v_cvt_pk_f16_f32 v56, v20, v21
	v_cvt_pk_f16_f32 v57, v22, v23
	v_cvt_pk_f16_f32 v58, v16, v17
	v_cvt_pk_f16_f32 v59, v18, v19
	global_store_dwordx4 v[148:149], v[56:59], off offset:256
	s_waitcnt vmcnt(7)
;     __device__ __forceinline__ void operator()(const f32x4 (&acc)[2][2][4][2], const Unit& u, int wr, int wc, int fr, int fq) const {
;     ...
;                     ss[ai][m] += ((x0[0] * x0[0] + x0[1] * x0[1]) + (x0[2] * x0[2] + x0[3] * x0[3])) + ((x1[0] * x1[0] + x1[1] * x1[1]) + (x1[2] * x1[2] + x1[3] * x1[3]));
;                 }
;                 asm volatile("" ::: "memory");
;             }
;         }
; #pragma unroll
;         for (int ai = 0; ai < 2; ++ai)
; #pragma unroll
;             for (int m = 0; m < 4; ++m) { float t = ss[ai][m]; t += __shfl_xor(t, 16); t += __shfl_xor(t, 32);
;                 if (fq == 0) atomicAdd(rowss + row0 + ai * HALF + m * 16, t); }
	v_cvt_f32_f16_e32 v60, v78
	v_cvt_f32_f16_sdwa v61, v78 dst_sel:DWORD dst_unused:UNUSED_PAD src0_sel:WORD_1
	v_cvt_f32_f16_e32 v56, v76
	v_cvt_f32_f16_sdwa v57, v76 dst_sel:DWORD dst_unused:UNUSED_PAD src0_sel:WORD_1
	v_cvt_f32_f16_e32 v58, v77
	v_cvt_f32_f16_sdwa v59, v77 dst_sel:DWORD dst_unused:UNUSED_PAD src0_sel:WORD_1
	v_cvt_f32_f16_e32 v62, v79
	v_cvt_f32_f16_sdwa v63, v79 dst_sel:DWORD dst_unused:UNUSED_PAD src0_sel:WORD_1
	v_pk_fma_f32 v[12:13], v[12:13], v[68:69], v[56:57]
	v_pk_fma_f32 v[14:15], v[14:15], v[70:71], v[58:59]
	v_pk_fma_f32 v[8:9], v[8:9], v[64:65], v[60:61]
	v_pk_fma_f32 v[10:11], v[10:11], v[66:67], v[62:63]
	v_cvt_pk_f16_f32 v56, v12, v13
	v_cvt_pk_f16_f32 v57, v14, v15
	v_cvt_pk_f16_f32 v58, v8, v9
	v_cvt_pk_f16_f32 v59, v10, v11
	global_store_dwordx4 v[142:143], v[56:59], off offset:256
	s_waitcnt vmcnt(7)
	v_cvt_f32_f16_e32 v60, v74
	v_cvt_f32_f16_sdwa v61, v74 dst_sel:DWORD dst_unused:UNUSED_PAD src0_sel:WORD_1
	v_cvt_f32_f16_e32 v56, v72
	v_cvt_f32_f16_sdwa v57, v72 dst_sel:DWORD dst_unused:UNUSED_PAD src0_sel:WORD_1
	v_cvt_f32_f16_e32 v58, v73
	v_cvt_f32_f16_sdwa v59, v73 dst_sel:DWORD dst_unused:UNUSED_PAD src0_sel:WORD_1
	v_cvt_f32_f16_e32 v62, v75
	v_cvt_f32_f16_sdwa v63, v75 dst_sel:DWORD dst_unused:UNUSED_PAD src0_sel:WORD_1
	v_pk_fma_f32 v[4:5], v[4:5], v[68:69], v[56:57]
	v_pk_fma_f32 v[6:7], v[6:7], v[70:71], v[58:59]
	v_pk_fma_f32 v[0:1], v[0:1], v[64:65], v[60:61]
	v_pk_fma_f32 v[2:3], v[2:3], v[66:67], v[62:63]
	v_cvt_pk_f16_f32 v56, v4, v5
	v_cvt_pk_f16_f32 v57, v6, v7
	v_cvt_pk_f16_f32 v58, v0, v1
	v_cvt_pk_f16_f32 v59, v2, v3
	global_store_dwordx4 v[130:131], v[56:59], off offset:256
	s_nop 1
	v_and_b32_e32 v57, 64, v230
	v_xor_b32_e32 v56, 16, v230
	v_add_u32_e32 v57, 64, v57
	v_cmp_lt_i32_e32 vcc, v56, v57
	s_nop 1
	v_cndmask_b32_e32 v56, v230, v56, vcc
	v_lshlrev_b32_e32 v58, 2, v56
	v_xor_b32_e32 v56, 32, v230
	v_cmp_lt_i32_e32 vcc, v56, v57
	s_nop 1
	v_cndmask_b32_e32 v56, v230, v56, vcc
	v_lshlrev_b32_e32 v59, 2, v56
	v_mov_b32_e32 v56, v132
	v_mov_b32_e32 v60, v132
	s_nop 1
	v_permlane16_swap_b32_e32 v56, v60
	s_waitcnt lgkmcnt(0)
	v_add_f32_e32 v60, v60, v56
	v_mov_b32_e32 v61, v60
	s_nop 1
	v_permlane32_swap_b32_e32 v61, v60
	v_lshl_add_u64 v[56:57], v[172:173], 2, s[12:13]
	s_and_saveexec_b64 s[4:5], s[38:39]
	s_cbranch_execz .LBB0_1002
	s_waitcnt lgkmcnt(0)
	v_add_f32_e32 v60, v60, v61
	global_atomic_add_f32 v[56:57], v60, off
.LBB0_1002:
	s_or_b64 exec, exec, s[4:5]
	v_mul_f32_e32 v60, v117, v117
	s_waitcnt lgkmcnt(0)
	v_mul_f32_e32 v61, v119, v119
	v_fmac_f32_e32 v60, v116, v116
	v_fmac_f32_e32 v61, v118, v118
	v_mul_f32_e32 v53, v53, v53
	v_mul_f32_e32 v49, v49, v49
	v_add_f32_e32 v60, v60, v61
	v_mul_f32_e32 v61, v113, v113
	v_mul_f32_e32 v62, v115, v115
	v_fmac_f32_e32 v53, v52, v52
	v_mul_f32_e32 v52, v55, v55
	v_fmac_f32_e32 v49, v48, v48
	v_mul_f32_e32 v48, v51, v51
	v_fmac_f32_e32 v61, v112, v112
	v_fmac_f32_e32 v62, v114, v114
	v_fmac_f32_e32 v52, v54, v54
	v_fmac_f32_e32 v48, v50, v50
	v_add_f32_e32 v61, v61, v62
	v_add_f32_e32 v52, v53, v52
	v_add_f32_e32 v48, v49, v48
	v_add_f32_e32 v60, v60, v61
	v_add_f32_e32 v48, v52, v48
	v_add_f32_e32 v48, v60, v48
	v_mov_b32_e32 v49, v48
	s_nop 1
	v_permlane16_swap_b32_e32 v49, v48
	s_waitcnt lgkmcnt(0)
	v_add_f32_e32 v48, v48, v49
	v_mov_b32_e32 v49, v48
	s_nop 1
	v_permlane32_swap_b32_e32 v49, v48
	s_and_saveexec_b64 s[4:5], s[38:39]
	s_cbranch_execz .LBB0_1004
	s_waitcnt lgkmcnt(0)
	v_add_f32_e32 v48, v48, v49
	global_atomic_add_f32 v[56:57], v48, off offset:64
.LBB0_1004:
	s_or_b64 exec, exec, s[4:5]
	v_mul_f32_e32 v48, v159, v159
	s_waitcnt lgkmcnt(0)
	v_mul_f32_e32 v49, v111, v111
	v_fmac_f32_e32 v48, v158, v158
	v_fmac_f32_e32 v49, v110, v110
	v_mul_f32_e32 v45, v45, v45
	v_mul_f32_e32 v41, v41, v41
	v_add_f32_e32 v48, v48, v49
	v_mul_f32_e32 v49, v125, v125
	v_mul_f32_e32 v50, v107, v107
	v_fmac_f32_e32 v45, v44, v44
	v_mul_f32_e32 v44, v47, v47
	v_fmac_f32_e32 v41, v40, v40
	v_mul_f32_e32 v40, v43, v43
	v_fmac_f32_e32 v49, v124, v124
	v_fmac_f32_e32 v50, v106, v106
	v_fmac_f32_e32 v44, v46, v46
	v_fmac_f32_e32 v40, v42, v42
	v_add_f32_e32 v49, v49, v50
	v_add_f32_e32 v44, v45, v44
	v_add_f32_e32 v40, v41, v40
	v_add_f32_e32 v48, v48, v49
	v_add_f32_e32 v40, v44, v40
	v_add_f32_e32 v40, v48, v40
	v_mov_b32_e32 v41, v40
	s_nop 1
	v_permlane16_swap_b32_e32 v41, v40
	s_waitcnt lgkmcnt(0)
	v_add_f32_e32 v40, v40, v41
	v_mov_b32_e32 v41, v40
	s_nop 1
	v_permlane32_swap_b32_e32 v41, v40
	s_and_saveexec_b64 s[4:5], s[38:39]
	s_cbranch_execz .LBB0_1006
	s_waitcnt lgkmcnt(0)
	v_add_f32_e32 v40, v40, v41
	global_atomic_add_f32 v[56:57], v40, off offset:128
;     __device__ __forceinline__ void operator()(const f32x4 (&acc)[2][2][4][2], const Unit& u, int wr, int wc, int fr, int fq) const {
;     ...
;                     ss[ai][m] += ((x0[0] * x0[0] + x0[1] * x0[1]) + (x0[2] * x0[2] + x0[3] * x0[3])) + ((x1[0] * x1[0] + x1[1] * x1[1]) + (x1[2] * x1[2] + x1[3] * x1[3]));
;                 }
;                 asm volatile("" ::: "memory");
;             }
;         }
; #pragma unroll
;         for (int ai = 0; ai < 2; ++ai)
; #pragma unroll
;             for (int m = 0; m < 4; ++m) { float t = ss[ai][m]; t += __shfl_xor(t, 16); t += __shfl_xor(t, 32);
;                 if (fq == 0) atomicAdd(rowss + row0 + ai * HALF + m * 16, t); }
.LBB0_1006:
	s_or_b64 exec, exec, s[4:5]
	v_mul_f32_e32 v40, v155, v155
	s_waitcnt lgkmcnt(0)
	v_mul_f32_e32 v41, v103, v103
	v_fmac_f32_e32 v40, v154, v154
	v_fmac_f32_e32 v41, v102, v102
	v_mul_f32_e32 v37, v37, v37
	v_mul_f32_e32 v33, v33, v33
	v_add_f32_e32 v40, v40, v41
	v_mul_f32_e32 v41, v109, v109
	v_mul_f32_e32 v42, v99, v99
	v_fmac_f32_e32 v37, v36, v36
	v_mul_f32_e32 v36, v39, v39
	v_fmac_f32_e32 v33, v32, v32
	v_mul_f32_e32 v32, v35, v35
	v_fmac_f32_e32 v41, v108, v108
	v_fmac_f32_e32 v42, v98, v98
	v_fmac_f32_e32 v36, v38, v38
	v_fmac_f32_e32 v32, v34, v34
	v_add_f32_e32 v41, v41, v42
	v_add_f32_e32 v36, v37, v36
	v_add_f32_e32 v32, v33, v32
	v_add_f32_e32 v40, v40, v41
	v_add_f32_e32 v32, v36, v32
	v_add_f32_e32 v32, v40, v32
	v_mov_b32_e32 v33, v32
	s_nop 1
	v_permlane16_swap_b32_e32 v33, v32
	s_waitcnt lgkmcnt(0)
	v_add_f32_e32 v32, v32, v33
	v_mov_b32_e32 v33, v32
	s_nop 1
	v_permlane32_swap_b32_e32 v33, v32
	s_and_saveexec_b64 s[4:5], s[38:39]
	s_cbranch_execz .LBB0_1008
	s_waitcnt lgkmcnt(0)
	v_add_f32_e32 v32, v32, v33
	global_atomic_add_f32 v[56:57], v32, off offset:192
.LBB0_1008:
	s_or_b64 exec, exec, s[4:5]
	v_mul_f32_e32 v32, v151, v151
	s_waitcnt lgkmcnt(0)
	v_mul_f32_e32 v33, v101, v101
	v_fmac_f32_e32 v32, v150, v150
	v_fmac_f32_e32 v33, v100, v100
	v_mul_f32_e32 v29, v29, v29
	v_mul_f32_e32 v25, v25, v25
	v_add_f32_e32 v32, v32, v33
	v_mul_f32_e32 v33, v121, v121
	v_mul_f32_e32 v34, v91, v91
	v_fmac_f32_e32 v29, v28, v28
	v_mul_f32_e32 v28, v31, v31
	v_fmac_f32_e32 v25, v24, v24
	v_mul_f32_e32 v24, v27, v27
	v_fmac_f32_e32 v33, v120, v120
	v_fmac_f32_e32 v34, v90, v90
	v_fmac_f32_e32 v28, v30, v30
	v_fmac_f32_e32 v24, v26, v26
	v_add_f32_e32 v33, v33, v34
	v_add_f32_e32 v28, v29, v28
	v_add_f32_e32 v24, v25, v24
	v_add_f32_e32 v32, v32, v33
	v_add_f32_e32 v24, v28, v24
	v_add_f32_e32 v24, v32, v24
	v_mov_b32_e32 v25, v24
	s_nop 1
	v_permlane16_swap_b32_e32 v25, v24
	s_waitcnt lgkmcnt(0)
	v_add_f32_e32 v24, v24, v25
	v_mov_b32_e32 v25, v24
	s_nop 1
	v_permlane32_swap_b32_e32 v25, v24
	s_and_saveexec_b64 s[4:5], s[38:39]
	s_cbranch_execz .LBB0_1010
	s_waitcnt lgkmcnt(0)
	v_add_f32_e32 v24, v24, v25
	global_atomic_add_f32 v[56:57], v24, off offset:512
.LBB0_1010:
	s_or_b64 exec, exec, s[4:5]
	v_mul_f32_e32 v24, v147, v147
	s_waitcnt lgkmcnt(0)
	v_mul_f32_e32 v25, v95, v95
	v_fmac_f32_e32 v24, v146, v146
	v_fmac_f32_e32 v25, v94, v94
	v_mul_f32_e32 v21, v21, v21
	v_mul_f32_e32 v17, v17, v17
	v_add_f32_e32 v24, v24, v25
	v_mul_f32_e32 v25, v105, v105
	v_mul_f32_e32 v26, v85, v85
	v_fmac_f32_e32 v21, v20, v20
	v_mul_f32_e32 v20, v23, v23
	v_fmac_f32_e32 v17, v16, v16
	v_mul_f32_e32 v16, v19, v19
	v_fmac_f32_e32 v25, v104, v104
	v_fmac_f32_e32 v26, v84, v84
	v_fmac_f32_e32 v20, v22, v22
	v_fmac_f32_e32 v16, v18, v18
	v_add_f32_e32 v25, v25, v26
	v_add_f32_e32 v20, v21, v20
	v_add_f32_e32 v16, v17, v16
	v_add_f32_e32 v24, v24, v25
	v_add_f32_e32 v16, v20, v16
	v_add_f32_e32 v16, v24, v16
	v_mov_b32_e32 v17, v16
	s_nop 1
	v_permlane16_swap_b32_e32 v17, v16
	s_waitcnt lgkmcnt(0)
	v_add_f32_e32 v16, v16, v17
	v_mov_b32_e32 v17, v16
	s_nop 1
	v_permlane32_swap_b32_e32 v17, v16
	s_and_saveexec_b64 s[4:5], s[38:39]
	s_cbranch_execz .LBB0_1012
	s_waitcnt lgkmcnt(0)
	v_add_f32_e32 v16, v16, v17
	global_atomic_add_f32 v[56:57], v16, off offset:576
.LBB0_1012:
	s_or_b64 exec, exec, s[4:5]
	v_mul_f32_e32 v16, v127, v127
	s_waitcnt lgkmcnt(0)
	v_mul_f32_e32 v17, v89, v89
	v_fmac_f32_e32 v16, v126, v126
	v_fmac_f32_e32 v17, v88, v88
	v_mul_f32_e32 v13, v13, v13
	v_mul_f32_e32 v9, v9, v9
	v_add_f32_e32 v16, v16, v17
	v_mul_f32_e32 v17, v97, v97
	v_mul_f32_e32 v18, v83, v83
	v_fmac_f32_e32 v13, v12, v12
	v_mul_f32_e32 v12, v15, v15
	v_fmac_f32_e32 v9, v8, v8
	v_mul_f32_e32 v8, v11, v11
	v_fmac_f32_e32 v17, v96, v96
	v_fmac_f32_e32 v18, v82, v82
	v_fmac_f32_e32 v12, v14, v14
	v_fmac_f32_e32 v8, v10, v10
	v_add_f32_e32 v17, v17, v18
	v_add_f32_e32 v12, v13, v12
	v_add_f32_e32 v8, v9, v8
	v_add_f32_e32 v16, v16, v17
	v_add_f32_e32 v8, v12, v8
	v_add_f32_e32 v8, v16, v8
	v_mov_b32_e32 v9, v8
	s_nop 1
	v_permlane16_swap_b32_e32 v9, v8
	s_waitcnt lgkmcnt(0)
	v_add_f32_e32 v8, v8, v9
	v_mov_b32_e32 v9, v8
	s_nop 1
	v_permlane32_swap_b32_e32 v9, v8
	s_and_saveexec_b64 s[4:5], s[38:39]
	s_cbranch_execz .LBB0_1014
	s_waitcnt lgkmcnt(0)
	v_add_f32_e32 v8, v8, v9
	global_atomic_add_f32 v[56:57], v8, off offset:640
.LBB0_1014:
	s_or_b64 exec, exec, s[4:5]
	v_mul_f32_e32 v8, v123, v123
	s_waitcnt lgkmcnt(0)
	v_mul_f32_e32 v9, v87, v87
	v_fmac_f32_e32 v8, v122, v122
	v_fmac_f32_e32 v9, v86, v86
	v_mul_f32_e32 v5, v5, v5
	v_mul_f32_e32 v1, v1, v1
	v_add_f32_e32 v8, v8, v9
	v_mul_f32_e32 v9, v93, v93
	v_mul_f32_e32 v10, v81, v81
	v_fmac_f32_e32 v5, v4, v4
	v_mul_f32_e32 v4, v7, v7
	v_fmac_f32_e32 v1, v0, v0
	v_mul_f32_e32 v0, v3, v3
	v_fmac_f32_e32 v9, v92, v92
	v_fmac_f32_e32 v10, v80, v80
	v_fmac_f32_e32 v4, v6, v6
	v_fmac_f32_e32 v0, v2, v2
	v_add_f32_e32 v9, v9, v10
	v_add_f32_e32 v4, v5, v4
	v_add_f32_e32 v0, v1, v0
	v_add_f32_e32 v8, v8, v9
	v_add_f32_e32 v0, v4, v0
	v_add_f32_e32 v0, v8, v0
	v_mov_b32_e32 v1, v0
	s_nop 1
	v_permlane16_swap_b32_e32 v1, v0
	s_waitcnt lgkmcnt(0)
	v_add_f32_e32 v0, v0, v1
	v_mov_b32_e32 v1, v0
	s_nop 1
	v_permlane32_swap_b32_e32 v1, v0
	s_and_saveexec_b64 s[4:5], s[38:39]
	s_cbranch_execz .LBB0_1016
	s_waitcnt lgkmcnt(0)
	v_add_f32_e32 v0, v0, v1
	global_atomic_add_f32 v[56:57], v0, off offset:704
